# whole-kernel static priority for the older wave half (prio resets after GEMM phases removed), on static-prio base
# speedup vs baseline: 1.0002x; 1.0002x over previous
;     __device__ bool next(int i, Unit& u) const {
;         if (i >= icnt) return false;
;         const long L = (long)(i + ioff) * G + c; if (L >= nwg) return false;
; template <class Epi>
; __device__ __forceinline__ void gemm_phase(LAS unsigned char* lds, const Gemm g, const StaticOrder& S, const Epi& E) {
;     int tid = threadIdx.x; asm volatile("" : "+v"(tid));
;     const int wid = __builtin_amdgcn_readfirstlane(tid >> 6), lane = tid & 63, wr = wid >> 2, wc = wid & 3, fr = lane & 15, fq = lane >> 4;
;     const int K = g.K, nt = K / BK;
;     unsigned voffA[2], voffB0[2], voffB1[2];
; #pragma unroll
;     for (int i = 0; i < 2; ++i) { int R, C; stage_rc(tid * 16 + i * 8192, R, C);
;         const int Rw = 64 * (R >> 5) + 16 * ((R >> 2) & 3) + 4 * ((R >> 4) & 1) + (R & 3);
;         const int Rf = 64 * (R >> 5) + 8 * ((R >> 2) & 3) + 4 * ((R >> 4) & 1) + (R & 3);
;         const int Rb0 = Epi::PERM ? (Epi::F32OUT ? Rf : Rw) : R, Rb1 = Epi::PERM ? (Epi::F32OUT ? Rf + 32 : Rw + 8) : R + HALF;
;         voffA[i] = (unsigned)(R * K + C) * 2u; voffB0[i] = (unsigned)(Rb0 * K + C) * 2u; voffB1[i] = (unsigned)(Rb1 * K + C) * 2u; }
;     const size_t kstep = (size_t)(BK * 2);
;     const size_t hstep = (size_t)HALF * K * 2;
;     const size_t tstep = 2 * hstep;
;     const unsigned ldsw = (unsigned)wid * 1024u;
;     const int aoff = lds_byte(wr * 64 + fr, fq * 8), boff = lds_byte(wc * 32 + fr, fq * 8);
;     ...
;     Unit cur, nxt; int ui = 0;
;     if (!S.next(0, cur)) return;
;     f32x4 acc[2][2][4][2];
; #pragma unroll
;     for (int a = 0; a < 2; ++a)
; #pragma unroll
;         for (int b = 0; b < 2; ++b)
; #pragma unroll
;             for (int m = 0; m < 4; ++m)
; #pragma unroll
;                 for (int n = 0; n < 2; ++n) acc[a][b][m][n] = (f32x4){0.f, 0.f, 0.f, 0.f};
;     bf16x8 At[4][2], B0[2][2], B1[2][2];
;     const char* cA = (const char*)g.A + (size_t)cur.pm * tstep; const char* cB = (const char*)g.Bt + (size_t)cur.pn * tstep;
;     PG8_STAGE(PG8_SB(0, 0), cB, voffB0); PG8_STAGE(PG8_SA(0, 0), cA, voffA); PG8_STAGE(PG8_SB(0, 1), cB, voffB1); PG8_STAGE(PG8_SA(0, 1), cA + hstep, voffA);
;     if (wr == 1) PG8_BAR;
;     PG8_WAIT_V(4); PG8_BAR;
;     PG8_STAGE(PG8_SB(1, 0), cB + kstep, voffB0); PG8_STAGE(PG8_SA(1, 0), cA + kstep, voffA); PG8_STAGE(PG8_SB(1, 1), cB + kstep, voffB1);
;     PG8_WAIT_V(6); PG8_BAR;
.LBB0_99:
	s_or_b64 exec, exec, s[4:5]
	s_mov_b64 s[4:5], s[0:1]
	s_waitcnt lgkmcnt(0)
	v_mov_b32_e32 v0, v202
	s_mov_b32 s6, s2
	v_mov_b32_e32 v12, v202
	s_barrier
	s_cmpk_gt_i32 s2, 0x3ff
	v_readfirstlane_b32 s27, v12
	s_cbranch_scc1 .LBB0_112
	v_lshlrev_b32_e32 v0, 4, v12
	v_add_u32_e32 v1, 0x2000, v0
	v_ashrrev_i32_e32 v2, 31, v1
	v_lshrrev_b32_e32 v2, 22, v2
	v_add_u32_e32 v2, v1, v2
	v_ashrrev_i32_e32 v13, 10, v2
	v_mul_i32_i24_e32 v2, 0x400, v13
	v_sub_u32_e32 v1, v1, v2
	v_lshrrev_b32_e32 v2, 4, v1
	v_bitop3_b32 v1, v2, v1, 32 bitop3:0x6c
	v_ashrrev_i32_e32 v2, 31, v1
	v_lshrrev_b32_e32 v2, 26, v2
	v_add_u32_e32 v2, v1, v2
	v_lshlrev_b32_e32 v3, 3, v13
	v_ashrrev_i32_e32 v14, 6, v2
	v_and_b32_e32 v3, -16, v3
	s_load_dwordx2 s[4:5], s[4:5], 0xf0
	v_add_u32_e32 v3, v14, v3
	v_lshlrev_b32_e32 v4, 2, v3
	v_and_b32_e32 v5, 3, v14
	v_and_or_b32 v4, v4, 48, v5
	v_lshlrev_b32_e32 v5, 1, v3
	v_lshrrev_b32_e32 v6, 2, v3
	v_and_b32_e32 v2, 0xc0, v2
	v_and_b32_e32 v5, 0xfffc0, v5
	v_and_b32_e32 v6, 4, v6
	v_sub_u32_e32 v1, v1, v2
	v_mov_b32_e32 v2, 1
	v_or3_b32 v4, v4, v5, v6
	v_lshlrev_b32_e32 v5, 5, v13
	v_ashrrev_i16_sdwa v1, v2, sext(v1) dst_sel:DWORD dst_unused:UNUSED_PAD src0_sel:DWORD src1_sel:BYTE_0
	s_waitcnt lgkmcnt(0)
	s_add_u32 s40, s4, 0x6400000
	v_and_b32_e32 v5, 32, v5
	v_bfe_i32 v15, v1, 0, 16
	s_addc_u32 s41, s5, 0
	v_add_lshl_u32 v1, v5, v15, 1
	s_add_u32 s42, s4, 0x4900000
	v_lshl_add_u32 v128, v4, 12, v1
	v_lshl_add_u32 v132, v3, 12, v1
	v_bfe_i32 v1, v12, 27, 1
	s_addc_u32 s43, s5, 0
	v_lshrrev_b32_e32 v1, 22, v1
	s_ashr_i32 s45, s2, 31
	v_add_u32_e32 v1, v0, v1
	s_lshr_b32 s6, s45, 29
	v_and_b32_e32 v1, 0xfffffc00, v1
	s_add_i32 s6, s2, s6
	v_sub_u32_e32 v0, v0, v1
	s_ashr_i32 s7, s6, 3
	s_and_b32 s6, s6, -8
	v_lshrrev_b32_e32 v1, 4, v0
	v_ashrrev_i32_e32 v3, 31, v12
	s_sub_i32 s6, s2, s6
	v_bitop3_b32 v0, v1, v0, 32 bitop3:0x6c
	v_lshrrev_b32_e32 v3, 26, v3
	s_lshr_b32 s8, s6, 31
	v_ashrrev_i32_e32 v1, 31, v0
	v_add_u32_e32 v3, v12, v3
	s_bitset1_b32 s8, 7
	v_lshrrev_b32_e32 v1, 26, v1
	v_ashrrev_i32_e32 v17, 6, v3
	s_mul_i32 s6, s8, s6
	v_add_u32_e32 v1, v0, v1
	v_lshlrev_b32_e32 v3, 3, v17
	s_add_i32 s6, s6, s7
	v_ashrrev_i32_e32 v16, 6, v1
	v_and_b32_e32 v3, -16, v3
	s_ashr_i32 s7, s6, 31
	v_add_u32_e32 v3, v16, v3
	s_lshr_b32 s7, s7, 25
	v_lshlrev_b32_e32 v4, 2, v3
	v_and_b32_e32 v5, 3, v16
	s_add_i32 s7, s6, s7
	v_and_or_b32 v4, v4, 48, v5
	v_lshlrev_b32_e32 v5, 1, v3
	v_lshrrev_b32_e32 v6, 2, v3
	v_and_b32_e32 v1, 0xc0, v1
	s_ashr_i32 s7, s7, 7
	v_and_b32_e32 v5, 0xfffc0, v5
	v_and_b32_e32 v6, 4, v6
	v_sub_u32_e32 v0, v0, v1
	s_lshl_b32 s8, s7, 3
	v_or3_b32 v4, v4, v5, v6
	v_lshlrev_b32_e32 v5, 5, v17
	v_ashrrev_i16_sdwa v0, v2, sext(v0) dst_sel:DWORD dst_unused:UNUSED_PAD src0_sel:DWORD src1_sel:BYTE_0
	s_sub_i32 s9, 64, s8
	s_lshl_b32 s7, s7, 7
	v_and_b32_e32 v5, 32, v5
	v_bfe_i32 v18, v0, 0, 16
	s_min_u32 s9, s9, 8
	s_sub_i32 s13, s6, s7
	v_add_lshl_u32 v0, v5, v18, 1
	s_sext_i32_i8 s6, s13
	v_cvt_f32_ubyte0_e32 v2, s9
	v_lshl_add_u32 v134, v4, 12, v0
	v_cvt_f32_i32_e32 v1, s6
	v_rcp_iflag_f32_e32 v4, v2
	v_lshl_add_u32 v138, v3, 12, v0
	s_ashr_i32 s12, s27, 6
	s_ashr_i32 s6, s6, 30
	v_mul_f32_e32 v0, v1, v4
	v_trunc_f32_e32 v0, v0
	v_fma_f32 v1, -v0, v2, v1
	v_cvt_i32_f32_e32 v0, v0
	s_ashr_i32 s11, s27, 8
	s_lshl_b32 s44, s12, 10
	s_or_b32 s10, s6, 1
	v_cmp_ge_f32_e64 s[6:7], |v1|, v2
	s_and_b64 s[6:7], s[6:7], exec
	s_cselect_b32 s6, s10, 0
	v_readfirstlane_b32 s7, v0
	s_add_i32 s10, s7, s6
	s_mul_i32 s6, s10, s9
	s_sub_i32 s6, s13, s6
	s_sext_i32_i8 s6, s6
	s_add_i32 s30, s8, s6
	s_ashr_i32 s31, s30, 31
	s_bfe_i64 s[8:9], s[10:11], 0x80000
	s_lshl_b64 s[6:7], s[30:31], 20
	s_lshl_b64 s[8:9], s[8:9], 20
	s_add_u32 s36, s42, s8
	s_addc_u32 s37, s43, s9
	s_add_i32 s31, s44, 0
	s_add_i32 m0, s31, 0x10000
	v_add_u32_e32 v136, 0x8000, v134
	global_load_lds_dwordx4 v134, s[36:37]
	s_add_i32 m0, s31, 0x12000
	s_add_u32 s34, s40, s6
	global_load_lds_dwordx4 v128, s[36:37]
	s_addc_u32 s35, s41, s7
	s_mov_b32 m0, s31
	s_add_i32 s46, s31, 0x2000
	global_load_lds_dwordx4 v138, s[34:35]
	s_mov_b32 m0, s46
	v_add_u32_e32 v130, 0x8000, v128
	global_load_lds_dwordx4 v132, s[34:35]
	s_add_i32 m0, s31, 0x14000
	v_mov_b32_e32 v135, 0
	global_load_lds_dwordx4 v136, s[36:37]
	s_add_i32 m0, s31, 0x16000
	s_add_u32 s6, s34, 0x80000
	s_addc_u32 s7, s35, 0
	s_add_i32 s47, s31, 0x4000
	global_load_lds_dwordx4 v130, s[36:37]
	s_mov_b32 m0, s47
	s_add_i32 s48, s31, 0x6000
	global_load_lds_dwordx4 v138, s[6:7]
	s_mov_b32 m0, s48
	v_mov_b32_e32 v129, v135
	global_load_lds_dwordx4 v132, s[6:7]
	v_mov_b32_e32 v139, v135
	v_mov_b32_e32 v133, v135
	v_mov_b32_e32 v137, v135
	v_mov_b32_e32 v131, v135
	s_mov_b32 s50, 0
	s_mov_b32 s49, 0x10000
	v_lshl_add_u64 v[10:11], s[36:37], 0, v[134:135]
	v_lshl_add_u64 v[8:9], s[36:37], 0, v[128:129]
	v_lshl_add_u64 v[6:7], s[34:35], 0, v[138:139]
	v_lshl_add_u64 v[4:5], s[34:35], 0, v[132:133]
	v_lshl_add_u64 v[0:1], s[36:37], 0, v[136:137]
	s_cmp_lg_u32 s11, 1
	v_lshl_add_u64 v[2:3], s[36:37], 0, v[130:131]
	s_setprio 1
	s_cbranch_scc1 .LBB0_102
	s_barrier
; #define PG8_STAGE(bufoff, gbase, voff) do { _Pragma("unroll") for (int _i = 0; _i < 2; ++_i) \
;         __builtin_amdgcn_global_load_lds((const unsigned*)((const char*)(gbase) + (voff)[_i]), (LAS unsigned*)(lds + (bufoff) + ldsw + _i * 8192), 16, 0, 0); } while (0)
; #define PG8_WAIT_V(n) asm volatile("s_waitcnt vmcnt(" #n ")" ::: "memory")
; #define PG8_BAR __builtin_amdgcn_s_barrier()
; template <class Epi>
; __device__ __forceinline__ void gemm_phase(LAS unsigned char* lds, const Gemm g, const StaticOrder& S, const Epi& E) {
;     ...
;     const unsigned ldsw = (unsigned)wid * 1024u;
;     const int aoff = lds_byte(wr * 64 + fr, fq * 8), boff = lds_byte(wc * 32 + fr, fq * 8);
;     ...
;     PG8_WAIT_V(4); PG8_BAR;
;     PG8_STAGE(PG8_SB(1, 0), cB + kstep, voffB0); PG8_STAGE(PG8_SA(1, 0), cA + kstep, voffA); PG8_STAGE(PG8_SB(1, 1), cB + kstep, voffB1);
;     PG8_WAIT_V(6); PG8_BAR;
.LBB0_102:
	s_add_u32 s6, s4, 0xec00000
	s_mov_b64 s[8:9], 0x80
	s_addc_u32 s7, s5, 0
	s_add_i32 m0, s31, 0x18000
	v_lshl_add_u64 v[10:11], v[10:11], 0, s[8:9]
	s_waitcnt vmcnt(4)
	s_barrier
	global_load_lds_dwordx4 v[10:11], off
	v_lshl_add_u64 v[8:9], v[8:9], 0, s[8:9]
	s_add_i32 m0, s31, 0x1a000
	s_add_i32 s51, s31, 0x8000
	global_load_lds_dwordx4 v[8:9], off
	v_lshl_add_u64 v[6:7], v[6:7], 0, s[8:9]
	s_mov_b32 m0, s51
	s_add_i32 s52, s31, 0xa000
	global_load_lds_dwordx4 v[6:7], off
	v_lshl_add_u64 v[4:5], v[4:5], 0, s[8:9]
	s_mov_b32 m0, s52
	v_lshl_add_u64 v[0:1], v[0:1], 0, s[8:9]
	global_load_lds_dwordx4 v[4:5], off
	s_add_i32 m0, s31, 0x1c000
	v_and_b32_e32 v147, 15, v12
	global_load_lds_dwordx4 v[0:1], off
	v_lshl_add_u64 v[0:1], v[2:3], 0, s[8:9]
	s_add_i32 m0, s31, 0x1e000
	v_lshlrev_b32_e32 v2, 2, v12
	global_load_lds_dwordx4 v[0:1], off
	v_and_b32_e32 v0, 48, v12
	s_and_b32 s4, s12, 3
	s_lshl_b32 s5, s11, 13
	v_lshl_or_b32 v1, v147, 6, v0
	v_and_b32_e32 v2, 32, v2
	v_bitop3_b32 v3, v1, s5, v2 bitop3:0xde
	s_lshl_b32 s5, s4, 12
	s_sext_i32_i8 s58, s10
	v_bitop3_b32 v148, v1, s5, v2 bitop3:0xde
	s_lshl_b32 s10, s4, 6
	v_and_b32_e32 v1, 8, v12
	v_or3_b32 v157, s10, v1, v0
	v_lshlrev_b32_e32 v0, 15, v17
	v_and_b32_e32 v0, 0xffff0000, v0
	v_lshl_add_u32 v0, v16, 12, v0
	v_and_b32_e32 v1, 1, v17
	v_lshl_or_b32 v0, v1, 6, v0
	v_lshl_add_u32 v140, v18, 1, v0
	v_lshlrev_b32_e32 v0, 15, v13
	v_and_b32_e32 v0, 0xffff0000, v0
	s_waitcnt vmcnt(6)
	v_and_b32_e32 v149, 7, v12
	v_lshl_add_u32 v0, v14, 12, v0
	v_and_b32_e32 v1, 1, v13
	v_sub_u32_e32 v2, v149, v147
	v_lshl_or_b32 v0, v1, 6, v0
	s_add_i32 s56, 0, 0x10000
	s_add_i32 s57, 0, 0x14000
	s_lshl_b32 s53, s11, 6
	v_cmp_gt_u32_e64 s[4:5], 8, v147
	s_ashr_i32 s54, s20, 31
	s_mov_b32 s55, s20
	v_add_u32_e32 v150, 16, v2
	v_add_u32_e32 v151, 32, v2
	v_add_u32_e32 v152, 48, v2
	v_add_u32_e32 v153, 0x80, v2
	v_add_u32_e32 v154, 0x90, v2
	v_add_u32_e32 v155, 0xa0, v2
	v_add_u32_e32 v156, 0xb0, v2
	v_mov_b32_e32 v141, v135
	v_lshl_add_u32 v142, v15, 1, v0
	v_mov_b32_e32 v143, v135
	v_add_u32_e32 v158, s56, v148
	v_add_u32_e32 v159, 0, v3
	v_add_u32_e32 v160, s57, v148
	v_mov_b64_e32 v[144:145], 0x3ff
	s_barrier

;     __device__ bool next(int i, Unit& u) const {
;         if (i >= icnt) return false;
;         const long L = (long)(i + ioff) * G + c; if (L >= nwg) return false;
; template <class Epi>
; __device__ __forceinline__ void gemm_phase(LAS unsigned char* lds, const Gemm g, const StaticOrder& S, const Epi& E) {
;     int tid = threadIdx.x; asm volatile("" : "+v"(tid));
;     const int wid = __builtin_amdgcn_readfirstlane(tid >> 6), lane = tid & 63, wr = wid >> 2, wc = wid & 3, fr = lane & 15, fq = lane >> 4;
;     const int K = g.K, nt = K / BK;
;     unsigned voffA[2], voffB0[2], voffB1[2];
; #pragma unroll
;     for (int i = 0; i < 2; ++i) { int R, C; stage_rc(tid * 16 + i * 8192, R, C);
;         const int Rw = 64 * (R >> 5) + 16 * ((R >> 2) & 3) + 4 * ((R >> 4) & 1) + (R & 3);
;         const int Rf = 64 * (R >> 5) + 8 * ((R >> 2) & 3) + 4 * ((R >> 4) & 1) + (R & 3);
;         const int Rb0 = Epi::PERM ? (Epi::F32OUT ? Rf : Rw) : R, Rb1 = Epi::PERM ? (Epi::F32OUT ? Rf + 32 : Rw + 8) : R + HALF;
;         voffA[i] = (unsigned)(R * K + C) * 2u; voffB0[i] = (unsigned)(Rb0 * K + C) * 2u; voffB1[i] = (unsigned)(Rb1 * K + C) * 2u; }
;     const size_t kstep = (size_t)(BK * 2);
;     const size_t hstep = (size_t)HALF * K * 2;
;     const size_t tstep = 2 * hstep;
;     const unsigned ldsw = (unsigned)wid * 1024u;
;     const int aoff = lds_byte(wr * 64 + fr, fq * 8), boff = lds_byte(wc * 32 + fr, fq * 8);
;     ...
;     Unit cur, nxt; int ui = 0;
;     if (!S.next(0, cur)) return;
;     f32x4 acc[2][2][4][2];
; #pragma unroll
;     for (int a = 0; a < 2; ++a)
; #pragma unroll
;         for (int b = 0; b < 2; ++b)
; #pragma unroll
;             for (int m = 0; m < 4; ++m)
; #pragma unroll
;                 for (int n = 0; n < 2; ++n) acc[a][b][m][n] = (f32x4){0.f, 0.f, 0.f, 0.f};
;     bf16x8 At[4][2], B0[2][2], B1[2][2];
;     const char* cA = (const char*)g.A + (size_t)cur.pm * tstep; const char* cB = (const char*)g.Bt + (size_t)cur.pn * tstep;
;     PG8_STAGE(PG8_SB(0, 0), cB, voffB0); PG8_STAGE(PG8_SA(0, 0), cA, voffA); PG8_STAGE(PG8_SB(0, 1), cB, voffB1); PG8_STAGE(PG8_SA(0, 1), cA + hstep, voffA);
;     if (wr == 1) PG8_BAR;
;     PG8_WAIT_V(4); PG8_BAR;
;     PG8_STAGE(PG8_SB(1, 0), cB + kstep, voffB0); PG8_STAGE(PG8_SA(1, 0), cA + kstep, voffA); PG8_STAGE(PG8_SB(1, 1), cB + kstep, voffB1);
;     PG8_WAIT_V(6); PG8_BAR;
.LBB0_226:
	s_or_b64 exec, exec, s[4:5]
	s_mov_b64 s[4:5], s[0:1]
	s_waitcnt lgkmcnt(0)
	v_mov_b32_e32 v0, v202
	s_mov_b32 s6, s2
	v_mov_b32_e32 v12, v202
	s_barrier
	s_cmpk_gt_i32 s2, 0x17f
	v_readfirstlane_b32 s44, v12
	s_cbranch_scc1 .LBB0_239
	v_lshlrev_b32_e32 v0, 4, v12
	v_add_u32_e32 v1, 0x2000, v0
	v_ashrrev_i32_e32 v2, 31, v1
	v_lshrrev_b32_e32 v2, 22, v2
	v_add_u32_e32 v2, v1, v2
	v_ashrrev_i32_e32 v13, 10, v2
	v_mul_i32_i24_e32 v2, 0x400, v13
	v_sub_u32_e32 v1, v1, v2
	v_lshrrev_b32_e32 v2, 4, v1
	v_bitop3_b32 v1, v2, v1, 32 bitop3:0x6c
	v_ashrrev_i32_e32 v2, 31, v1
	v_lshrrev_b32_e32 v2, 26, v2
	v_add_u32_e32 v2, v1, v2
	v_lshlrev_b32_e32 v3, 3, v13
	v_ashrrev_i32_e32 v14, 6, v2
	v_and_b32_e32 v3, -16, v3
	v_add_u32_e32 v3, v14, v3
	s_load_dwordx2 s[4:5], s[4:5], 0xf0
	v_lshlrev_b32_e32 v4, 2, v3
	v_and_b32_e32 v5, 3, v14
	v_and_or_b32 v4, v4, 48, v5
	v_lshlrev_b32_e32 v5, 1, v3
	v_lshrrev_b32_e32 v6, 2, v3
	v_and_b32_e32 v2, 0xc0, v2
	v_and_b32_e32 v5, 0x3fffc0, v5
	v_and_b32_e32 v6, 4, v6
	v_sub_u32_e32 v1, v1, v2
	v_mov_b32_e32 v2, 1
	v_or3_b32 v4, v4, v5, v6
	v_lshlrev_b32_e32 v5, 5, v13
	v_ashrrev_i16_sdwa v1, v2, sext(v1) dst_sel:DWORD dst_unused:UNUSED_PAD src0_sel:DWORD src1_sel:BYTE_0
	v_and_b32_e32 v5, 32, v5
	v_bfe_i32 v15, v1, 0, 16
	s_waitcnt lgkmcnt(0)
	s_add_u32 s45, s4, 0x1cc00000
	v_add_lshl_u32 v1, v5, v15, 1
	s_addc_u32 s46, s5, 0
	v_lshl_add_u32 v128, v4, 10, v1
	v_lshl_add_u32 v132, v3, 10, v1
	v_bfe_i32 v1, v12, 27, 1
	s_add_u32 s47, s4, 0x5900000
	v_lshrrev_b32_e32 v1, 22, v1
	s_addc_u32 s48, s5, 0
	v_add_u32_e32 v1, v0, v1
	s_ashr_i32 s50, s2, 31
	v_and_b32_e32 v1, 0xfffffc00, v1
	s_lshr_b32 s6, s50, 29
	v_sub_u32_e32 v0, v0, v1
	s_add_i32 s6, s2, s6
	v_lshrrev_b32_e32 v1, 4, v0
	v_ashrrev_i32_e32 v3, 31, v12
	s_ashr_i32 s7, s6, 3
	s_and_b32 s6, s6, -8
	v_bitop3_b32 v0, v1, v0, 32 bitop3:0x6c
	v_lshrrev_b32_e32 v3, 26, v3
	s_sub_i32 s6, s2, s6
	v_ashrrev_i32_e32 v1, 31, v0
	v_add_u32_e32 v3, v12, v3
	s_lshr_b32 s8, s6, 31
	v_lshrrev_b32_e32 v1, 26, v1
	v_ashrrev_i32_e32 v17, 6, v3
	s_or_b32 s8, s8, 48
	v_add_u32_e32 v1, v0, v1
	v_lshlrev_b32_e32 v3, 3, v17
	s_mul_i32 s6, s8, s6
	v_ashrrev_i32_e32 v16, 6, v1
	v_and_b32_e32 v3, -16, v3
	s_add_i32 s6, s6, s7
	v_add_u32_e32 v3, v16, v3
	s_mul_hi_i32 s7, s6, 0x2aaaaaab
	v_lshlrev_b32_e32 v4, 2, v3
	v_and_b32_e32 v5, 3, v16
	s_lshr_b32 s8, s7, 31
	s_ashr_i32 s7, s7, 3
	v_and_or_b32 v4, v4, 48, v5
	v_lshlrev_b32_e32 v5, 1, v3
	v_lshrrev_b32_e32 v6, 2, v3
	v_and_b32_e32 v1, 0xc0, v1
	s_add_i32 s7, s7, s8
	v_and_b32_e32 v5, 0x3fffc0, v5
	v_and_b32_e32 v6, 4, v6
	v_sub_u32_e32 v0, v0, v1
	s_lshl_b32 s8, s7, 3
	v_or3_b32 v4, v4, v5, v6
	v_lshlrev_b32_e32 v5, 5, v17
	v_ashrrev_i16_sdwa v0, v2, sext(v0) dst_sel:DWORD dst_unused:UNUSED_PAD src0_sel:DWORD src1_sel:BYTE_0
	s_sub_i32 s9, 64, s8
	s_mul_i32 s7, s7, 48
	v_and_b32_e32 v5, 32, v5
	v_bfe_i32 v18, v0, 0, 16
	s_min_u32 s9, s9, 8
	s_sub_i32 s17, s6, s7
	v_add_lshl_u32 v0, v5, v18, 1
	s_sext_i32_i8 s6, s17
	v_cvt_f32_ubyte0_e32 v2, s9
	v_lshl_add_u32 v134, v4, 10, v0
	v_cvt_f32_i32_e32 v1, s6
	v_rcp_iflag_f32_e32 v4, v2
	v_lshl_add_u32 v138, v3, 10, v0
	s_ashr_i32 s16, s44, 6
	s_ashr_i32 s6, s6, 30
	v_mul_f32_e32 v0, v1, v4
	v_trunc_f32_e32 v0, v0
	v_fma_f32 v1, -v0, v2, v1
	v_cvt_i32_f32_e32 v0, v0
	s_ashr_i32 s11, s44, 8
	s_lshl_b32 s49, s16, 10
	s_or_b32 s10, s6, 1
	v_cmp_ge_f32_e64 s[6:7], |v1|, v2
	s_and_b64 s[6:7], s[6:7], exec
	s_cselect_b32 s6, s10, 0
	v_readfirstlane_b32 s7, v0
	s_add_i32 s10, s7, s6
	s_mul_i32 s6, s10, s9
	s_sub_i32 s6, s17, s6
	s_sext_i32_i8 s6, s6
	s_add_i32 s36, s8, s6
	s_ashr_i32 s37, s36, 31
	s_bfe_i64 s[8:9], s[10:11], 0x80000
	s_lshl_b64 s[6:7], s[36:37], 18
	s_lshl_b64 s[8:9], s[8:9], 18
	s_add_u32 s40, s47, s8
	s_addc_u32 s41, s48, s9
	s_add_i32 s37, s49, 0
	s_add_i32 m0, s37, 0x10000
	v_add_u32_e32 v136, 0x2000, v134
	global_load_lds_dwordx4 v134, s[40:41]
	s_add_i32 m0, s37, 0x12000
	s_add_u32 s38, s45, s6
	global_load_lds_dwordx4 v128, s[40:41]
	s_addc_u32 s39, s46, s7
	s_mov_b32 m0, s37
	s_add_i32 s51, s37, 0x2000
	global_load_lds_dwordx4 v138, s[38:39]
	s_mov_b32 m0, s51
	v_add_u32_e32 v130, 0x2000, v128
	global_load_lds_dwordx4 v132, s[38:39]
	s_add_i32 m0, s37, 0x14000
	v_mov_b32_e32 v135, 0
	global_load_lds_dwordx4 v136, s[40:41]
	s_add_i32 m0, s37, 0x16000
	s_add_u32 s6, s38, 0x20000
	s_addc_u32 s7, s39, 0
	s_add_i32 s52, s37, 0x4000
	global_load_lds_dwordx4 v130, s[40:41]
	s_mov_b32 m0, s52
	s_add_i32 s53, s37, 0x6000
	global_load_lds_dwordx4 v138, s[6:7]
	s_mov_b32 m0, s53
	v_mov_b32_e32 v129, v135
	global_load_lds_dwordx4 v132, s[6:7]
	v_mov_b32_e32 v139, v135
	v_mov_b32_e32 v133, v135
	v_mov_b32_e32 v137, v135
	v_mov_b32_e32 v131, v135
	s_mov_b32 s54, 0
	v_lshl_add_u64 v[10:11], s[40:41], 0, v[134:135]
	v_lshl_add_u64 v[8:9], s[40:41], 0, v[128:129]
	v_lshl_add_u64 v[6:7], s[38:39], 0, v[138:139]
	v_lshl_add_u64 v[4:5], s[38:39], 0, v[132:133]
	v_lshl_add_u64 v[0:1], s[40:41], 0, v[136:137]
	s_cmp_lg_u32 s11, 1
	v_lshl_add_u64 v[2:3], s[40:41], 0, v[130:131]
	s_setprio 1
	s_cbranch_scc1 .LBB0_229
	s_barrier
; #define PG8_STAGE(bufoff, gbase, voff) do { _Pragma("unroll") for (int _i = 0; _i < 2; ++_i) \
;         __builtin_amdgcn_global_load_lds((const unsigned*)((const char*)(gbase) + (voff)[_i]), (LAS unsigned*)(lds + (bufoff) + ldsw + _i * 8192), 16, 0, 0); } while (0)
; #define PG8_WAIT_V(n) asm volatile("s_waitcnt vmcnt(" #n ")" ::: "memory")
; #define PG8_BAR __builtin_amdgcn_s_barrier()
; template <class Epi>
; __device__ __forceinline__ void gemm_phase(LAS unsigned char* lds, const Gemm g, const StaticOrder& S, const Epi& E) {
;     ...
;     const unsigned ldsw = (unsigned)wid * 1024u;
;     const int aoff = lds_byte(wr * 64 + fr, fq * 8), boff = lds_byte(wc * 32 + fr, fq * 8);
;     ...
;     PG8_WAIT_V(4); PG8_BAR;
;     PG8_STAGE(PG8_SB(1, 0), cB + kstep, voffB0); PG8_STAGE(PG8_SA(1, 0), cA + kstep, voffA); PG8_STAGE(PG8_SB(1, 1), cB + kstep, voffB1);
;     PG8_WAIT_V(6); PG8_BAR;
.LBB0_229:
	s_add_u32 s6, s4, 0xec00000
	s_mov_b64 s[8:9], 0x80
	s_addc_u32 s7, s5, 0
	s_add_i32 m0, s37, 0x18000
	v_lshl_add_u64 v[10:11], v[10:11], 0, s[8:9]
	s_waitcnt vmcnt(4)
	s_barrier
	global_load_lds_dwordx4 v[10:11], off
	v_lshl_add_u64 v[8:9], v[8:9], 0, s[8:9]
	s_add_i32 m0, s37, 0x1a000
	s_add_i32 s55, s37, 0x8000
	global_load_lds_dwordx4 v[8:9], off
	v_lshl_add_u64 v[6:7], v[6:7], 0, s[8:9]
	s_mov_b32 m0, s55
	s_add_i32 s56, s37, 0xa000
	global_load_lds_dwordx4 v[6:7], off
	v_lshl_add_u64 v[4:5], v[4:5], 0, s[8:9]
	s_mov_b32 m0, s56
	v_lshl_add_u64 v[0:1], v[0:1], 0, s[8:9]
	global_load_lds_dwordx4 v[4:5], off
	s_add_i32 m0, s37, 0x1c000
	v_and_b32_e32 v146, 15, v12
	global_load_lds_dwordx4 v[0:1], off
	v_lshl_add_u64 v[0:1], v[2:3], 0, s[8:9]
	s_add_i32 m0, s37, 0x1e000
	v_lshlrev_b32_e32 v2, 2, v12
	global_load_lds_dwordx4 v[0:1], off
	v_and_b32_e32 v0, 48, v12
	s_and_b32 s4, s16, 3
	s_lshl_b32 s5, s11, 13
	v_lshl_or_b32 v1, v146, 6, v0
	v_and_b32_e32 v2, 32, v2
	v_bitop3_b32 v3, v1, s5, v2 bitop3:0xde
	s_lshl_b32 s5, s4, 12
	s_sext_i32_i8 s63, s10
	v_bitop3_b32 v147, v1, s5, v2 bitop3:0xde
	s_lshl_b32 s10, s4, 6
	v_and_b32_e32 v1, 8, v12
	v_or3_b32 v156, s10, v1, v0
	v_lshlrev_b32_e32 v0, 13, v17
	v_and_b32_e32 v0, 0xffffc000, v0
	v_lshl_add_u32 v0, v16, 10, v0
	v_and_b32_e32 v1, 1, v17
	v_lshl_or_b32 v0, v1, 6, v0
	v_lshl_add_u32 v140, v18, 1, v0
	v_lshlrev_b32_e32 v0, 13, v13
	v_and_b32_e32 v0, 0xffffc000, v0
	s_waitcnt vmcnt(6)
	v_and_b32_e32 v148, 7, v12
	v_lshl_add_u32 v0, v14, 10, v0
	v_and_b32_e32 v1, 1, v13
	v_sub_u32_e32 v2, v148, v146
	v_lshl_or_b32 v0, v1, 6, v0
	s_add_i32 s60, 0, 0x10000
	s_add_i32 s61, 0, 0x14000
	s_lshl_b32 s57, s11, 6
	v_cmp_gt_u32_e64 s[4:5], 8, v146
	s_ashr_i32 s58, s20, 31
	s_mov_b32 s59, s20
	v_add_u32_e32 v149, 16, v2
	v_add_u32_e32 v150, 32, v2
	v_add_u32_e32 v151, 48, v2
	v_add_u32_e32 v152, 0x80, v2
	v_add_u32_e32 v153, 0x90, v2
	v_add_u32_e32 v154, 0xa0, v2
	v_add_u32_e32 v155, 0xb0, v2
	v_mov_b32_e32 v141, v135
	v_lshl_add_u32 v142, v15, 1, v0
	v_mov_b32_e32 v143, v135
	v_add_u32_e32 v157, s60, v147
	v_add_u32_e32 v158, 0, v3
	v_add_u32_e32 v159, s61, v147
	s_movk_i32 s62, 0xc00
	v_mov_b64_e32 v[144:145], 0x17f
	s_barrier

; #define PG8_WAIT_V(n) asm volatile("s_waitcnt vmcnt(" #n ")" ::: "memory")
; #define PG8_BAR __builtin_amdgcn_s_barrier()
; template <class Epi>
; __device__ __forceinline__ void gemm_phase(LAS unsigned char* lds, const Gemm g, const StaticOrder& S, const Epi& E) {
;     int tid = threadIdx.x; asm volatile("" : "+v"(tid));
;     const int wid = __builtin_amdgcn_readfirstlane(tid >> 6), lane = tid & 63, wr = wid >> 2, wc = wid & 3, fr = lane & 15, fq = lane >> 4;
;     const int K = g.K, nt = K / BK;
;     unsigned voffA[2], voffB0[2], voffB1[2];
; #pragma unroll
;     for (int i = 0; i < 2; ++i) { int R, C; stage_rc(tid * 16 + i * 8192, R, C);
;         const int Rw = 64 * (R >> 5) + 16 * ((R >> 2) & 3) + 4 * ((R >> 4) & 1) + (R & 3);
;         const int Rf = 64 * (R >> 5) + 8 * ((R >> 2) & 3) + 4 * ((R >> 4) & 1) + (R & 3);
;         const int Rb0 = Epi::PERM ? (Epi::F32OUT ? Rf : Rw) : R, Rb1 = Epi::PERM ? (Epi::F32OUT ? Rf + 32 : Rw + 8) : R + HALF;
;         voffA[i] = (unsigned)(R * K + C) * 2u; voffB0[i] = (unsigned)(Rb0 * K + C) * 2u; voffB1[i] = (unsigned)(Rb1 * K + C) * 2u; }
;     const size_t kstep = (size_t)(BK * 2);
;     const size_t hstep = (size_t)HALF * K * 2;
;     const size_t tstep = 2 * hstep;
;     const unsigned ldsw = (unsigned)wid * 1024u;
;     const int aoff = lds_byte(wr * 64 + fr, fq * 8), boff = lds_byte(wc * 32 + fr, fq * 8);
;     ...
;     Unit cur, nxt; int ui = 0;
;     if (!S.next(0, cur)) return;
;     f32x4 acc[2][2][4][2];
; #pragma unroll
;     for (int a = 0; a < 2; ++a)
; #pragma unroll
;         for (int b = 0; b < 2; ++b)
; #pragma unroll
;             for (int m = 0; m < 4; ++m)
; #pragma unroll
;                 for (int n = 0; n < 2; ++n) acc[a][b][m][n] = (f32x4){0.f, 0.f, 0.f, 0.f};
;     bf16x8 At[4][2], B0[2][2], B1[2][2];
;     const char* cA = (const char*)g.A + (size_t)cur.pm * tstep; const char* cB = (const char*)g.Bt + (size_t)cur.pn * tstep;
;     PG8_STAGE(PG8_SB(0, 0), cB, voffB0); PG8_STAGE(PG8_SA(0, 0), cA, voffA); PG8_STAGE(PG8_SB(0, 1), cB, voffB1); PG8_STAGE(PG8_SA(0, 1), cA + hstep, voffA);
;     if (wr == 1) PG8_BAR;
;     PG8_WAIT_V(4); PG8_BAR;
;     PG8_STAGE(PG8_SB(1, 0), cB + kstep, voffB0); PG8_STAGE(PG8_SA(1, 0), cA + kstep, voffA); PG8_STAGE(PG8_SB(1, 1), cB + kstep, voffB1);
;     PG8_WAIT_V(6); PG8_BAR;
;     ...
;     PG8_WAIT_V(0);
;     if (wr == 0) PG8_BAR;
;     PG8_BAR;
.LBB0_238:
	s_barrier
.LBB0_239:
	s_mov_b64 s[4:5], s[0:1]
	v_mov_b32_e32 v0, v202
	s_mov_b32 s6, s2
	s_waitcnt vmcnt(0) lgkmcnt(0)
	s_barrier
	s_cmpk_lt_i32 s2, 0x200
	v_mov_b32_e32 v12, v202
	s_cselect_b64 s[6:7], -1, 0
	v_writelane_b32 v252, s6, 0
	s_cmpk_gt_i32 s2, 0x1ff
	v_readfirstlane_b32 s52, v12
	v_writelane_b32 v252, s7, 1
	s_cbranch_scc1 .LBB0_253
	v_lshlrev_b32_e32 v0, 4, v12
	v_add_u32_e32 v1, 0x2000, v0
	v_ashrrev_i32_e32 v2, 31, v1
	v_lshrrev_b32_e32 v2, 22, v2
	v_add_u32_e32 v2, v1, v2
	v_ashrrev_i32_e32 v2, 10, v2
	v_mul_i32_i24_e32 v3, 0x400, v2
	v_sub_u32_e32 v1, v1, v3
	v_lshrrev_b32_e32 v3, 4, v1
	v_bitop3_b32 v1, v3, v1, 32 bitop3:0x6c
	v_ashrrev_i32_e32 v3, 31, v1
	s_load_dwordx2 s[4:5], s[4:5], 0xf0
	v_lshrrev_b32_e32 v3, 26, v3
	v_add_u32_e32 v3, v1, v3
	v_lshlrev_b32_e32 v5, 3, v2
	v_ashrrev_i32_e32 v4, 6, v3
	v_and_b32_e32 v5, -16, v5
	v_add_u32_e32 v5, v4, v5
	v_and_b32_e32 v3, 0xc0, v3
	v_lshlrev_b32_e32 v6, 2, v5
	v_and_b32_e32 v4, 3, v4
	v_sub_u32_e32 v1, v1, v3
	v_mov_b32_e32 v3, 1
	s_waitcnt lgkmcnt(0)
	s_add_u32 s53, s4, 0x1dc00000
	v_and_or_b32 v4, v6, 48, v4
	v_lshlrev_b32_e32 v6, 1, v5
	v_lshrrev_b32_e32 v7, 2, v5
	v_lshlrev_b32_e32 v2, 5, v2
	v_ashrrev_i16_sdwa v1, v3, sext(v1) dst_sel:DWORD dst_unused:UNUSED_PAD src0_sel:DWORD src1_sel:BYTE_0
	s_addc_u32 s54, s5, 0
	v_and_b32_e32 v6, 0x7fffc0, v6
	v_and_b32_e32 v7, 4, v7
	v_and_b32_e32 v2, 32, v2
	v_bfe_i32 v1, v1, 0, 16
	s_add_u32 s55, s4, 0x5a80000
	v_or3_b32 v4, v4, v6, v7
	v_add_lshl_u32 v1, v2, v1, 1
	s_addc_u32 s56, s5, 0
	v_lshl_add_u32 v128, v4, 9, v1
	v_lshl_add_u32 v132, v5, 9, v1
	v_bfe_i32 v1, v12, 27, 1
	s_ashr_i32 s58, s2, 31
	v_lshrrev_b32_e32 v1, 22, v1
	s_lshr_b32 s6, s58, 29
	v_add_u32_e32 v1, v0, v1
	s_add_i32 s6, s2, s6
	v_and_b32_e32 v1, 0xfffffc00, v1
	s_ashr_i32 s7, s6, 3
	s_and_b32 s6, s6, -8
	v_sub_u32_e32 v0, v0, v1
	s_sub_i32 s6, s2, s6
	v_lshrrev_b32_e32 v1, 4, v0
	v_ashrrev_i32_e32 v4, 31, v12
	s_lshr_b32 s8, s6, 31
	v_bitop3_b32 v0, v1, v0, 32 bitop3:0x6c
	v_lshrrev_b32_e32 v4, 26, v4
	s_or_b32 s8, s8, 64
	v_ashrrev_i32_e32 v1, 31, v0
	v_add_u32_e32 v4, v12, v4
	s_mul_i32 s6, s8, s6
	v_lshrrev_b32_e32 v1, 26, v1
	v_ashrrev_i32_e32 v4, 6, v4
	s_add_i32 s6, s6, s7
	v_add_u32_e32 v1, v0, v1
	v_lshlrev_b32_e32 v5, 3, v4
	s_ashr_i32 s7, s6, 31
	v_ashrrev_i32_e32 v2, 6, v1
	v_and_b32_e32 v5, -16, v5
	s_lshr_b32 s7, s7, 26
	v_add_u32_e32 v5, v2, v5
	v_and_b32_e32 v1, 0xc0, v1
	s_add_i32 s7, s6, s7
	v_lshlrev_b32_e32 v6, 2, v5
	v_and_b32_e32 v2, 3, v2
	v_sub_u32_e32 v0, v0, v1
	s_ashr_i32 s7, s7, 6
	v_and_or_b32 v2, v6, 48, v2
	v_lshlrev_b32_e32 v6, 1, v5
	v_lshrrev_b32_e32 v7, 2, v5
	v_lshlrev_b32_e32 v4, 5, v4
	v_ashrrev_i16_sdwa v0, v3, sext(v0) dst_sel:DWORD dst_unused:UNUSED_PAD src0_sel:DWORD src1_sel:BYTE_0
	s_lshl_b32 s8, s7, 3
	v_and_b32_e32 v6, 0x7fffc0, v6
	v_and_b32_e32 v7, 4, v7
	v_and_b32_e32 v4, 32, v4
	v_bfe_i32 v0, v0, 0, 16
	s_sub_i32 s9, 64, s8
	s_lshl_b32 s7, s7, 6
	v_or3_b32 v2, v2, v6, v7
	v_add_lshl_u32 v0, v4, v0, 1
	s_min_u32 s9, s9, 8
	s_sub_i32 s16, s6, s7
	v_lshl_add_u32 v134, v2, 9, v0
	s_sext_i32_i8 s6, s16
	v_cvt_f32_ubyte0_e32 v2, s9
	v_cvt_f32_i32_e32 v1, s6
	v_rcp_iflag_f32_e32 v3, v2
	v_lshl_add_u32 v138, v5, 9, v0
	s_ashr_i32 s18, s52, 6
	s_ashr_i32 s6, s6, 30
	v_mul_f32_e32 v0, v1, v3
	v_trunc_f32_e32 v0, v0
	v_fma_f32 v1, -v0, v2, v1
	v_cvt_i32_f32_e32 v0, v0
	s_ashr_i32 s11, s52, 8
	s_lshl_b32 s57, s18, 10
	s_or_b32 s10, s6, 1
	v_cmp_ge_f32_e64 s[6:7], |v1|, v2
	s_and_b64 s[6:7], s[6:7], exec
	s_cselect_b32 s6, s10, 0
	v_readfirstlane_b32 s7, v0
	s_add_i32 s10, s7, s6
	s_mul_i32 s6, s10, s9
	s_sub_i32 s6, s16, s6
	s_sext_i32_i8 s6, s6
	s_add_i32 s38, s8, s6
	s_ashr_i32 s39, s38, 31
	s_bfe_i64 s[8:9], s[10:11], 0x80000
	s_lshl_b64 s[6:7], s[38:39], 17
	s_lshl_b64 s[8:9], s[8:9], 17
	s_add_u32 s40, s55, s8
	s_addc_u32 s41, s56, s9
	s_add_i32 s39, s57, 0
	s_add_i32 m0, s39, 0x10000
	v_add_u32_e32 v136, 0x1000, v134
	global_load_lds_dwordx4 v134, s[40:41]
	s_add_i32 m0, s39, 0x12000
	s_add_u32 s42, s53, s6
	global_load_lds_dwordx4 v128, s[40:41]
	s_addc_u32 s43, s54, s7
	s_mov_b32 m0, s39
	s_add_i32 s59, s39, 0x2000
	global_load_lds_dwordx4 v138, s[42:43]
	s_mov_b32 m0, s59
	v_add_u32_e32 v130, 0x1000, v128
	global_load_lds_dwordx4 v132, s[42:43]
	s_add_i32 m0, s39, 0x14000
	v_mov_b32_e32 v135, 0
	global_load_lds_dwordx4 v136, s[40:41]
	s_add_i32 m0, s39, 0x16000
	s_add_u32 s6, s42, 0x10000
	s_addc_u32 s7, s43, 0
	s_add_i32 s60, s39, 0x4000
	global_load_lds_dwordx4 v130, s[40:41]
	s_mov_b32 m0, s60
	s_add_i32 s61, s39, 0x6000
	global_load_lds_dwordx4 v138, s[6:7]
	s_mov_b32 m0, s61
	v_mov_b32_e32 v129, v135
	global_load_lds_dwordx4 v132, s[6:7]
	v_mov_b32_e32 v139, v135
	v_mov_b32_e32 v133, v135
	v_mov_b32_e32 v137, v135
	v_mov_b32_e32 v131, v135
	s_mov_b32 s62, 0
	v_lshl_add_u64 v[10:11], s[40:41], 0, v[134:135]
	v_lshl_add_u64 v[8:9], s[40:41], 0, v[128:129]
	v_lshl_add_u64 v[6:7], s[42:43], 0, v[138:139]
	v_lshl_add_u64 v[4:5], s[42:43], 0, v[132:133]
	v_lshl_add_u64 v[0:1], s[40:41], 0, v[136:137]
	s_cmp_lg_u32 s11, 1
	v_lshl_add_u64 v[2:3], s[40:41], 0, v[130:131]
	s_setprio 1
	s_cbranch_scc1 .LBB0_242
	s_barrier
.LBB0_242:
	s_add_u32 s6, s4, 0x11c00000
	s_mov_b64 s[8:9], 0x80
	s_addc_u32 s7, s5, 0
	s_add_i32 m0, s39, 0x18000
	v_lshl_add_u64 v[10:11], v[10:11], 0, s[8:9]
	s_waitcnt vmcnt(4)
	s_barrier
	global_load_lds_dwordx4 v[10:11], off
	v_lshl_add_u64 v[8:9], v[8:9], 0, s[8:9]
	s_add_i32 m0, s39, 0x1a000
	s_add_i32 s63, s39, 0x8000
	global_load_lds_dwordx4 v[8:9], off
	v_lshl_add_u64 v[6:7], v[6:7], 0, s[8:9]
	s_mov_b32 m0, s63
	s_add_i32 s64, s39, 0xa000
	global_load_lds_dwordx4 v[6:7], off
	v_lshl_add_u64 v[4:5], v[4:5], 0, s[8:9]
	s_mov_b32 m0, s64
	v_lshl_add_u64 v[0:1], v[0:1], 0, s[8:9]
	global_load_lds_dwordx4 v[4:5], off
	s_add_i32 m0, s39, 0x1c000
	v_and_b32_e32 v142, 15, v12
	global_load_lds_dwordx4 v[0:1], off
	v_lshl_add_u64 v[0:1], v[2:3], 0, s[8:9]
	s_add_i32 m0, s39, 0x1e000
	v_lshlrev_b32_e32 v2, 2, v12
	global_load_lds_dwordx4 v[0:1], off
	v_and_b32_e32 v0, 48, v12
	s_and_b32 s4, s18, 3
	s_lshl_b32 s5, s11, 13
	v_lshl_or_b32 v1, v142, 6, v0
	v_and_b32_e32 v2, 32, v2
	v_bitop3_b32 v3, v1, s5, v2 bitop3:0xde
	s_lshl_b32 s5, s4, 12
	s_waitcnt vmcnt(6)
	v_and_b32_e32 v144, 7, v12
	s_sext_i32_i8 s71, s10
	v_bitop3_b32 v143, v1, s5, v2 bitop3:0xde
	s_lshl_b32 s10, s4, 6
	v_and_b32_e32 v1, 8, v12
	v_sub_u32_e32 v2, v144, v142
	s_add_i32 s69, 0, 0x10000
	s_add_i32 s70, 0, 0x14000
	s_lshl_b32 s65, s11, 6
	s_mov_b32 s66, 0x8000
	v_cmp_gt_u32_e64 s[4:5], 8, v142
	s_ashr_i32 s67, s20, 31
	s_mov_b32 s68, s20
	v_add_u32_e32 v145, 16, v2
	v_add_u32_e32 v146, 32, v2
	v_add_u32_e32 v147, 48, v2
	v_add_u32_e32 v148, 0x80, v2
	v_add_u32_e32 v149, 0x90, v2
	v_add_u32_e32 v150, 0xa0, v2
	v_add_u32_e32 v151, 0xb0, v2
	v_or3_b32 v152, s10, v1, v0
	v_add_u32_e32 v153, s69, v143
	v_add_u32_e32 v154, 0, v3
	v_add_u32_e32 v155, s70, v143
	v_mov_b64_e32 v[140:141], 0x1ff
	s_barrier

; #define PG8_WAIT_V(n) asm volatile("s_waitcnt vmcnt(" #n ")" ::: "memory")
; #define PG8_BAR __builtin_amdgcn_s_barrier()
; template <class Epi>
; __device__ __forceinline__ void gemm_phase(LAS unsigned char* lds, const Gemm g, const StaticOrder& S, const Epi& E) {
;     int tid = threadIdx.x; asm volatile("" : "+v"(tid));
;     const int wid = __builtin_amdgcn_readfirstlane(tid >> 6), lane = tid & 63, wr = wid >> 2, wc = wid & 3, fr = lane & 15, fq = lane >> 4;
;     const int K = g.K, nt = K / BK;
;     unsigned voffA[2], voffB0[2], voffB1[2];
; #pragma unroll
;     for (int i = 0; i < 2; ++i) { int R, C; stage_rc(tid * 16 + i * 8192, R, C);
;         const int Rw = 64 * (R >> 5) + 16 * ((R >> 2) & 3) + 4 * ((R >> 4) & 1) + (R & 3);
;         const int Rf = 64 * (R >> 5) + 8 * ((R >> 2) & 3) + 4 * ((R >> 4) & 1) + (R & 3);
;         const int Rb0 = Epi::PERM ? (Epi::F32OUT ? Rf : Rw) : R, Rb1 = Epi::PERM ? (Epi::F32OUT ? Rf + 32 : Rw + 8) : R + HALF;
;         voffA[i] = (unsigned)(R * K + C) * 2u; voffB0[i] = (unsigned)(Rb0 * K + C) * 2u; voffB1[i] = (unsigned)(Rb1 * K + C) * 2u; }
;     const size_t kstep = (size_t)(BK * 2);
;     const size_t hstep = (size_t)HALF * K * 2;
;     const size_t tstep = 2 * hstep;
;     const unsigned ldsw = (unsigned)wid * 1024u;
;     const int aoff = lds_byte(wr * 64 + fr, fq * 8), boff = lds_byte(wc * 32 + fr, fq * 8);
;     ...
;     Unit cur, nxt; int ui = 0;
;     if (!S.next(0, cur)) return;
;     f32x4 acc[2][2][4][2];
; #pragma unroll
;     for (int a = 0; a < 2; ++a)
; #pragma unroll
;         for (int b = 0; b < 2; ++b)
; #pragma unroll
;             for (int m = 0; m < 4; ++m)
; #pragma unroll
;                 for (int n = 0; n < 2; ++n) acc[a][b][m][n] = (f32x4){0.f, 0.f, 0.f, 0.f};
;     bf16x8 At[4][2], B0[2][2], B1[2][2];
;     const char* cA = (const char*)g.A + (size_t)cur.pm * tstep; const char* cB = (const char*)g.Bt + (size_t)cur.pn * tstep;
;     PG8_STAGE(PG8_SB(0, 0), cB, voffB0); PG8_STAGE(PG8_SA(0, 0), cA, voffA); PG8_STAGE(PG8_SB(0, 1), cB, voffB1); PG8_STAGE(PG8_SA(0, 1), cA + hstep, voffA);
;     if (wr == 1) PG8_BAR;
;     PG8_WAIT_V(4); PG8_BAR;
;     PG8_STAGE(PG8_SB(1, 0), cB + kstep, voffB0); PG8_STAGE(PG8_SA(1, 0), cA + kstep, voffA); PG8_STAGE(PG8_SB(1, 1), cB + kstep, voffB1);
;     PG8_WAIT_V(6); PG8_BAR;
.LBB0_600:
	s_load_dwordx4 s[16:19], s[8:9], 0x0
	s_and_b64 vcc, exec, s[4:5]
	s_cbranch_vccnz .LBB0_633
	v_ashrrev_i32_e32 v1, 31, v12
	v_lshrrev_b32_e32 v1, 26, v1
	v_add_u32_e32 v1, v12, v1
	v_ashrrev_i32_e32 v13, 6, v1
	v_bfe_i32 v1, v12, 27, 1
	v_lshlrev_b32_e32 v0, 4, v12
	v_lshrrev_b32_e32 v1, 22, v1
	v_add_u32_e32 v1, v0, v1
	v_and_b32_e32 v1, 0xfffffc00, v1
	v_sub_u32_e32 v1, v0, v1
	v_lshrrev_b32_e32 v2, 4, v1
	v_bitop3_b32 v1, v2, v1, 32 bitop3:0x6c
	v_ashrrev_i32_e32 v3, 31, v1
	v_lshrrev_b32_e32 v3, 26, v3
	v_add_u32_e32 v3, v1, v3
	v_lshlrev_b32_e32 v2, 3, v13
	v_ashrrev_i32_e32 v14, 6, v3
	v_and_b32_e32 v3, 0xc0, v3
	v_and_b32_e32 v2, -16, v2
	v_sub_u32_e32 v1, v1, v3
	v_mov_b32_e32 v3, 1
	v_add_u32_e32 v2, v14, v2
	v_ashrrev_i16_sdwa v1, v3, sext(v1) dst_sel:DWORD dst_unused:UNUSED_PAD src0_sel:DWORD src1_sel:BYTE_0
	v_lshlrev_b32_e32 v4, 5, v13
	v_bfe_i32 v15, v1, 0, 16
	v_lshlrev_b32_e32 v1, 1, v2
	v_lshlrev_b32_e32 v5, 2, v2
	v_lshrrev_b32_e32 v6, 2, v2
	v_and_b32_e32 v7, 3, v14
	v_and_b32_e32 v4, 32, v4
	v_and_b32_e32 v1, 0xfffc0, v1
	v_and_b32_e32 v6, 4, v6
	v_and_or_b32 v5, v5, 48, v7
	v_or3_b32 v1, v5, v1, v6
	v_add_lshl_u32 v4, v4, v15, 1
	v_add_u32_e32 v0, 0x2000, v0
	v_lshl_add_u32 v130, v1, 12, v4
	v_ashrrev_i32_e32 v1, 31, v0
	v_lshrrev_b32_e32 v1, 22, v1
	v_add_u32_e32 v1, v0, v1
	s_waitcnt vmcnt(5)
	v_ashrrev_i32_e32 v16, 10, v1
	v_mul_i32_i24_e32 v1, 0x400, v16
	v_sub_u32_e32 v0, v0, v1
	v_lshrrev_b32_e32 v1, 4, v0
	v_bitop3_b32 v0, v1, v0, 32 bitop3:0x6c
	s_waitcnt lgkmcnt(0)
	s_add_u32 s61, s6, 0xec00000
	v_lshl_add_u32 v128, v2, 12, v4
	v_ashrrev_i32_e32 v2, 31, v0
	s_addc_u32 s62, s7, 0
	v_lshrrev_b32_e32 v2, 26, v2
	s_add_u32 s63, s6, 0x5b80000
	v_add_u32_e32 v2, v0, v2
	s_addc_u32 s64, s7, 0
	s_ashr_i32 s8, s60, 6
	v_lshlrev_b32_e32 v1, 3, v16
	v_ashrrev_i32_e32 v17, 6, v2
	v_and_b32_e32 v2, 0xc0, v2
	s_ashr_i32 s53, s52, 31
	s_ashr_i32 s51, s50, 31
	v_and_b32_e32 v1, -16, v1
	v_sub_u32_e32 v0, v0, v2
	s_ashr_i32 s9, s60, 8
	s_lshl_b32 s65, s8, 10
	s_lshl_b64 s[10:11], s[52:53], 20
	s_lshl_b64 s[12:13], s[50:51], 20
	v_add_u32_e32 v1, v17, v1
	v_ashrrev_i16_sdwa v0, v3, sext(v0) dst_sel:DWORD dst_unused:UNUSED_PAD src0_sel:DWORD src1_sel:BYTE_0
	s_add_u32 s56, s63, s12
	v_lshlrev_b32_e32 v4, 5, v16
	v_bfe_i32 v18, v0, 0, 16
	v_lshlrev_b32_e32 v0, 1, v1
	v_lshlrev_b32_e32 v2, 2, v1
	v_lshrrev_b32_e32 v3, 2, v1
	v_and_b32_e32 v5, 3, v17
	s_addc_u32 s57, s64, s13
	s_add_i32 s53, s65, 0
	v_and_b32_e32 v4, 32, v4
	v_and_b32_e32 v0, 0xfffc0, v0
	v_and_b32_e32 v3, 4, v3
	v_and_or_b32 v2, v2, 48, v5
	s_add_i32 m0, s53, 0x10000
	v_or3_b32 v0, v2, v0, v3
	v_add_lshl_u32 v2, v4, v18, 1
	global_load_lds_dwordx4 v130, s[56:57]
	s_add_i32 m0, s53, 0x12000
	v_lshl_add_u32 v136, v0, 12, v2
	s_add_u32 s54, s61, s10
	global_load_lds_dwordx4 v136, s[56:57]
	s_addc_u32 s55, s62, s11
	s_mov_b32 m0, s53
	s_add_i32 s66, s53, 0x2000
	v_lshl_add_u32 v134, v1, 12, v2
	global_load_lds_dwordx4 v128, s[54:55]
	s_mov_b32 m0, s66
	v_add_u32_e32 v132, 0x8000, v130
	global_load_lds_dwordx4 v134, s[54:55]
	s_add_i32 m0, s53, 0x14000
	v_add_u32_e32 v138, 0x8000, v136
	global_load_lds_dwordx4 v132, s[56:57]
	s_add_i32 m0, s53, 0x16000
	s_add_u32 s10, s54, 0x80000
	s_addc_u32 s11, s55, 0
	s_add_i32 s67, s53, 0x4000
	global_load_lds_dwordx4 v138, s[56:57]
	s_mov_b32 m0, s67
	s_add_i32 s68, s53, 0x6000
	global_load_lds_dwordx4 v128, s[10:11]
	s_mov_b32 m0, s68
	v_mov_b32_e32 v131, 0
	global_load_lds_dwordx4 v134, s[10:11]
	v_mov_b32_e32 v137, v131
	v_mov_b32_e32 v129, v131
	v_mov_b32_e32 v135, v131
	v_mov_b32_e32 v133, v131
	v_mov_b32_e32 v139, v131
	s_mov_b32 s69, 0x8000
	s_movk_i32 s70, 0x2000
	s_mov_b32 s71, 0
	v_lshl_add_u64 v[10:11], s[56:57], 0, v[130:131]
	v_lshl_add_u64 v[8:9], s[56:57], 0, v[136:137]
	v_lshl_add_u64 v[6:7], s[54:55], 0, v[128:129]
	v_lshl_add_u64 v[4:5], s[54:55], 0, v[134:135]
	v_lshl_add_u64 v[0:1], s[56:57], 0, v[132:133]
	s_cmp_lg_u32 s9, 1
	v_lshl_add_u64 v[2:3], s[56:57], 0, v[138:139]
	s_setprio 1
	s_cbranch_scc1 .LBB0_603
	s_barrier
.LBB0_603:
	s_add_u32 s10, s6, 0x6400000
	s_addc_u32 s11, s7, 0
	s_add_u32 s12, s6, 0x1ec00000
	s_mov_b64 s[36:37], 0x80
	s_addc_u32 s13, s7, 0
	s_add_i32 m0, s53, 0x18000
	v_lshl_add_u64 v[10:11], v[10:11], 0, s[36:37]
	s_waitcnt vmcnt(4)
	s_barrier
	global_load_lds_dwordx4 v[10:11], off
	v_lshl_add_u64 v[8:9], v[8:9], 0, s[36:37]
	s_add_i32 m0, s53, 0x1a000
	s_add_i32 s72, s53, 0x8000
	global_load_lds_dwordx4 v[8:9], off
	v_lshl_add_u64 v[6:7], v[6:7], 0, s[36:37]
	s_mov_b32 m0, s72
	s_add_i32 s73, s53, 0xa000
	global_load_lds_dwordx4 v[6:7], off
	v_lshl_add_u64 v[4:5], v[4:5], 0, s[36:37]
	s_mov_b32 m0, s73
	v_lshl_add_u64 v[0:1], v[0:1], 0, s[36:37]
	global_load_lds_dwordx4 v[4:5], off
	s_add_i32 m0, s53, 0x1c000
	s_and_b32 s33, s8, 3
	global_load_lds_dwordx4 v[0:1], off
	v_lshl_add_u64 v[0:1], v[2:3], 0, s[36:37]
	s_add_i32 m0, s53, 0x1e000
	s_lshl_b32 s74, s9, 6
	global_load_lds_dwordx4 v[0:1], off
	v_bfe_u32 v0, v12, 4, 2
	v_lshlrev_b32_e32 v1, 4, v0
	s_lshl_b32 s6, s9, 13
	v_cmp_eq_u32_e64 s[8:9], 0, v0
	v_lshlrev_b32_e32 v0, 15, v13
	v_and_b32_e32 v150, 15, v12
	v_and_b32_e32 v0, 0xffff0000, v0
	v_lshl_or_b32 v2, v150, 6, v1
	v_lshl_or_b32 v154, s33, 6, v1
	v_lshl_add_u32 v0, v14, 12, v0
	v_and_b32_e32 v1, 1, v13
	v_lshl_or_b32 v0, v1, 6, v0
	v_lshlrev_b32_e32 v3, 2, v12
	v_lshl_add_u32 v140, v15, 1, v0
	v_lshlrev_b32_e32 v0, 15, v16
	v_and_b32_e32 v3, 32, v3
	v_and_b32_e32 v0, 0xffff0000, v0
	v_bitop3_b32 v4, v2, s6, v3 bitop3:0xde
	s_lshl_b32 s6, s33, 12
	s_waitcnt vmcnt(6)
	v_lshl_add_u32 v0, v17, 12, v0
	v_and_b32_e32 v1, 1, v16
	v_bitop3_b32 v151, v2, s6, v3 bitop3:0xde
	v_lshl_or_b32 v0, v1, 6, v0
	s_add_i32 s79, 0, 0x10000
	s_add_i32 s80, 0, 0x14000
	s_brev_b32 s38, 63
	v_cmp_gt_u32_e64 s[6:7], 8, v150
	v_and_b32_e32 v152, 7, v12
	v_and_b32_e32 v153, 8, v12
	s_ashr_i32 s75, s20, 31
	s_mov_b32 s77, s20
	s_ashr_i32 s78, s2, 31
	v_mov_b32_e32 v141, v131
	v_lshl_add_u32 v142, v18, 1, v0
	v_mov_b32_e32 v143, v131
	v_add_u32_e32 v155, s79, v151
	v_add_u32_e32 v156, 0, v4
	v_add_u32_e32 v157, s80, v151
	s_mov_b32 s39, -1
	s_movk_i32 s81, 0x1f80
	s_movk_i32 s82, 0x1f70
	s_movk_i32 s83, 0x1f60
	s_movk_i32 s84, 0x1f50
	v_mov_b64_e32 v[144:145], 0x1ff
	s_barrier
	s_branch .LBB0_605

; #define PG8_WAIT_V(n) asm volatile("s_waitcnt vmcnt(" #n ")" ::: "memory")
; #define PG8_BAR __builtin_amdgcn_s_barrier()
; template <class Epi>
; __device__ __forceinline__ void gemm_phase(LAS unsigned char* lds, const Gemm g, const StaticOrder& S, const Epi& E) {
;     int tid = threadIdx.x; asm volatile("" : "+v"(tid));
;     const int wid = __builtin_amdgcn_readfirstlane(tid >> 6), lane = tid & 63, wr = wid >> 2, wc = wid & 3, fr = lane & 15, fq = lane >> 4;
;     const int K = g.K, nt = K / BK;
;     unsigned voffA[2], voffB0[2], voffB1[2];
; #pragma unroll
;     for (int i = 0; i < 2; ++i) { int R, C; stage_rc(tid * 16 + i * 8192, R, C);
;         const int Rw = 64 * (R >> 5) + 16 * ((R >> 2) & 3) + 4 * ((R >> 4) & 1) + (R & 3);
;         const int Rf = 64 * (R >> 5) + 8 * ((R >> 2) & 3) + 4 * ((R >> 4) & 1) + (R & 3);
;         const int Rb0 = Epi::PERM ? (Epi::F32OUT ? Rf : Rw) : R, Rb1 = Epi::PERM ? (Epi::F32OUT ? Rf + 32 : Rw + 8) : R + HALF;
;         voffA[i] = (unsigned)(R * K + C) * 2u; voffB0[i] = (unsigned)(Rb0 * K + C) * 2u; voffB1[i] = (unsigned)(Rb1 * K + C) * 2u; }
;     const size_t kstep = (size_t)(BK * 2);
;     const size_t hstep = (size_t)HALF * K * 2;
;     const size_t tstep = 2 * hstep;
;     const unsigned ldsw = (unsigned)wid * 1024u;
;     const int aoff = lds_byte(wr * 64 + fr, fq * 8), boff = lds_byte(wc * 32 + fr, fq * 8);
;     ...
;     Unit cur, nxt; int ui = 0;
;     if (!S.next(0, cur)) return;
;     f32x4 acc[2][2][4][2];
; #pragma unroll
;     for (int a = 0; a < 2; ++a)
; #pragma unroll
;         for (int b = 0; b < 2; ++b)
; #pragma unroll
;             for (int m = 0; m < 4; ++m)
; #pragma unroll
;                 for (int n = 0; n < 2; ++n) acc[a][b][m][n] = (f32x4){0.f, 0.f, 0.f, 0.f};
;     bf16x8 At[4][2], B0[2][2], B1[2][2];
;     const char* cA = (const char*)g.A + (size_t)cur.pm * tstep; const char* cB = (const char*)g.Bt + (size_t)cur.pn * tstep;
;     PG8_STAGE(PG8_SB(0, 0), cB, voffB0); PG8_STAGE(PG8_SA(0, 0), cA, voffA); PG8_STAGE(PG8_SB(0, 1), cB, voffB1); PG8_STAGE(PG8_SA(0, 1), cA + hstep, voffA);
;     if (wr == 1) PG8_BAR;
;     PG8_WAIT_V(4); PG8_BAR;
;     PG8_STAGE(PG8_SB(1, 0), cB + kstep, voffB0); PG8_STAGE(PG8_SA(1, 0), cA + kstep, voffA); PG8_STAGE(PG8_SB(1, 1), cB + kstep, voffB1);
;     PG8_WAIT_V(6); PG8_BAR;
.LBB0_635:
	s_and_b64 vcc, exec, s[4:5]
	s_cbranch_vccnz .LBB0_665
	v_bfe_i32 v2, v12, 27, 1
	v_lshlrev_b32_e32 v0, 4, v12
	v_lshrrev_b32_e32 v2, 22, v2
	v_add_u32_e32 v2, v0, v2
	v_and_b32_e32 v2, 0xfffffc00, v2
	v_sub_u32_e32 v2, v0, v2
	v_ashrrev_i32_e32 v1, 31, v12
	v_lshrrev_b32_e32 v3, 4, v2
	v_lshrrev_b32_e32 v1, 26, v1
	v_bitop3_b32 v2, v3, v2, 32 bitop3:0x6c
	v_add_u32_e32 v1, v12, v1
	v_ashrrev_i32_e32 v4, 31, v2
	v_ashrrev_i32_e32 v1, 6, v1
	v_lshrrev_b32_e32 v4, 26, v4
	v_lshlrev_b32_e32 v3, 3, v1
	v_add_u32_e32 v4, v2, v4
	v_and_b32_e32 v3, -16, v3
	v_ashrrev_i32_e32 v5, 6, v4
	v_and_b32_e32 v4, 0xc0, v4
	v_add_u32_e32 v3, v5, v3
	v_sub_u32_e32 v2, v2, v4
	v_mov_b32_e32 v4, 1
	v_lshlrev_b32_e32 v1, 5, v1
	v_ashrrev_i16_sdwa v2, v4, sext(v2) dst_sel:DWORD dst_unused:UNUSED_PAD src0_sel:DWORD src1_sel:BYTE_0
	v_lshlrev_b32_e32 v6, 1, v3
	v_lshlrev_b32_e32 v7, 2, v3
	v_lshrrev_b32_e32 v8, 2, v3
	v_and_b32_e32 v5, 3, v5
	v_and_b32_e32 v1, 32, v1
	v_bfe_i32 v2, v2, 0, 16
	v_and_b32_e32 v6, 0x7fffc0, v6
	v_and_b32_e32 v8, 4, v8
	v_and_or_b32 v5, v7, 48, v5
	v_or3_b32 v5, v5, v6, v8
	v_add_lshl_u32 v1, v1, v2, 1
	v_add_u32_e32 v0, 0x2000, v0
	v_lshl_add_u32 v128, v3, 9, v1
	v_lshl_add_u32 v130, v5, 9, v1
	v_ashrrev_i32_e32 v1, 31, v0
	v_lshrrev_b32_e32 v1, 22, v1
	s_load_dwordx2 s[6:7], s[6:7], 0xf0
	v_add_u32_e32 v1, v0, v1
	v_ashrrev_i32_e32 v1, 10, v1
	v_mul_i32_i24_e32 v2, 0x400, v1
	v_sub_u32_e32 v0, v0, v2
	v_lshrrev_b32_e32 v2, 4, v0
	s_waitcnt lgkmcnt(0)
	s_add_u32 s61, s6, 0xe400000
	v_bitop3_b32 v0, v2, v0, 32 bitop3:0x6c
	s_addc_u32 s62, s7, 0
	v_ashrrev_i32_e32 v3, 31, v0
	s_add_u32 s63, s6, 0x4800000
	v_lshrrev_b32_e32 v3, 26, v3
	s_addc_u32 s64, s7, 0
	s_ashr_i32 s8, s60, 6
	v_lshlrev_b32_e32 v2, 3, v1
	v_add_u32_e32 v3, v0, v3
	s_ashr_i32 s47, s46, 31
	s_ashr_i32 s45, s44, 31
	v_and_b32_e32 v2, -16, v2
	v_ashrrev_i32_e32 v5, 6, v3
	v_and_b32_e32 v3, 0xc0, v3
	s_ashr_i32 s9, s60, 8
	s_lshl_b32 s65, s8, 10
	s_lshl_b64 s[10:11], s[46:47], 17
	s_lshl_b64 s[12:13], s[44:45], 17
	v_add_u32_e32 v2, v5, v2
	v_sub_u32_e32 v0, v0, v3
	s_add_u32 s48, s63, s12
	v_lshlrev_b32_e32 v1, 5, v1
	v_ashrrev_i16_sdwa v0, v4, sext(v0) dst_sel:DWORD dst_unused:UNUSED_PAD src0_sel:DWORD src1_sel:BYTE_0
	v_lshlrev_b32_e32 v3, 1, v2
	v_lshlrev_b32_e32 v4, 2, v2
	v_lshrrev_b32_e32 v6, 2, v2
	v_and_b32_e32 v5, 3, v5
	s_addc_u32 s49, s64, s13
	s_add_i32 s47, s65, 0
	v_and_b32_e32 v1, 32, v1
	v_bfe_i32 v0, v0, 0, 16
	v_and_b32_e32 v3, 0x7fffc0, v3
	v_and_b32_e32 v6, 4, v6
	v_and_or_b32 v4, v4, 48, v5
	s_add_i32 m0, s47, 0x10000
	v_or3_b32 v3, v4, v3, v6
	v_add_lshl_u32 v0, v1, v0, 1
	global_load_lds_dwordx4 v130, s[48:49]
	s_add_i32 m0, s47, 0x12000
	v_lshl_add_u32 v136, v3, 9, v0
	s_add_u32 s50, s61, s10
	global_load_lds_dwordx4 v136, s[48:49]
	s_addc_u32 s51, s62, s11
	s_mov_b32 m0, s47
	s_add_i32 s66, s47, 0x2000
	v_lshl_add_u32 v134, v2, 9, v0
	global_load_lds_dwordx4 v128, s[50:51]
	s_mov_b32 m0, s66
	v_add_u32_e32 v132, 0x1000, v130
	global_load_lds_dwordx4 v134, s[50:51]
	s_add_i32 m0, s47, 0x14000
	v_add_u32_e32 v138, 0x1000, v136
	global_load_lds_dwordx4 v132, s[48:49]
	s_add_i32 m0, s47, 0x16000
	s_add_u32 s10, s50, 0x10000
	s_addc_u32 s11, s51, 0
	s_add_i32 s67, s47, 0x4000
	global_load_lds_dwordx4 v138, s[48:49]
	s_mov_b32 m0, s67
	s_add_i32 s68, s47, 0x6000
	global_load_lds_dwordx4 v128, s[10:11]
	s_mov_b32 m0, s68
	v_mov_b32_e32 v131, 0
	global_load_lds_dwordx4 v134, s[10:11]
	v_mov_b32_e32 v137, v131
	v_mov_b32_e32 v129, v131
	v_mov_b32_e32 v135, v131
	v_mov_b32_e32 v133, v131
	v_mov_b32_e32 v139, v131
	s_mov_b32 s69, 0
	v_lshl_add_u64 v[10:11], s[48:49], 0, v[130:131]
	v_lshl_add_u64 v[8:9], s[48:49], 0, v[136:137]
	v_lshl_add_u64 v[6:7], s[50:51], 0, v[128:129]
	v_lshl_add_u64 v[4:5], s[50:51], 0, v[134:135]
	v_lshl_add_u64 v[0:1], s[48:49], 0, v[132:133]
	s_cmp_lg_u32 s9, 1
	v_lshl_add_u64 v[2:3], s[48:49], 0, v[138:139]
	s_setprio 1
	s_cbranch_scc1 .LBB0_638
	s_barrier
.LBB0_638:
	s_add_u32 s10, s6, 0xa400000
	s_addc_u32 s11, s7, 0
	s_add_u32 s12, s6, 0x1ec30000
	s_mov_b64 s[16:17], 0x80
	s_addc_u32 s13, s7, 0
	s_add_i32 m0, s47, 0x18000
	v_lshl_add_u64 v[10:11], v[10:11], 0, s[16:17]
	s_waitcnt vmcnt(4)
	s_barrier
	global_load_lds_dwordx4 v[10:11], off
	v_lshl_add_u64 v[8:9], v[8:9], 0, s[16:17]
	s_add_i32 m0, s47, 0x1a000
	s_add_i32 s70, s47, 0x8000
	global_load_lds_dwordx4 v[8:9], off
	v_lshl_add_u64 v[6:7], v[6:7], 0, s[16:17]
	s_mov_b32 m0, s70
	s_add_i32 s71, s47, 0xa000
	global_load_lds_dwordx4 v[6:7], off
	v_lshl_add_u64 v[4:5], v[4:5], 0, s[16:17]
	s_mov_b32 m0, s71
	v_lshl_add_u64 v[0:1], v[0:1], 0, s[16:17]
	global_load_lds_dwordx4 v[4:5], off
	s_add_i32 m0, s47, 0x1c000
	v_and_b32_e32 v146, 15, v12
	global_load_lds_dwordx4 v[0:1], off
	v_lshl_add_u64 v[0:1], v[2:3], 0, s[16:17]
	s_add_i32 m0, s47, 0x1e000
	v_lshlrev_b32_e32 v3, 2, v12
	global_load_lds_dwordx4 v[0:1], off
	v_bfe_u32 v0, v12, 4, 2
	v_lshlrev_b32_e32 v1, 4, v0
	s_and_b32 s6, s8, 3
	v_lshl_or_b32 v2, v146, 6, v1
	s_lshl_b32 s7, s9, 13
	v_and_b32_e32 v3, 32, v3
	v_bitop3_b32 v4, v2, s7, v3 bitop3:0xde
	s_lshl_b32 s7, s6, 12
	s_waitcnt vmcnt(6)
	v_bitop3_b32 v147, v2, s7, v3 bitop3:0xde
	s_lshl_b32 s18, s6, 6
	v_and_b32_e32 v2, 8, v12
	s_add_i32 s78, 0, 0x10000
	s_add_i32 s79, 0, 0x14000
	s_lshl_b32 s72, s9, 6
	s_mov_b32 s73, 0x8000
	v_cmp_gt_u32_e64 s[6:7], 8, v146
	v_and_b32_e32 v148, 7, v12
	v_cmp_eq_u32_e64 s[8:9], 0, v0
	s_ashr_i32 s74, s20, 31
	s_mov_b32 s75, s20
	s_ashr_i32 s77, s2, 31
	v_or3_b32 v149, s18, v2, v1
	v_add_u32_e32 v150, s78, v147
	v_add_u32_e32 v151, 0, v4
	v_add_u32_e32 v152, s79, v147
	v_mov_b64_e32 v[140:141], 0x1ff
	s_barrier
	s_waitcnt vmcnt(0)
	s_branch .LBB0_640

; #define PG8_WAIT_V(n) asm volatile("s_waitcnt vmcnt(" #n ")" ::: "memory")
; #define PG8_BAR __builtin_amdgcn_s_barrier()
; template <class Epi>
; __device__ __forceinline__ void gemm_phase(LAS unsigned char* lds, const Gemm g, const StaticOrder& S, const Epi& E) {
;     int tid = threadIdx.x; asm volatile("" : "+v"(tid));
;     const int wid = __builtin_amdgcn_readfirstlane(tid >> 6), lane = tid & 63, wr = wid >> 2, wc = wid & 3, fr = lane & 15, fq = lane >> 4;
;     const int K = g.K, nt = K / BK;
;     unsigned voffA[2], voffB0[2], voffB1[2];
; #pragma unroll
;     for (int i = 0; i < 2; ++i) { int R, C; stage_rc(tid * 16 + i * 8192, R, C);
;         const int Rw = 64 * (R >> 5) + 16 * ((R >> 2) & 3) + 4 * ((R >> 4) & 1) + (R & 3);
;         const int Rf = 64 * (R >> 5) + 8 * ((R >> 2) & 3) + 4 * ((R >> 4) & 1) + (R & 3);
;         const int Rb0 = Epi::PERM ? (Epi::F32OUT ? Rf : Rw) : R, Rb1 = Epi::PERM ? (Epi::F32OUT ? Rf + 32 : Rw + 8) : R + HALF;
;         voffA[i] = (unsigned)(R * K + C) * 2u; voffB0[i] = (unsigned)(Rb0 * K + C) * 2u; voffB1[i] = (unsigned)(Rb1 * K + C) * 2u; }
;     const size_t kstep = (size_t)(BK * 2);
;     const size_t hstep = (size_t)HALF * K * 2;
;     const size_t tstep = 2 * hstep;
;     const unsigned ldsw = (unsigned)wid * 1024u;
;     const int aoff = lds_byte(wr * 64 + fr, fq * 8), boff = lds_byte(wc * 32 + fr, fq * 8);
;     ...
;     Unit cur, nxt; int ui = 0;
;     if (!S.next(0, cur)) return;
;     f32x4 acc[2][2][4][2];
; #pragma unroll
;     for (int a = 0; a < 2; ++a)
; #pragma unroll
;         for (int b = 0; b < 2; ++b)
; #pragma unroll
;             for (int m = 0; m < 4; ++m)
; #pragma unroll
;                 for (int n = 0; n < 2; ++n) acc[a][b][m][n] = (f32x4){0.f, 0.f, 0.f, 0.f};
;     bf16x8 At[4][2], B0[2][2], B1[2][2];
;     const char* cA = (const char*)g.A + (size_t)cur.pm * tstep; const char* cB = (const char*)g.Bt + (size_t)cur.pn * tstep;
;     PG8_STAGE(PG8_SB(0, 0), cB, voffB0); PG8_STAGE(PG8_SA(0, 0), cA, voffA); PG8_STAGE(PG8_SB(0, 1), cB, voffB1); PG8_STAGE(PG8_SA(0, 1), cA + hstep, voffA);
;     if (wr == 1) PG8_BAR;
;     PG8_WAIT_V(4); PG8_BAR;
;     PG8_STAGE(PG8_SB(1, 0), cB + kstep, voffB0); PG8_STAGE(PG8_SA(1, 0), cA + kstep, voffA); PG8_STAGE(PG8_SB(1, 1), cB + kstep, voffB1);
;     PG8_WAIT_V(6); PG8_BAR;
.LBB0_722:
	v_ashrrev_i32_e32 v1, 31, v12
	v_lshrrev_b32_e32 v1, 26, v1
	v_add_u32_e32 v1, v12, v1
	v_ashrrev_i32_e32 v13, 6, v1
	v_bfe_i32 v1, v12, 27, 1
	v_lshlrev_b32_e32 v0, 4, v12
	v_lshrrev_b32_e32 v1, 22, v1
	v_add_u32_e32 v1, v0, v1
	v_and_b32_e32 v1, 0xfffffc00, v1
	v_sub_u32_e32 v1, v0, v1
	v_lshrrev_b32_e32 v2, 4, v1
	v_bitop3_b32 v1, v2, v1, 32 bitop3:0x6c
	v_ashrrev_i32_e32 v3, 31, v1
	v_lshrrev_b32_e32 v3, 26, v3
	v_add_u32_e32 v3, v1, v3
	v_lshlrev_b32_e32 v2, 3, v13
	v_ashrrev_i32_e32 v14, 6, v3
	v_and_b32_e32 v3, 0xc0, v3
	v_and_b32_e32 v2, -16, v2
	v_sub_u32_e32 v1, v1, v3
	v_mov_b32_e32 v3, 1
	s_ashr_i32 s6, s11, 3
	v_add_u32_e32 v2, v14, v2
	v_ashrrev_i16_sdwa v1, v3, sext(v1) dst_sel:DWORD dst_unused:UNUSED_PAD src0_sel:DWORD src1_sel:BYTE_0
	s_waitcnt lgkmcnt(0)
	s_add_u32 s54, s8, 0x6400000
	v_lshlrev_b32_e32 v4, 5, v13
	v_bfe_i32 v15, v1, 0, 16
	v_lshlrev_b32_e32 v1, 1, v2
	v_lshlrev_b32_e32 v5, 2, v2
	v_lshrrev_b32_e32 v6, 2, v2
	v_and_b32_e32 v7, 3, v14
	s_addc_u32 s55, s9, 0
	v_and_b32_e32 v4, 32, v4
	v_and_b32_e32 v1, 0xfffc0, v1
	v_and_b32_e32 v6, 4, v6
	v_and_or_b32 v5, v5, 48, v7
	s_add_i32 s6, s10, s6
	v_or3_b32 v1, v5, v1, v6
	v_add_lshl_u32 v4, v4, v15, 1
	v_add_u32_e32 v0, 0x2000, v0
	s_ashr_i32 s10, s6, 31
	v_lshl_add_u32 v130, v1, 12, v4
	v_ashrrev_i32_e32 v1, 31, v0
	s_lshr_b32 s10, s10, 24
	v_lshrrev_b32_e32 v1, 22, v1
	s_add_i32 s10, s6, s10
	v_add_u32_e32 v1, v0, v1
	s_ashr_i32 s11, s10, 8
	s_and_b32 s10, s10, 0xffffff00
	v_ashrrev_i32_e32 v16, 10, v1
	s_sub_i32 s10, s6, s10
	v_mul_i32_i24_e32 v1, 0x400, v16
	s_sext_i32_i16 s6, s10
	v_sub_u32_e32 v0, v0, v1
	s_bfe_u32 s6, s6, 0x3001c
	v_lshrrev_b32_e32 v1, 4, v0
	s_add_i32 s16, s10, s6
	v_bitop3_b32 v0, v1, v0, 32 bitop3:0x6c
	s_sext_i32_i16 s6, s16
	s_and_b32 s16, s16, 0xfff8
	v_lshl_add_u32 v128, v2, 12, v4
	v_ashrrev_i32_e32 v2, 31, v0
	s_sub_i32 s10, s10, s16
	v_lshrrev_b32_e32 v2, 26, v2
	s_lshl_b32 s11, s11, 3
	s_sext_i32_i16 s10, s10
	s_ashr_i32 s7, s52, 6
	v_add_u32_e32 v2, v0, v2
	s_lshr_b32 s6, s6, 3
	s_add_i32 s44, s11, s10
	v_lshlrev_b32_e32 v1, 3, v16
	v_ashrrev_i32_e32 v17, 6, v2
	v_and_b32_e32 v2, 0xc0, v2
	s_ashr_i32 s45, s44, 31
	s_bfe_i64 s[16:17], s[6:7], 0x100000
	v_and_b32_e32 v1, -16, v1
	v_sub_u32_e32 v0, v0, v2
	s_ashr_i32 s18, s52, 8
	s_lshl_b32 s56, s7, 10
	s_lshl_b64 s[10:11], s[44:45], 20
	s_lshl_b64 s[16:17], s[16:17], 20
	v_add_u32_e32 v1, v17, v1
	v_ashrrev_i16_sdwa v0, v3, sext(v0) dst_sel:DWORD dst_unused:UNUSED_PAD src0_sel:DWORD src1_sel:BYTE_0
	s_add_u32 s48, s8, s16
	v_lshlrev_b32_e32 v4, 5, v16
	v_bfe_i32 v18, v0, 0, 16
	v_lshlrev_b32_e32 v0, 1, v1
	v_lshlrev_b32_e32 v2, 2, v1
	v_lshrrev_b32_e32 v3, 2, v1
	v_and_b32_e32 v5, 3, v17
	s_addc_u32 s49, s9, s17
	s_add_i32 s45, s56, 0
	v_and_b32_e32 v4, 32, v4
	v_and_b32_e32 v0, 0xfffc0, v0
	v_and_b32_e32 v3, 4, v3
	v_and_or_b32 v2, v2, 48, v5
	s_add_i32 m0, s45, 0x10000
	v_or3_b32 v0, v2, v0, v3
	v_add_lshl_u32 v2, v4, v18, 1
	global_load_lds_dwordx4 v130, s[48:49]
	s_add_i32 m0, s45, 0x12000
	v_lshl_add_u32 v136, v0, 12, v2
	s_add_u32 s46, s54, s10
	global_load_lds_dwordx4 v136, s[48:49]
	s_addc_u32 s47, s55, s11
	s_mov_b32 m0, s45
	s_add_i32 s57, s45, 0x2000
	v_lshl_add_u32 v134, v1, 12, v2
	global_load_lds_dwordx4 v128, s[46:47]
	s_mov_b32 m0, s57
	v_add_u32_e32 v132, 0x8000, v130
	global_load_lds_dwordx4 v134, s[46:47]
	s_add_i32 m0, s45, 0x14000
	v_add_u32_e32 v138, 0x8000, v136
	global_load_lds_dwordx4 v132, s[48:49]
	s_add_i32 m0, s45, 0x16000
	s_add_u32 s10, s46, 0x80000
	s_addc_u32 s11, s47, 0
	s_add_i32 s58, s45, 0x4000
	global_load_lds_dwordx4 v138, s[48:49]
	s_mov_b32 m0, s58
	s_add_i32 s59, s45, 0x6000
	global_load_lds_dwordx4 v128, s[10:11]
	s_mov_b32 m0, s59
	v_mov_b32_e32 v131, 0
	global_load_lds_dwordx4 v134, s[10:11]
	v_mov_b32_e32 v137, v131
	v_mov_b32_e32 v129, v131
	v_mov_b32_e32 v135, v131
	v_mov_b32_e32 v133, v131
	v_mov_b32_e32 v139, v131
	s_mov_b32 s60, 0
	v_lshl_add_u64 v[10:11], s[48:49], 0, v[130:131]
	v_lshl_add_u64 v[8:9], s[48:49], 0, v[136:137]
	v_lshl_add_u64 v[6:7], s[46:47], 0, v[128:129]
	v_lshl_add_u64 v[4:5], s[46:47], 0, v[134:135]
	v_lshl_add_u64 v[0:1], s[48:49], 0, v[132:133]
	s_cmp_lg_u32 s18, 1
	v_lshl_add_u64 v[2:3], s[48:49], 0, v[138:139]
	s_setprio 1
	s_cbranch_scc1 .LBB0_724
	s_barrier
.LBB0_724:
	s_add_u32 s10, s8, 0xec00000
	s_mov_b64 s[16:17], 0x80
	s_addc_u32 s11, s9, 0
	s_add_i32 m0, s45, 0x18000
	v_lshl_add_u64 v[10:11], v[10:11], 0, s[16:17]
	s_waitcnt vmcnt(4)
	s_barrier
	global_load_lds_dwordx4 v[10:11], off
	v_lshl_add_u64 v[8:9], v[8:9], 0, s[16:17]
	s_add_i32 m0, s45, 0x1a000
	s_add_i32 s61, s45, 0x8000
	global_load_lds_dwordx4 v[8:9], off
	v_lshl_add_u64 v[6:7], v[6:7], 0, s[16:17]
	s_mov_b32 m0, s61
	s_add_i32 s62, s45, 0xa000
	global_load_lds_dwordx4 v[6:7], off
	v_lshl_add_u64 v[4:5], v[4:5], 0, s[16:17]
	s_mov_b32 m0, s62
	v_lshl_add_u64 v[0:1], v[0:1], 0, s[16:17]
	global_load_lds_dwordx4 v[4:5], off
	s_add_i32 m0, s45, 0x1c000
	v_and_b32_e32 v146, 15, v12
	global_load_lds_dwordx4 v[0:1], off
	v_lshl_add_u64 v[0:1], v[2:3], 0, s[16:17]
	s_add_i32 m0, s45, 0x1e000
	v_lshlrev_b32_e32 v2, 2, v12
	global_load_lds_dwordx4 v[0:1], off
	v_and_b32_e32 v0, 48, v12
	s_sext_i32_i16 s69, s6
	s_and_b32 s6, s7, 3
	s_lshl_b32 s7, s18, 13
	v_lshl_or_b32 v1, v146, 6, v0
	v_and_b32_e32 v2, 32, v2
	v_bitop3_b32 v3, v1, s7, v2 bitop3:0xde
	s_lshl_b32 s7, s6, 12
	s_lshl_b32 s63, s18, 6
	v_bitop3_b32 v147, v1, s7, v2 bitop3:0xde
	s_lshl_b32 s18, s6, 6
	v_and_b32_e32 v1, 8, v12
	v_or3_b32 v156, s18, v1, v0
	v_lshlrev_b32_e32 v0, 15, v13
	v_and_b32_e32 v0, 0xffff0000, v0
	v_lshl_add_u32 v0, v14, 12, v0
	v_and_b32_e32 v1, 1, v13
	v_lshl_or_b32 v0, v1, 6, v0
	v_lshl_add_u32 v140, v15, 1, v0
	v_lshlrev_b32_e32 v0, 15, v16
	v_and_b32_e32 v0, 0xffff0000, v0
	s_waitcnt vmcnt(6)
	v_and_b32_e32 v148, 7, v12
	v_lshl_add_u32 v0, v17, 12, v0
	v_and_b32_e32 v1, 1, v16
	v_sub_u32_e32 v2, v148, v146
	v_lshl_or_b32 v0, v1, 6, v0
	s_add_i32 s66, 0, 0x10000
	s_add_i32 s67, 0, 0x14000
	v_cmp_gt_u32_e64 s[6:7], 8, v146
	s_ashr_i32 s64, s20, 31
	s_mov_b32 s65, s20
	v_add_u32_e32 v149, 16, v2
	v_add_u32_e32 v150, 32, v2
	v_add_u32_e32 v151, 48, v2
	v_add_u32_e32 v152, 0x80, v2
	v_add_u32_e32 v153, 0x90, v2
	v_add_u32_e32 v154, 0xa0, v2
	v_add_u32_e32 v155, 0xb0, v2
	v_mov_b32_e32 v141, v131
	v_lshl_add_u32 v142, v18, 1, v0
	v_mov_b32_e32 v143, v131
	v_add_u32_e32 v157, s66, v147
	v_add_u32_e32 v158, 0, v3
	v_add_u32_e32 v159, s67, v147
	s_mov_b32 s68, 0x20000
	v_mov_b64_e32 v[144:145], 0x7ff
	s_barrier

; #define PG8_WAIT_V(n) asm volatile("s_waitcnt vmcnt(" #n ")" ::: "memory")
; #define PG8_BAR __builtin_amdgcn_s_barrier()
; template <class Epi>
; __device__ __forceinline__ void gemm_phase(LAS unsigned char* lds, const Gemm g, const StaticOrder& S, const Epi& E) {
;     int tid = threadIdx.x; asm volatile("" : "+v"(tid));
;     const int wid = __builtin_amdgcn_readfirstlane(tid >> 6), lane = tid & 63, wr = wid >> 2, wc = wid & 3, fr = lane & 15, fq = lane >> 4;
;     const int K = g.K, nt = K / BK;
;     unsigned voffA[2], voffB0[2], voffB1[2];
; #pragma unroll
;     for (int i = 0; i < 2; ++i) { int R, C; stage_rc(tid * 16 + i * 8192, R, C);
;         const int Rw = 64 * (R >> 5) + 16 * ((R >> 2) & 3) + 4 * ((R >> 4) & 1) + (R & 3);
;         const int Rf = 64 * (R >> 5) + 8 * ((R >> 2) & 3) + 4 * ((R >> 4) & 1) + (R & 3);
;         const int Rb0 = Epi::PERM ? (Epi::F32OUT ? Rf : Rw) : R, Rb1 = Epi::PERM ? (Epi::F32OUT ? Rf + 32 : Rw + 8) : R + HALF;
;         voffA[i] = (unsigned)(R * K + C) * 2u; voffB0[i] = (unsigned)(Rb0 * K + C) * 2u; voffB1[i] = (unsigned)(Rb1 * K + C) * 2u; }
;     const size_t kstep = (size_t)(BK * 2);
;     const size_t hstep = (size_t)HALF * K * 2;
;     const size_t tstep = 2 * hstep;
;     const unsigned ldsw = (unsigned)wid * 1024u;
;     const int aoff = lds_byte(wr * 64 + fr, fq * 8), boff = lds_byte(wc * 32 + fr, fq * 8);
;     ...
;     Unit cur, nxt; int ui = 0;
;     if (!S.next(0, cur)) return;
;     f32x4 acc[2][2][4][2];
; #pragma unroll
;     for (int a = 0; a < 2; ++a)
; #pragma unroll
;         for (int b = 0; b < 2; ++b)
; #pragma unroll
;             for (int m = 0; m < 4; ++m)
; #pragma unroll
;                 for (int n = 0; n < 2; ++n) acc[a][b][m][n] = (f32x4){0.f, 0.f, 0.f, 0.f};
;     bf16x8 At[4][2], B0[2][2], B1[2][2];
;     const char* cA = (const char*)g.A + (size_t)cur.pm * tstep; const char* cB = (const char*)g.Bt + (size_t)cur.pn * tstep;
;     PG8_STAGE(PG8_SB(0, 0), cB, voffB0); PG8_STAGE(PG8_SA(0, 0), cA, voffA); PG8_STAGE(PG8_SB(0, 1), cB, voffB1); PG8_STAGE(PG8_SA(0, 1), cA + hstep, voffA);
;     if (wr == 1) PG8_BAR;
;     PG8_WAIT_V(4); PG8_BAR;
;     PG8_STAGE(PG8_SB(1, 0), cB + kstep, voffB0); PG8_STAGE(PG8_SA(1, 0), cA + kstep, voffA); PG8_STAGE(PG8_SB(1, 1), cB + kstep, voffB1);
;     PG8_WAIT_V(6); PG8_BAR;
.LBB0_795:
	v_ashrrev_i32_e32 v1, 31, v12
	v_lshrrev_b32_e32 v1, 26, v1
	v_add_u32_e32 v1, v12, v1
	v_ashrrev_i32_e32 v13, 6, v1
	v_bfe_i32 v1, v12, 27, 1
	v_lshlrev_b32_e32 v0, 4, v12
	v_lshrrev_b32_e32 v1, 22, v1
	v_add_u32_e32 v1, v0, v1
	v_and_b32_e32 v1, 0xfffffc00, v1
	v_sub_u32_e32 v1, v0, v1
	v_lshrrev_b32_e32 v2, 4, v1
	v_bitop3_b32 v2, v2, v1, 32 bitop3:0x6c
	v_ashrrev_i32_e32 v1, 31, v1
	v_lshrrev_b32_e32 v1, 26, v1
	v_add_u32_e32 v1, v2, v1
	s_ashr_i32 s6, s19, 3
	v_ashrrev_i32_e32 v14, 6, v1
	s_waitcnt lgkmcnt(0)
	s_add_u32 s58, s10, 0xec00000
	v_lshlrev_b32_e32 v3, 3, v13
	v_mul_i32_i24_e32 v4, 64, v14
	s_addc_u32 s59, s11, 0
	v_and_b32_e32 v3, -16, v3
	v_sub_u32_e32 v2, v2, v4
	v_mov_b32_e32 v4, 1
	s_add_u32 s60, s10, 0x2000000
	v_add_u32_e32 v1, v14, v3
	v_lshlrev_b32_e32 v3, 5, v13
	v_ashrrev_i16_sdwa v2, v4, sext(v2) dst_sel:DWORD dst_unused:UNUSED_PAD src0_sel:DWORD src1_sel:BYTE_0
	s_addc_u32 s61, s11, 0
	v_and_b32_e32 v3, 32, v3
	v_bfe_i32 v15, v2, 0, 16
	s_add_i32 s6, s18, s6
	v_add_lshl_u32 v3, v3, v15, 1
	v_add_u32_e32 v0, 0x2000, v0
	s_ashr_i32 s16, s6, 31
	v_lshlrev_b32_e32 v2, 1, v1
	v_lshlrev_b32_e32 v5, 2, v1
	v_lshrrev_b32_e32 v6, 2, v1
	v_lshl_add_u32 v128, v1, 14, v3
	v_ashrrev_i32_e32 v1, 31, v0
	s_lshr_b32 s16, s16, 26
	v_lshrrev_b32_e32 v1, 22, v1
	s_add_i32 s16, s6, s16
	v_add_u32_e32 v1, v0, v1
	s_ashr_i32 s17, s16, 6
	s_andn2_b32 s16, s16, 63
	v_ashrrev_i32_e32 v16, 10, v1
	s_sub_i32 s16, s6, s16
	v_mul_i32_i24_e32 v1, 0x400, v16
	s_bfe_i32 s6, s16, 0x80000
	v_and_b32_e32 v7, 3, v14
	v_sub_u32_e32 v0, v0, v1
	s_bfe_u32 s6, s6, 0x3000c
	v_and_b32_e32 v2, 0x3ffc0, v2
	v_and_b32_e32 v6, 4, v6
	v_and_or_b32 v5, v5, 48, v7
	v_lshrrev_b32_e32 v1, 4, v0
	s_add_i32 s18, s16, s6
	v_or3_b32 v2, v5, v2, v6
	v_bitop3_b32 v0, v1, v0, 32 bitop3:0x6c
	s_bfe_i32 s6, s18, 0x80000
	s_and_b32 s18, s18, 0xf8
	v_lshl_add_u32 v130, v2, 14, v3
	v_ashrrev_i32_e32 v2, 31, v0
	s_sub_i32 s16, s16, s18
	v_lshrrev_b32_e32 v2, 26, v2
	s_lshl_b32 s17, s17, 3
	s_sext_i32_i16 s6, s6
	s_sext_i32_i8 s16, s16
	s_ashr_i32 s7, s56, 6
	v_add_u32_e32 v2, v0, v2
	s_lshr_b32 s6, s6, 3
	s_add_i32 s48, s17, s16
	v_lshlrev_b32_e32 v1, 3, v16
	v_ashrrev_i32_e32 v17, 6, v2
	v_and_b32_e32 v2, 0xc0, v2
	s_ashr_i32 s49, s48, 31
	s_bfe_i64 s[18:19], s[6:7], 0x100000
	v_and_b32_e32 v1, -16, v1
	v_sub_u32_e32 v0, v0, v2
	s_ashr_i32 s36, s56, 8
	s_lshl_b32 s62, s7, 10
	s_lshl_b64 s[16:17], s[48:49], 22
	s_lshl_b64 s[18:19], s[18:19], 22
	v_add_u32_e32 v1, v17, v1
	v_ashrrev_i16_sdwa v0, v4, sext(v0) dst_sel:DWORD dst_unused:UNUSED_PAD src0_sel:DWORD src1_sel:BYTE_0
	s_add_u32 s52, s60, s18
	v_lshlrev_b32_e32 v3, 5, v16
	v_bfe_i32 v18, v0, 0, 16
	v_lshlrev_b32_e32 v0, 1, v1
	v_lshlrev_b32_e32 v2, 2, v1
	v_lshrrev_b32_e32 v4, 2, v1
	v_and_b32_e32 v5, 3, v17
	s_addc_u32 s53, s61, s19
	s_add_i32 s49, s62, 0
	v_and_b32_e32 v3, 32, v3
	v_and_b32_e32 v0, 0x3ffc0, v0
	v_and_b32_e32 v4, 4, v4
	v_and_or_b32 v2, v2, 48, v5
	s_add_i32 m0, s49, 0x10000
	v_or3_b32 v0, v2, v0, v4
	v_add_lshl_u32 v2, v3, v18, 1
	global_load_lds_dwordx4 v130, s[52:53]
	s_add_i32 m0, s49, 0x12000
	v_lshl_add_u32 v136, v0, 14, v2
	s_add_u32 s50, s58, s16
	global_load_lds_dwordx4 v136, s[52:53]
	s_addc_u32 s51, s59, s17
	s_mov_b32 m0, s49
	s_add_i32 s63, s49, 0x2000
	v_lshl_add_u32 v134, v1, 14, v2
	global_load_lds_dwordx4 v128, s[50:51]
	s_mov_b32 m0, s63
	v_add_u32_e32 v132, 0x20000, v130
	global_load_lds_dwordx4 v134, s[50:51]
	s_add_i32 m0, s49, 0x14000
	v_add_u32_e32 v138, 0x20000, v136
	global_load_lds_dwordx4 v132, s[52:53]
	s_add_i32 m0, s49, 0x16000
	s_add_u32 s16, s50, 0x200000
	s_addc_u32 s17, s51, 0
	s_add_i32 s64, s49, 0x4000
	global_load_lds_dwordx4 v138, s[52:53]
	s_mov_b32 m0, s64
	s_add_i32 s65, s49, 0x6000
	global_load_lds_dwordx4 v128, s[16:17]
	s_mov_b32 m0, s65
	v_mov_b32_e32 v131, 0
	global_load_lds_dwordx4 v134, s[16:17]
	v_mov_b32_e32 v137, v131
	v_mov_b32_e32 v129, v131
	v_mov_b32_e32 v135, v131
	v_mov_b32_e32 v133, v131
	v_mov_b32_e32 v139, v131
	s_mov_b32 s66, 0
	v_lshl_add_u64 v[10:11], s[52:53], 0, v[130:131]
	v_lshl_add_u64 v[8:9], s[52:53], 0, v[136:137]
	v_lshl_add_u64 v[6:7], s[50:51], 0, v[128:129]
	v_lshl_add_u64 v[4:5], s[50:51], 0, v[134:135]
	v_lshl_add_u64 v[0:1], s[52:53], 0, v[132:133]
	s_cmp_lg_u32 s36, 1
	v_lshl_add_u64 v[2:3], s[52:53], 0, v[138:139]
	s_setprio 1
	s_cbranch_scc1 .LBB0_797
	s_barrier
.LBB0_797:
	s_add_u32 s16, s10, 0x6400000
	s_addc_u32 s17, s11, 0
	s_add_u32 s10, s10, 0x1ec00000
	s_mov_b64 s[18:19], 0x80
	s_addc_u32 s11, s11, 0
	s_add_i32 m0, s49, 0x18000
	v_lshl_add_u64 v[10:11], v[10:11], 0, s[18:19]
	s_waitcnt vmcnt(4)
	s_barrier
	global_load_lds_dwordx4 v[10:11], off
	v_lshl_add_u64 v[8:9], v[8:9], 0, s[18:19]
	s_add_i32 m0, s49, 0x1a000
	s_add_i32 s67, s49, 0x8000
	global_load_lds_dwordx4 v[8:9], off
	v_lshl_add_u64 v[6:7], v[6:7], 0, s[18:19]
	s_mov_b32 m0, s67
	s_add_i32 s68, s49, 0xa000
	global_load_lds_dwordx4 v[6:7], off
	v_lshl_add_u64 v[4:5], v[4:5], 0, s[18:19]
	s_mov_b32 m0, s68
	v_lshl_add_u64 v[0:1], v[0:1], 0, s[18:19]
	global_load_lds_dwordx4 v[4:5], off
	s_add_i32 m0, s49, 0x1c000
	v_and_b32_e32 v152, 15, v12
	global_load_lds_dwordx4 v[0:1], off
	v_lshl_add_u64 v[0:1], v[2:3], 0, s[18:19]
	s_add_i32 m0, s49, 0x1e000
	v_lshlrev_b32_e32 v2, 2, v12
	global_load_lds_dwordx4 v[0:1], off
	v_and_b32_e32 v0, 48, v12
	s_sext_i32_i8 s74, s6
	s_and_b32 s6, s7, 3
	s_lshl_b32 s7, s36, 13
	v_lshl_or_b32 v1, v152, 6, v0
	v_and_b32_e32 v2, 32, v2
	v_bitop3_b32 v3, v1, s7, v2 bitop3:0xde
	s_lshl_b32 s7, s6, 12
	v_bitop3_b32 v153, v1, s7, v2 bitop3:0xde
	s_lshl_b32 s33, s6, 6
	v_and_b32_e32 v1, 8, v12
	v_or3_b32 v155, s33, v1, v0
	v_lshlrev_b32_e32 v0, 17, v13
	v_and_b32_e32 v0, 0xfffc0000, v0
	v_lshl_add_u32 v0, v14, 14, v0
	v_and_b32_e32 v1, 1, v13
	v_lshl_or_b32 v0, v1, 6, v0
	v_lshl_add_u32 v140, v15, 1, v0
	v_lshlrev_b32_e32 v0, 17, v16
	v_and_b32_e32 v0, 0xfffc0000, v0
	s_waitcnt vmcnt(6)
	v_lshl_add_u32 v0, v17, 14, v0
	v_and_b32_e32 v1, 1, v16
	v_lshl_or_b32 v0, v1, 6, v0
	s_add_i32 s72, 0, 0x10000
	s_add_i32 s73, 0, 0x14000
	s_lshl_b32 s69, s36, 6
	v_cmp_gt_u32_e64 s[6:7], 8, v152
	v_and_b32_e32 v154, 7, v12
	s_ashr_i32 s70, s20, 31
	s_mov_b32 s71, s20
	v_mov_b32_e32 v141, v131
	v_lshl_add_u32 v142, v18, 1, v0
	v_mov_b32_e32 v143, v131
	v_add_u32_e32 v156, s72, v153
	v_add_u32_e32 v157, 0, v3
	v_add_u32_e32 v158, s73, v153
	v_mov_b32_e32 v159, 0x358637bd
	s_mov_b64 s[36:37], 0x8000
	v_mov_b64_e32 v[144:145], 0x1ff
	s_barrier

; #define PG8_WAIT_V(n) asm volatile("s_waitcnt vmcnt(" #n ")" ::: "memory")
; #define PG8_BAR __builtin_amdgcn_s_barrier()
; template <class Epi>
; __device__ __forceinline__ void gemm_phase(LAS unsigned char* lds, const Gemm g, const StaticOrder& S, const Epi& E) {
;     int tid = threadIdx.x; asm volatile("" : "+v"(tid));
;     const int wid = __builtin_amdgcn_readfirstlane(tid >> 6), lane = tid & 63, wr = wid >> 2, wc = wid & 3, fr = lane & 15, fq = lane >> 4;
;     const int K = g.K, nt = K / BK;
;     unsigned voffA[2], voffB0[2], voffB1[2];
; #pragma unroll
;     for (int i = 0; i < 2; ++i) { int R, C; stage_rc(tid * 16 + i * 8192, R, C);
;         const int Rw = 64 * (R >> 5) + 16 * ((R >> 2) & 3) + 4 * ((R >> 4) & 1) + (R & 3);
;         const int Rf = 64 * (R >> 5) + 8 * ((R >> 2) & 3) + 4 * ((R >> 4) & 1) + (R & 3);
;         const int Rb0 = Epi::PERM ? (Epi::F32OUT ? Rf : Rw) : R, Rb1 = Epi::PERM ? (Epi::F32OUT ? Rf + 32 : Rw + 8) : R + HALF;
;         voffA[i] = (unsigned)(R * K + C) * 2u; voffB0[i] = (unsigned)(Rb0 * K + C) * 2u; voffB1[i] = (unsigned)(Rb1 * K + C) * 2u; }
;     const size_t kstep = (size_t)(BK * 2);
;     const size_t hstep = (size_t)HALF * K * 2;
;     const size_t tstep = 2 * hstep;
;     const unsigned ldsw = (unsigned)wid * 1024u;
;     const int aoff = lds_byte(wr * 64 + fr, fq * 8), boff = lds_byte(wc * 32 + fr, fq * 8);
;     ...
;     Unit cur, nxt; int ui = 0;
;     if (!S.next(0, cur)) return;
;     f32x4 acc[2][2][4][2];
; #pragma unroll
;     for (int a = 0; a < 2; ++a)
; #pragma unroll
;         for (int b = 0; b < 2; ++b)
; #pragma unroll
;             for (int m = 0; m < 4; ++m)
; #pragma unroll
;                 for (int n = 0; n < 2; ++n) acc[a][b][m][n] = (f32x4){0.f, 0.f, 0.f, 0.f};
;     bf16x8 At[4][2], B0[2][2], B1[2][2];
;     const char* cA = (const char*)g.A + (size_t)cur.pm * tstep; const char* cB = (const char*)g.Bt + (size_t)cur.pn * tstep;
;     PG8_STAGE(PG8_SB(0, 0), cB, voffB0); PG8_STAGE(PG8_SA(0, 0), cA, voffA); PG8_STAGE(PG8_SB(0, 1), cB, voffB1); PG8_STAGE(PG8_SA(0, 1), cA + hstep, voffA);
;     if (wr == 1) PG8_BAR;
;     PG8_WAIT_V(4); PG8_BAR;
;     PG8_STAGE(PG8_SB(1, 0), cB + kstep, voffB0); PG8_STAGE(PG8_SA(1, 0), cA + kstep, voffA); PG8_STAGE(PG8_SB(1, 1), cB + kstep, voffB1);
;     PG8_WAIT_V(6); PG8_BAR;
.LBB0_869:
	s_load_dwordx4 s[16:19], s[6:7], 0xe8
	s_and_b64 vcc, exec, s[4:5]
	s_cbranch_vccnz .LBB0_902
	v_ashrrev_i32_e32 v1, 31, v12
	v_lshrrev_b32_e32 v1, 26, v1
	v_add_u32_e32 v1, v12, v1
	v_ashrrev_i32_e32 v13, 6, v1
	v_bfe_i32 v1, v12, 27, 1
	v_lshlrev_b32_e32 v0, 4, v12
	v_lshrrev_b32_e32 v1, 22, v1
	v_add_u32_e32 v1, v0, v1
	v_and_b32_e32 v1, 0xfffffc00, v1
	v_sub_u32_e32 v1, v0, v1
	v_lshrrev_b32_e32 v2, 4, v1
	v_bitop3_b32 v1, v2, v1, 32 bitop3:0x6c
	v_ashrrev_i32_e32 v3, 31, v1
	v_lshrrev_b32_e32 v3, 26, v3
	v_add_u32_e32 v3, v1, v3
	v_lshlrev_b32_e32 v2, 3, v13
	v_ashrrev_i32_e32 v14, 6, v3
	v_and_b32_e32 v3, 0xc0, v3
	v_and_b32_e32 v2, -16, v2
	v_sub_u32_e32 v1, v1, v3
	v_mov_b32_e32 v3, 1
	v_add_u32_e32 v2, v14, v2
	v_ashrrev_i16_sdwa v1, v3, sext(v1) dst_sel:DWORD dst_unused:UNUSED_PAD src0_sel:DWORD src1_sel:BYTE_0
	v_lshlrev_b32_e32 v4, 5, v13
	v_bfe_i32 v15, v1, 0, 16
	v_lshlrev_b32_e32 v1, 1, v2
	v_lshlrev_b32_e32 v5, 2, v2
	v_lshrrev_b32_e32 v6, 2, v2
	v_and_b32_e32 v7, 3, v14
	v_and_b32_e32 v4, 32, v4
	v_and_b32_e32 v1, 0xfffc0, v1
	v_and_b32_e32 v6, 4, v6
	v_and_or_b32 v5, v5, 48, v7
	v_or3_b32 v1, v5, v1, v6
	v_add_lshl_u32 v4, v4, v15, 1
	v_add_u32_e32 v0, 0x2000, v0
	v_lshl_add_u32 v146, v1, 12, v4
	v_ashrrev_i32_e32 v1, 31, v0
	v_lshrrev_b32_e32 v1, 22, v1
	v_add_u32_e32 v1, v0, v1
	v_ashrrev_i32_e32 v16, 10, v1
	v_mul_i32_i24_e32 v1, 0x400, v16
	v_sub_u32_e32 v0, v0, v1
	v_lshrrev_b32_e32 v1, 4, v0
	v_bitop3_b32 v0, v1, v0, 32 bitop3:0x6c
	v_lshl_add_u32 v144, v2, 12, v4
	v_ashrrev_i32_e32 v2, 31, v0
	v_lshrrev_b32_e32 v2, 26, v2
	s_waitcnt lgkmcnt(0)
	s_add_u32 s67, s18, 0x4000000
	v_add_u32_e32 v2, v0, v2
	s_addc_u32 s68, s19, 0
	s_ashr_i32 s6, s66, 6
	v_lshlrev_b32_e32 v1, 3, v16
	v_ashrrev_i32_e32 v17, 6, v2
	v_and_b32_e32 v2, 0xc0, v2
	s_ashr_i32 s59, s58, 31
	s_ashr_i32 s57, s56, 31
	v_and_b32_e32 v1, -16, v1
	v_sub_u32_e32 v0, v0, v2
	s_ashr_i32 s7, s66, 8
	s_lshl_b32 s69, s6, 10
	s_lshl_b64 s[8:9], s[58:59], 20
	s_lshl_b64 s[36:37], s[56:57], 20
	v_add_u32_e32 v1, v17, v1
	v_ashrrev_i16_sdwa v0, v3, sext(v0) dst_sel:DWORD dst_unused:UNUSED_PAD src0_sel:DWORD src1_sel:BYTE_0
	s_add_u32 s62, s67, s36
	v_lshlrev_b32_e32 v4, 5, v16
	v_bfe_i32 v18, v0, 0, 16
	v_lshlrev_b32_e32 v0, 1, v1
	v_lshlrev_b32_e32 v2, 2, v1
	v_lshrrev_b32_e32 v3, 2, v1
	v_and_b32_e32 v5, 3, v17
	s_addc_u32 s63, s68, s37
	s_add_i32 s59, s69, 0
	v_and_b32_e32 v4, 32, v4
	v_and_b32_e32 v0, 0xfffc0, v0
	v_and_b32_e32 v3, 4, v3
	v_and_or_b32 v2, v2, 48, v5
	s_add_i32 m0, s59, 0x10000
	v_or3_b32 v0, v2, v0, v3
	v_add_lshl_u32 v2, v4, v18, 1
	global_load_lds_dwordx4 v146, s[62:63]
	s_add_i32 m0, s59, 0x12000
	v_lshl_add_u32 v152, v0, 12, v2
	s_add_u32 s60, s16, s8
	global_load_lds_dwordx4 v152, s[62:63]
	s_addc_u32 s61, s17, s9
	s_mov_b32 m0, s59
	s_add_i32 s70, s59, 0x2000
	v_lshl_add_u32 v150, v1, 12, v2
	global_load_lds_dwordx4 v144, s[60:61]
	s_mov_b32 m0, s70
	v_add_u32_e32 v148, 0x8000, v146
	global_load_lds_dwordx4 v150, s[60:61]
	s_add_i32 m0, s59, 0x14000
	v_add_u32_e32 v154, 0x8000, v152
	global_load_lds_dwordx4 v148, s[62:63]
	s_add_i32 m0, s59, 0x16000
	s_add_u32 s8, s60, 0x80000
	s_addc_u32 s9, s61, 0
	s_add_i32 s71, s59, 0x4000
	global_load_lds_dwordx4 v154, s[62:63]
	s_mov_b32 m0, s71
	s_add_i32 s72, s59, 0x6000
	global_load_lds_dwordx4 v144, s[8:9]
	s_mov_b32 m0, s72
	v_mov_b32_e32 v147, 0
	global_load_lds_dwordx4 v150, s[8:9]
	v_mov_b32_e32 v153, v147
	v_mov_b32_e32 v145, v147
	v_mov_b32_e32 v151, v147
	v_mov_b32_e32 v149, v147
	v_mov_b32_e32 v155, v147
	s_mov_b32 s73, 0
	v_lshl_add_u64 v[10:11], s[62:63], 0, v[146:147]
	v_lshl_add_u64 v[8:9], s[62:63], 0, v[152:153]
	v_lshl_add_u64 v[6:7], s[60:61], 0, v[144:145]
	v_lshl_add_u64 v[4:5], s[60:61], 0, v[150:151]
	v_lshl_add_u64 v[0:1], s[62:63], 0, v[148:149]
	s_cmp_lg_u32 s7, 1
	v_lshl_add_u64 v[2:3], s[62:63], 0, v[154:155]
	s_setprio 1
	s_cbranch_scc1 .LBB0_872
	s_barrier
.LBB0_872:
	s_add_u32 s36, s18, 0x6400000
	s_addc_u32 s37, s19, 0
	s_add_u32 s38, s18, 0xa400000
	s_addc_u32 s39, s19, 0
	s_add_u32 s40, s18, 0x1ec30000
	s_addc_u32 s41, s19, 0
	s_add_u32 s18, s18, 0x1ec20000
	s_mov_b64 s[42:43], 0x80
	s_addc_u32 s19, s19, 0
	s_add_i32 m0, s59, 0x18000
	v_lshl_add_u64 v[10:11], v[10:11], 0, s[42:43]
	s_waitcnt vmcnt(4)
	s_barrier
	global_load_lds_dwordx4 v[10:11], off
	v_lshl_add_u64 v[8:9], v[8:9], 0, s[42:43]
	s_add_i32 m0, s59, 0x1a000
	s_add_i32 s74, s59, 0x8000
	global_load_lds_dwordx4 v[8:9], off
	v_lshl_add_u64 v[6:7], v[6:7], 0, s[42:43]
	s_mov_b32 m0, s74
	s_add_i32 s75, s59, 0xa000
	global_load_lds_dwordx4 v[6:7], off
	v_lshl_add_u64 v[4:5], v[4:5], 0, s[42:43]
	s_mov_b32 m0, s75
	v_lshl_add_u64 v[0:1], v[0:1], 0, s[42:43]
	global_load_lds_dwordx4 v[4:5], off
	s_add_i32 m0, s59, 0x1c000
	s_and_b32 s33, s6, 3
	global_load_lds_dwordx4 v[0:1], off
	v_lshl_add_u64 v[0:1], v[2:3], 0, s[42:43]
	s_add_i32 m0, s59, 0x1e000
	v_and_b32_e32 v172, 15, v12
	global_load_lds_dwordx4 v[0:1], off
	v_bfe_u32 v0, v12, 4, 2
	v_lshlrev_b32_e32 v1, 4, v0
	v_cmp_eq_u32_e64 s[8:9], 0, v0
	v_lshlrev_b32_e32 v0, 15, v13
	v_and_b32_e32 v0, 0xffff0000, v0
	v_lshl_or_b32 v2, v172, 6, v1
	v_lshl_or_b32 v176, s33, 6, v1
	v_lshl_add_u32 v0, v14, 12, v0
	v_and_b32_e32 v1, 1, v13
	v_lshl_or_b32 v0, v1, 6, v0
	v_lshlrev_b32_e32 v3, 2, v12
	v_lshl_add_u32 v156, v15, 1, v0
	v_lshlrev_b32_e32 v0, 15, v16
	s_lshl_b32 s6, s7, 13
	v_and_b32_e32 v3, 32, v3
	v_and_b32_e32 v0, 0xffff0000, v0
	v_bitop3_b32 v4, v2, s6, v3 bitop3:0xde
	s_lshl_b32 s6, s33, 12
	s_waitcnt vmcnt(6)
	v_lshl_add_u32 v0, v17, 12, v0
	v_and_b32_e32 v1, 1, v16
	v_bitop3_b32 v173, v2, s6, v3 bitop3:0xde
	v_lshl_or_b32 v0, v1, 6, v0
	s_add_i32 s81, 0, 0x10000
	s_add_i32 s82, 0, 0x14000
	s_lshl_b32 s77, s7, 6
	v_cmp_gt_u32_e64 s[6:7], 8, v172
	v_and_b32_e32 v174, 7, v12
	v_and_b32_e32 v175, 8, v12
	s_ashr_i32 s78, s20, 31
	s_mov_b32 s79, s20
	s_ashr_i32 s80, s2, 31
	v_mov_b32_e32 v157, v147
	v_lshl_add_u32 v158, v18, 1, v0
	v_mov_b32_e32 v159, v147
	v_add_u32_e32 v177, s81, v173
	v_add_u32_e32 v178, 0, v4
	v_add_u32_e32 v179, s82, v173
	v_mov_b32_e32 v180, 0x358637bd
	s_mov_b64 s[44:45], 0x8000
	v_mov_b64_e32 v[160:161], 0x1ff
	s_barrier
	s_branch .LBB0_874

;     __device__ bool next(int i, Unit& u) const {
;         if (i >= icnt) return false;
;         const long L = (long)(i + ioff) * G + c; if (L >= nwg) return false;
; template <class Epi>
; __device__ __forceinline__ void gemm_phase(LAS unsigned char* lds, const Gemm g, const StaticOrder& S, const Epi& E) {
;     int tid = threadIdx.x; asm volatile("" : "+v"(tid));
;     const int wid = __builtin_amdgcn_readfirstlane(tid >> 6), lane = tid & 63, wr = wid >> 2, wc = wid & 3, fr = lane & 15, fq = lane >> 4;
;     const int K = g.K, nt = K / BK;
;     unsigned voffA[2], voffB0[2], voffB1[2];
; #pragma unroll
;     for (int i = 0; i < 2; ++i) { int R, C; stage_rc(tid * 16 + i * 8192, R, C);
;         const int Rw = 64 * (R >> 5) + 16 * ((R >> 2) & 3) + 4 * ((R >> 4) & 1) + (R & 3);
;         const int Rf = 64 * (R >> 5) + 8 * ((R >> 2) & 3) + 4 * ((R >> 4) & 1) + (R & 3);
;         const int Rb0 = Epi::PERM ? (Epi::F32OUT ? Rf : Rw) : R, Rb1 = Epi::PERM ? (Epi::F32OUT ? Rf + 32 : Rw + 8) : R + HALF;
;         voffA[i] = (unsigned)(R * K + C) * 2u; voffB0[i] = (unsigned)(Rb0 * K + C) * 2u; voffB1[i] = (unsigned)(Rb1 * K + C) * 2u; }
;     const size_t kstep = (size_t)(BK * 2);
;     const size_t hstep = (size_t)HALF * K * 2;
;     const size_t tstep = 2 * hstep;
;     const unsigned ldsw = (unsigned)wid * 1024u;
;     const int aoff = lds_byte(wr * 64 + fr, fq * 8), boff = lds_byte(wc * 32 + fr, fq * 8);
;     ...
;     Unit cur, nxt; int ui = 0;
;     if (!S.next(0, cur)) return;
;     f32x4 acc[2][2][4][2];
; #pragma unroll
;     for (int a = 0; a < 2; ++a)
; #pragma unroll
;         for (int b = 0; b < 2; ++b)
; #pragma unroll
;             for (int m = 0; m < 4; ++m)
; #pragma unroll
;                 for (int n = 0; n < 2; ++n) acc[a][b][m][n] = (f32x4){0.f, 0.f, 0.f, 0.f};
;     bf16x8 At[4][2], B0[2][2], B1[2][2];
;     const char* cA = (const char*)g.A + (size_t)cur.pm * tstep; const char* cB = (const char*)g.Bt + (size_t)cur.pn * tstep;
;     PG8_STAGE(PG8_SB(0, 0), cB, voffB0); PG8_STAGE(PG8_SA(0, 0), cA, voffA); PG8_STAGE(PG8_SB(0, 1), cB, voffB1); PG8_STAGE(PG8_SA(0, 1), cA + hstep, voffA);
;     if (wr == 1) PG8_BAR;
;     PG8_WAIT_V(4); PG8_BAR;
;     PG8_STAGE(PG8_SB(1, 0), cB + kstep, voffB0); PG8_STAGE(PG8_SA(1, 0), cA + kstep, voffA); PG8_STAGE(PG8_SB(1, 1), cB + kstep, voffB1);
;     PG8_WAIT_V(6); PG8_BAR;
.LBB0_954:
	s_or_b64 exec, exec, s[6:7]
	s_mov_b64 s[6:7], s[0:1]
	s_waitcnt lgkmcnt(0)
	v_mov_b32_e32 v0, v202
	s_mov_b32 s8, s2
	v_mov_b32_e32 v12, v202
	s_barrier
	s_cmpk_gt_i32 s2, 0x2ff
	v_readfirstlane_b32 s52, v12
	s_cbranch_scc1 .LBB0_967
	v_lshlrev_b32_e32 v0, 4, v12
	v_add_u32_e32 v1, 0x2000, v0
	v_ashrrev_i32_e32 v2, 31, v1
	v_lshrrev_b32_e32 v2, 22, v2
	v_add_u32_e32 v2, v1, v2
	v_ashrrev_i32_e32 v13, 10, v2
	v_mul_i32_i24_e32 v2, 0x400, v13
	v_sub_u32_e32 v1, v1, v2
	v_lshrrev_b32_e32 v2, 4, v1
	v_bitop3_b32 v1, v2, v1, 32 bitop3:0x6c
	v_ashrrev_i32_e32 v2, 31, v1
	v_lshrrev_b32_e32 v2, 26, v2
	v_add_u32_e32 v2, v1, v2
	v_lshlrev_b32_e32 v3, 3, v13
	v_ashrrev_i32_e32 v14, 6, v2
	v_and_b32_e32 v3, -16, v3
	v_add_u32_e32 v3, v14, v3
	s_load_dwordx2 s[6:7], s[6:7], 0xf0
	v_lshlrev_b32_e32 v4, 2, v3
	v_and_b32_e32 v5, 3, v14
	v_and_or_b32 v4, v4, 48, v5
	v_lshlrev_b32_e32 v5, 1, v3
	v_lshrrev_b32_e32 v6, 2, v3
	v_and_b32_e32 v2, 0xc0, v2
	v_and_b32_e32 v5, 0xfffc0, v5
	v_and_b32_e32 v6, 4, v6
	v_sub_u32_e32 v1, v1, v2
	v_mov_b32_e32 v2, 1
	v_or3_b32 v4, v4, v5, v6
	v_lshlrev_b32_e32 v5, 5, v13
	v_ashrrev_i16_sdwa v1, v2, sext(v1) dst_sel:DWORD dst_unused:UNUSED_PAD src0_sel:DWORD src1_sel:BYTE_0
	v_and_b32_e32 v5, 32, v5
	v_bfe_i32 v15, v1, 0, 16
	s_waitcnt lgkmcnt(0)
	s_add_u32 s53, s6, 0x6400000
	v_add_lshl_u32 v1, v5, v15, 1
	s_addc_u32 s54, s7, 0
	v_lshl_add_u32 v128, v4, 12, v1
	v_lshl_add_u32 v132, v3, 12, v1
	v_bfe_i32 v1, v12, 27, 1
	s_add_u32 s55, s6, 0x4900000
	v_lshrrev_b32_e32 v1, 22, v1
	s_addc_u32 s56, s7, 0
	v_add_u32_e32 v1, v0, v1
	s_ashr_i32 s58, s2, 31
	v_and_b32_e32 v1, 0xfffffc00, v1
	s_lshr_b32 s8, s58, 29
	v_sub_u32_e32 v0, v0, v1
	s_add_i32 s8, s2, s8
	v_lshrrev_b32_e32 v1, 4, v0
	v_ashrrev_i32_e32 v3, 31, v12
	s_ashr_i32 s9, s8, 3
	s_and_b32 s8, s8, -8
	v_bitop3_b32 v0, v1, v0, 32 bitop3:0x6c
	v_lshrrev_b32_e32 v3, 26, v3
	s_sub_i32 s8, s2, s8
	v_ashrrev_i32_e32 v1, 31, v0
	v_add_u32_e32 v3, v12, v3
	s_lshr_b32 s10, s8, 31
	v_lshrrev_b32_e32 v1, 26, v1
	v_ashrrev_i32_e32 v17, 6, v3
	s_or_b32 s10, s10, 0x60
	v_add_u32_e32 v1, v0, v1
	v_lshlrev_b32_e32 v3, 3, v17
	s_mul_i32 s8, s10, s8
	v_ashrrev_i32_e32 v16, 6, v1
	v_and_b32_e32 v3, -16, v3
	s_add_i32 s8, s8, s9
	v_add_u32_e32 v3, v16, v3
	s_mul_hi_i32 s9, s8, 0x2aaaaaab
	v_lshlrev_b32_e32 v4, 2, v3
	v_and_b32_e32 v5, 3, v16
	s_lshr_b32 s10, s9, 31
	s_ashr_i32 s9, s9, 4
	v_and_or_b32 v4, v4, 48, v5
	v_lshlrev_b32_e32 v5, 1, v3
	v_lshrrev_b32_e32 v6, 2, v3
	v_and_b32_e32 v1, 0xc0, v1
	s_add_i32 s9, s9, s10
	v_and_b32_e32 v5, 0xfffc0, v5
	v_and_b32_e32 v6, 4, v6
	v_sub_u32_e32 v0, v0, v1
	s_lshl_b32 s10, s9, 3
	v_or3_b32 v4, v4, v5, v6
	v_lshlrev_b32_e32 v5, 5, v17
	v_ashrrev_i16_sdwa v0, v2, sext(v0) dst_sel:DWORD dst_unused:UNUSED_PAD src0_sel:DWORD src1_sel:BYTE_0
	s_sub_i32 s11, 64, s10
	s_mulk_i32 s9, 0x60
	v_and_b32_e32 v5, 32, v5
	v_bfe_i32 v18, v0, 0, 16
	s_min_u32 s11, s11, 8
	s_sub_i32 s16, s8, s9
	v_add_lshl_u32 v0, v5, v18, 1
	s_sext_i32_i8 s8, s16
	v_cvt_f32_ubyte0_e32 v2, s11
	v_lshl_add_u32 v134, v4, 12, v0
	v_cvt_f32_i32_e32 v1, s8
	v_rcp_iflag_f32_e32 v4, v2
	v_lshl_add_u32 v138, v3, 12, v0
	s_ashr_i32 s36, s52, 6
	s_ashr_i32 s8, s8, 30
	v_mul_f32_e32 v0, v1, v4
	v_trunc_f32_e32 v0, v0
	v_fma_f32 v1, -v0, v2, v1
	v_cvt_i32_f32_e32 v0, v0
	s_ashr_i32 s19, s52, 8
	s_lshl_b32 s57, s36, 10
	s_or_b32 s17, s8, 1
	v_cmp_ge_f32_e64 s[8:9], |v1|, v2
	s_and_b64 s[8:9], s[8:9], exec
	s_cselect_b32 s8, s17, 0
	v_readfirstlane_b32 s9, v0
	s_add_i32 s18, s9, s8
	s_mul_i32 s8, s18, s11
	s_sub_i32 s8, s16, s8
	s_sext_i32_i8 s8, s8
	s_add_i32 s44, s10, s8
	s_ashr_i32 s45, s44, 31
	s_bfe_i64 s[10:11], s[18:19], 0x80000
	s_lshl_b64 s[8:9], s[44:45], 20
	s_lshl_b64 s[10:11], s[10:11], 20
	s_add_u32 s48, s55, s10
	s_addc_u32 s49, s56, s11
	s_add_i32 s45, s57, 0
	s_add_i32 m0, s45, 0x10000
	v_add_u32_e32 v136, 0x8000, v134
	global_load_lds_dwordx4 v134, s[48:49]
	s_add_i32 m0, s45, 0x12000
	s_add_u32 s46, s53, s8
	global_load_lds_dwordx4 v128, s[48:49]
	s_addc_u32 s47, s54, s9
	s_mov_b32 m0, s45
	s_add_i32 s59, s45, 0x2000
	global_load_lds_dwordx4 v138, s[46:47]
	s_mov_b32 m0, s59
	v_add_u32_e32 v130, 0x8000, v128
	global_load_lds_dwordx4 v132, s[46:47]
	s_add_i32 m0, s45, 0x14000
	v_mov_b32_e32 v135, 0
	global_load_lds_dwordx4 v136, s[48:49]
	s_add_i32 m0, s45, 0x16000
	s_add_u32 s8, s46, 0x80000
	s_addc_u32 s9, s47, 0
	s_add_i32 s60, s45, 0x4000
	global_load_lds_dwordx4 v130, s[48:49]
	s_mov_b32 m0, s60
	s_add_i32 s61, s45, 0x6000
	global_load_lds_dwordx4 v138, s[8:9]
	s_mov_b32 m0, s61
	v_mov_b32_e32 v129, v135
	global_load_lds_dwordx4 v132, s[8:9]
	v_mov_b32_e32 v139, v135
	v_mov_b32_e32 v133, v135
	v_mov_b32_e32 v137, v135
	v_mov_b32_e32 v131, v135
	s_mov_b32 s62, 0
	v_lshl_add_u64 v[10:11], s[48:49], 0, v[134:135]
	v_lshl_add_u64 v[8:9], s[48:49], 0, v[128:129]
	v_lshl_add_u64 v[6:7], s[46:47], 0, v[138:139]
	v_lshl_add_u64 v[4:5], s[46:47], 0, v[132:133]
	v_lshl_add_u64 v[0:1], s[48:49], 0, v[136:137]
	s_cmp_lg_u32 s19, 1
	v_lshl_add_u64 v[2:3], s[48:49], 0, v[130:131]
	s_setprio 1
	s_cbranch_scc1 .LBB0_957
	s_barrier
; #define PG8_STAGE(bufoff, gbase, voff) do { _Pragma("unroll") for (int _i = 0; _i < 2; ++_i) \
;         __builtin_amdgcn_global_load_lds((const unsigned*)((const char*)(gbase) + (voff)[_i]), (LAS unsigned*)(lds + (bufoff) + ldsw + _i * 8192), 16, 0, 0); } while (0)
; #define PG8_WAIT_V(n) asm volatile("s_waitcnt vmcnt(" #n ")" ::: "memory")
; #define PG8_BAR __builtin_amdgcn_s_barrier()
; template <class Epi>
; __device__ __forceinline__ void gemm_phase(LAS unsigned char* lds, const Gemm g, const StaticOrder& S, const Epi& E) {
;     ...
;     const unsigned ldsw = (unsigned)wid * 1024u;
;     const int aoff = lds_byte(wr * 64 + fr, fq * 8), boff = lds_byte(wc * 32 + fr, fq * 8);
;     ...
;     PG8_WAIT_V(4); PG8_BAR;
;     PG8_STAGE(PG8_SB(1, 0), cB + kstep, voffB0); PG8_STAGE(PG8_SA(1, 0), cA + kstep, voffA); PG8_STAGE(PG8_SB(1, 1), cB + kstep, voffB1);
;     PG8_WAIT_V(6); PG8_BAR;
.LBB0_957:
	s_add_u32 s8, s6, 0xec00000
	s_addc_u32 s9, s7, 0
	s_add_u32 s10, s6, 0x1ec20000
	s_mov_b64 s[16:17], 0x80
	s_addc_u32 s11, s7, 0
	s_add_i32 m0, s45, 0x18000
	v_lshl_add_u64 v[10:11], v[10:11], 0, s[16:17]
	s_waitcnt vmcnt(4)
	s_barrier
	global_load_lds_dwordx4 v[10:11], off
	v_lshl_add_u64 v[8:9], v[8:9], 0, s[16:17]
	s_add_i32 m0, s45, 0x1a000
	s_add_i32 s63, s45, 0x8000
	global_load_lds_dwordx4 v[8:9], off
	v_lshl_add_u64 v[6:7], v[6:7], 0, s[16:17]
	s_mov_b32 m0, s63
	s_add_i32 s64, s45, 0xa000
	global_load_lds_dwordx4 v[6:7], off
	v_lshl_add_u64 v[4:5], v[4:5], 0, s[16:17]
	s_mov_b32 m0, s64
	v_lshl_add_u64 v[0:1], v[0:1], 0, s[16:17]
	global_load_lds_dwordx4 v[4:5], off
	s_add_i32 m0, s45, 0x1c000
	v_and_b32_e32 v154, 15, v12
	global_load_lds_dwordx4 v[0:1], off
	v_lshl_add_u64 v[0:1], v[2:3], 0, s[16:17]
	s_add_i32 m0, s45, 0x1e000
	v_lshlrev_b32_e32 v2, 2, v12
	global_load_lds_dwordx4 v[0:1], off
	v_and_b32_e32 v0, 48, v12
	s_and_b32 s6, s36, 3
	s_lshl_b32 s7, s19, 13
	v_lshl_or_b32 v1, v154, 6, v0
	v_and_b32_e32 v2, 32, v2
	v_bitop3_b32 v3, v1, s7, v2 bitop3:0xde
	s_lshl_b32 s7, s6, 12
	s_sext_i32_i8 s71, s18
	v_bitop3_b32 v155, v1, s7, v2 bitop3:0xde
	s_lshl_b32 s18, s6, 6
	v_and_b32_e32 v1, 8, v12
	v_or3_b32 v157, s18, v1, v0
	v_lshlrev_b32_e32 v0, 15, v17
	v_and_b32_e32 v0, 0xffff0000, v0
	v_lshl_add_u32 v0, v16, 12, v0
	v_and_b32_e32 v1, 1, v17
	v_lshl_or_b32 v0, v1, 6, v0
	v_lshl_add_u32 v140, v18, 1, v0
	v_lshlrev_b32_e32 v0, 15, v13
	v_and_b32_e32 v0, 0xffff0000, v0
	s_waitcnt vmcnt(6)
	v_lshl_add_u32 v0, v14, 12, v0
	v_and_b32_e32 v1, 1, v13
	v_lshl_or_b32 v0, v1, 6, v0
	s_add_i32 s68, 0, 0x10000
	s_add_i32 s69, 0, 0x14000
	s_lshl_b32 s65, s19, 6
	v_cmp_gt_u32_e64 s[6:7], 8, v154
	v_and_b32_e32 v156, 7, v12
	s_ashr_i32 s66, s20, 31
	s_mov_b32 s67, s20
	v_mov_b32_e32 v141, v135
	v_lshl_add_u32 v142, v15, 1, v0
	v_mov_b32_e32 v143, v135
	v_add_u32_e32 v158, s68, v155
	v_add_u32_e32 v159, 0, v3
	v_add_u32_e32 v160, s69, v155
	v_mov_b32_e32 v161, 0x358637bd
	s_movk_i32 s70, 0x1800
	v_mov_b64_e32 v[144:145], 0x2ff
	s_barrier

; #define PG8_WAIT_V(n) asm volatile("s_waitcnt vmcnt(" #n ")" ::: "memory")
; #define PG8_BAR __builtin_amdgcn_s_barrier()
; template <class Epi>
; __device__ __forceinline__ void gemm_phase(LAS unsigned char* lds, const Gemm g, const StaticOrder& S, const Epi& E) {
;     int tid = threadIdx.x; asm volatile("" : "+v"(tid));
;     const int wid = __builtin_amdgcn_readfirstlane(tid >> 6), lane = tid & 63, wr = wid >> 2, wc = wid & 3, fr = lane & 15, fq = lane >> 4;
;     const int K = g.K, nt = K / BK;
;     unsigned voffA[2], voffB0[2], voffB1[2];
; #pragma unroll
;     for (int i = 0; i < 2; ++i) { int R, C; stage_rc(tid * 16 + i * 8192, R, C);
;         const int Rw = 64 * (R >> 5) + 16 * ((R >> 2) & 3) + 4 * ((R >> 4) & 1) + (R & 3);
;         const int Rf = 64 * (R >> 5) + 8 * ((R >> 2) & 3) + 4 * ((R >> 4) & 1) + (R & 3);
;         const int Rb0 = Epi::PERM ? (Epi::F32OUT ? Rf : Rw) : R, Rb1 = Epi::PERM ? (Epi::F32OUT ? Rf + 32 : Rw + 8) : R + HALF;
;         voffA[i] = (unsigned)(R * K + C) * 2u; voffB0[i] = (unsigned)(Rb0 * K + C) * 2u; voffB1[i] = (unsigned)(Rb1 * K + C) * 2u; }
;     const size_t kstep = (size_t)(BK * 2);
;     const size_t hstep = (size_t)HALF * K * 2;
;     const size_t tstep = 2 * hstep;
;     const unsigned ldsw = (unsigned)wid * 1024u;
;     const int aoff = lds_byte(wr * 64 + fr, fq * 8), boff = lds_byte(wc * 32 + fr, fq * 8);
;     ...
;     Unit cur, nxt; int ui = 0;
;     if (!S.next(0, cur)) return;
;     f32x4 acc[2][2][4][2];
; #pragma unroll
;     for (int a = 0; a < 2; ++a)
; #pragma unroll
;         for (int b = 0; b < 2; ++b)
; #pragma unroll
;             for (int m = 0; m < 4; ++m)
; #pragma unroll
;                 for (int n = 0; n < 2; ++n) acc[a][b][m][n] = (f32x4){0.f, 0.f, 0.f, 0.f};
;     bf16x8 At[4][2], B0[2][2], B1[2][2];
;     const char* cA = (const char*)g.A + (size_t)cur.pm * tstep; const char* cB = (const char*)g.Bt + (size_t)cur.pn * tstep;
;     PG8_STAGE(PG8_SB(0, 0), cB, voffB0); PG8_STAGE(PG8_SA(0, 0), cA, voffA); PG8_STAGE(PG8_SB(0, 1), cB, voffB1); PG8_STAGE(PG8_SA(0, 1), cA + hstep, voffA);
;     if (wr == 1) PG8_BAR;
;     PG8_WAIT_V(4); PG8_BAR;
;     PG8_STAGE(PG8_SB(1, 0), cB + kstep, voffB0); PG8_STAGE(PG8_SA(1, 0), cA + kstep, voffA); PG8_STAGE(PG8_SB(1, 1), cB + kstep, voffB1);
;     PG8_WAIT_V(6); PG8_BAR;
.LBB0_1232:
	s_load_dwordx4 s[16:19], s[6:7], 0xe8
	s_and_b64 vcc, exec, s[4:5]
	s_cbranch_vccnz .LBB0_1265
	v_ashrrev_i32_e32 v1, 31, v12
	v_lshrrev_b32_e32 v1, 26, v1
	v_add_u32_e32 v1, v12, v1
	v_ashrrev_i32_e32 v13, 6, v1
	v_bfe_i32 v1, v12, 27, 1
	v_lshlrev_b32_e32 v0, 4, v12
	v_lshrrev_b32_e32 v1, 22, v1
	v_add_u32_e32 v1, v0, v1
	v_and_b32_e32 v1, 0xfffffc00, v1
	v_sub_u32_e32 v1, v0, v1
	v_lshrrev_b32_e32 v2, 4, v1
	v_bitop3_b32 v2, v2, v1, 32 bitop3:0x6c
	v_ashrrev_i32_e32 v1, 31, v1
	v_lshrrev_b32_e32 v1, 26, v1
	v_add_u32_e32 v1, v2, v1
	v_ashrrev_i32_e32 v14, 6, v1
	v_lshlrev_b32_e32 v3, 3, v13
	v_mul_i32_i24_e32 v4, 64, v14
	v_and_b32_e32 v3, -16, v3
	v_sub_u32_e32 v2, v2, v4
	v_mov_b32_e32 v4, 1
	v_add_u32_e32 v1, v14, v3
	v_lshlrev_b32_e32 v3, 5, v13
	v_ashrrev_i16_sdwa v2, v4, sext(v2) dst_sel:DWORD dst_unused:UNUSED_PAD src0_sel:DWORD src1_sel:BYTE_0
	v_and_b32_e32 v3, 32, v3
	v_bfe_i32 v15, v2, 0, 16
	v_add_lshl_u32 v3, v3, v15, 1
	v_add_u32_e32 v0, 0x2000, v0
	v_lshlrev_b32_e32 v2, 1, v1
	v_lshlrev_b32_e32 v5, 2, v1
	v_lshrrev_b32_e32 v6, 2, v1
	v_lshl_add_u32 v128, v1, 12, v3
	v_ashrrev_i32_e32 v1, 31, v0
	v_lshrrev_b32_e32 v1, 22, v1
	v_add_u32_e32 v1, v0, v1
	s_waitcnt vmcnt(1)
	v_ashrrev_i32_e32 v16, 10, v1
	v_mul_i32_i24_e32 v1, 0x400, v16
	v_and_b32_e32 v7, 3, v14
	v_sub_u32_e32 v0, v0, v1
	v_and_b32_e32 v2, 0xfffc0, v2
	v_and_b32_e32 v6, 4, v6
	v_and_or_b32 v5, v5, 48, v7
	v_lshrrev_b32_e32 v1, 4, v0
	v_or3_b32 v2, v5, v2, v6
	v_bitop3_b32 v0, v1, v0, 32 bitop3:0x6c
	s_waitcnt lgkmcnt(0)
	s_add_u32 s53, s18, 0x1ac00000
	v_lshl_add_u32 v130, v2, 12, v3
	v_ashrrev_i32_e32 v2, 31, v0
	s_addc_u32 s54, s19, 0
	v_lshrrev_b32_e32 v2, 26, v2
	s_add_u32 s55, s18, 0x5500000
	v_add_u32_e32 v2, v0, v2
	s_addc_u32 s56, s19, 0
	s_ashr_i32 s6, s52, 6
	v_lshlrev_b32_e32 v1, 3, v16
	v_ashrrev_i32_e32 v17, 6, v2
	v_and_b32_e32 v2, 0xc0, v2
	s_ashr_i32 s45, s44, 31
	s_ashr_i32 s43, s42, 31
	v_and_b32_e32 v1, -16, v1
	v_sub_u32_e32 v0, v0, v2
	s_ashr_i32 s7, s52, 8
	s_lshl_b32 s57, s6, 10
	s_lshl_b64 s[8:9], s[44:45], 20
	s_lshl_b64 s[10:11], s[42:43], 20
	v_add_u32_e32 v1, v17, v1
	v_ashrrev_i16_sdwa v0, v4, sext(v0) dst_sel:DWORD dst_unused:UNUSED_PAD src0_sel:DWORD src1_sel:BYTE_0
	s_add_u32 s48, s55, s10
	v_lshlrev_b32_e32 v3, 5, v16
	v_bfe_i32 v18, v0, 0, 16
	v_lshlrev_b32_e32 v0, 1, v1
	v_lshlrev_b32_e32 v2, 2, v1
	v_lshrrev_b32_e32 v4, 2, v1
	v_and_b32_e32 v5, 3, v17
	s_addc_u32 s49, s56, s11
	s_add_i32 s45, s57, 0
	v_and_b32_e32 v3, 32, v3
	v_and_b32_e32 v0, 0xfffc0, v0
	v_and_b32_e32 v4, 4, v4
	v_and_or_b32 v2, v2, 48, v5
	s_add_i32 m0, s45, 0x10000
	v_or3_b32 v0, v2, v0, v4
	v_add_lshl_u32 v2, v3, v18, 1
	global_load_lds_dwordx4 v130, s[48:49]
	s_add_i32 m0, s45, 0x12000
	v_lshl_add_u32 v136, v0, 12, v2
	s_add_u32 s46, s53, s8
	global_load_lds_dwordx4 v136, s[48:49]
	s_addc_u32 s47, s54, s9
	s_mov_b32 m0, s45
	s_add_i32 s58, s45, 0x2000
	v_lshl_add_u32 v134, v1, 12, v2
	global_load_lds_dwordx4 v128, s[46:47]
	s_mov_b32 m0, s58
	v_add_u32_e32 v132, 0x8000, v130
	global_load_lds_dwordx4 v134, s[46:47]
	s_add_i32 m0, s45, 0x14000
	v_add_u32_e32 v138, 0x8000, v136
	global_load_lds_dwordx4 v132, s[48:49]
	s_add_i32 m0, s45, 0x16000
	s_add_u32 s8, s46, 0x80000
	s_addc_u32 s9, s47, 0
	s_add_i32 s59, s45, 0x4000
	global_load_lds_dwordx4 v138, s[48:49]
	s_mov_b32 m0, s59
	s_add_i32 s60, s45, 0x6000
	global_load_lds_dwordx4 v128, s[8:9]
	s_mov_b32 m0, s60
	v_mov_b32_e32 v131, 0
	global_load_lds_dwordx4 v134, s[8:9]
	v_mov_b32_e32 v137, v131
	v_mov_b32_e32 v129, v131
	v_mov_b32_e32 v135, v131
	v_mov_b32_e32 v133, v131
	v_mov_b32_e32 v139, v131
	s_mov_b32 s61, 0
	v_lshl_add_u64 v[10:11], s[48:49], 0, v[130:131]
	v_lshl_add_u64 v[8:9], s[48:49], 0, v[136:137]
	v_lshl_add_u64 v[6:7], s[46:47], 0, v[128:129]
	v_lshl_add_u64 v[4:5], s[46:47], 0, v[134:135]
	v_lshl_add_u64 v[0:1], s[48:49], 0, v[132:133]
	s_cmp_lg_u32 s7, 1
	v_lshl_add_u64 v[2:3], s[48:49], 0, v[138:139]
	s_setprio 1
	s_cbranch_scc1 .LBB0_1235
	s_barrier
.LBB0_1235:
	s_add_u32 s10, s18, 0x6400000
	s_addc_u32 s11, s19, 0
	s_add_u32 s18, s18, 0x1ec10000
	s_mov_b64 s[26:27], 0x80
	s_addc_u32 s19, s19, 0
	s_add_i32 m0, s45, 0x18000
	v_lshl_add_u64 v[10:11], v[10:11], 0, s[26:27]
	s_waitcnt vmcnt(4)
	s_barrier
	global_load_lds_dwordx4 v[10:11], off
	v_lshl_add_u64 v[8:9], v[8:9], 0, s[26:27]
	s_add_i32 m0, s45, 0x1a000
	s_add_i32 s62, s45, 0x8000
	global_load_lds_dwordx4 v[8:9], off
	v_lshl_add_u64 v[6:7], v[6:7], 0, s[26:27]
	s_mov_b32 m0, s62
	s_add_i32 s63, s45, 0xa000
	global_load_lds_dwordx4 v[6:7], off
	v_lshl_add_u64 v[4:5], v[4:5], 0, s[26:27]
	s_mov_b32 m0, s63
	v_lshl_add_u64 v[0:1], v[0:1], 0, s[26:27]
	global_load_lds_dwordx4 v[4:5], off
	s_add_i32 m0, s45, 0x1c000
	v_and_b32_e32 v150, 15, v12
	global_load_lds_dwordx4 v[0:1], off
	v_lshl_add_u64 v[0:1], v[2:3], 0, s[26:27]
	s_add_i32 m0, s45, 0x1e000
	v_lshlrev_b32_e32 v3, 2, v12
	global_load_lds_dwordx4 v[0:1], off
	v_bfe_u32 v0, v12, 4, 2
	v_lshlrev_b32_e32 v1, 4, v0
	s_and_b32 s6, s6, 3
	s_lshl_b32 s64, s7, 6
	v_lshl_or_b32 v2, v150, 6, v1
	s_lshl_b32 s7, s7, 13
	v_and_b32_e32 v3, 32, v3
	v_bitop3_b32 v4, v2, s7, v3 bitop3:0xde
	s_lshl_b32 s7, s6, 12
	v_cmp_eq_u32_e64 s[8:9], 0, v0
	v_lshlrev_b32_e32 v0, 15, v13
	v_bitop3_b32 v151, v2, s7, v3 bitop3:0xde
	s_lshl_b32 s28, s6, 6
	v_and_b32_e32 v2, 8, v12
	v_and_b32_e32 v0, 0xffff0000, v0
	v_or3_b32 v153, s28, v2, v1
	v_lshl_add_u32 v0, v14, 12, v0
	v_and_b32_e32 v1, 1, v13
	v_lshl_or_b32 v0, v1, 6, v0
	v_lshl_add_u32 v140, v15, 1, v0
	v_lshlrev_b32_e32 v0, 15, v16
	v_and_b32_e32 v0, 0xffff0000, v0
	s_waitcnt vmcnt(6)
	v_lshl_add_u32 v0, v17, 12, v0
	v_and_b32_e32 v1, 1, v16
	v_lshl_or_b32 v0, v1, 6, v0
	s_add_i32 s68, 0, 0x10000
	s_add_i32 s69, 0, 0x14000
	v_cmp_gt_u32_e64 s[6:7], 8, v150
	v_and_b32_e32 v152, 7, v12
	s_ashr_i32 s65, s20, 31
	s_mov_b32 s66, s20
	s_ashr_i32 s67, s2, 31
	v_mov_b32_e32 v141, v131
	v_lshl_add_u32 v142, v18, 1, v0
	v_mov_b32_e32 v143, v131
	v_add_u32_e32 v154, s68, v151
	v_add_u32_e32 v155, 0, v4
	v_add_u32_e32 v156, s69, v151
	s_mov_b64 s[28:29], 0x8000
	v_mov_b64_e32 v[144:145], 0x1ff
	s_barrier
	s_branch .LBB0_1237

; #define PG8_WAIT_V(n) asm volatile("s_waitcnt vmcnt(" #n ")" ::: "memory")
; #define PG8_BAR __builtin_amdgcn_s_barrier()
; template <class Epi>
; __device__ __forceinline__ void gemm_phase(LAS unsigned char* lds, const Gemm g, const StaticOrder& S, const Epi& E) {
;     int tid = threadIdx.x; asm volatile("" : "+v"(tid));
;     const int wid = __builtin_amdgcn_readfirstlane(tid >> 6), lane = tid & 63, wr = wid >> 2, wc = wid & 3, fr = lane & 15, fq = lane >> 4;
;     const int K = g.K, nt = K / BK;
;     unsigned voffA[2], voffB0[2], voffB1[2];
; #pragma unroll
;     for (int i = 0; i < 2; ++i) { int R, C; stage_rc(tid * 16 + i * 8192, R, C);
;         const int Rw = 64 * (R >> 5) + 16 * ((R >> 2) & 3) + 4 * ((R >> 4) & 1) + (R & 3);
;         const int Rf = 64 * (R >> 5) + 8 * ((R >> 2) & 3) + 4 * ((R >> 4) & 1) + (R & 3);
;         const int Rb0 = Epi::PERM ? (Epi::F32OUT ? Rf : Rw) : R, Rb1 = Epi::PERM ? (Epi::F32OUT ? Rf + 32 : Rw + 8) : R + HALF;
;         voffA[i] = (unsigned)(R * K + C) * 2u; voffB0[i] = (unsigned)(Rb0 * K + C) * 2u; voffB1[i] = (unsigned)(Rb1 * K + C) * 2u; }
;     const size_t kstep = (size_t)(BK * 2);
;     const size_t hstep = (size_t)HALF * K * 2;
;     const size_t tstep = 2 * hstep;
;     const unsigned ldsw = (unsigned)wid * 1024u;
;     const int aoff = lds_byte(wr * 64 + fr, fq * 8), boff = lds_byte(wc * 32 + fr, fq * 8);
;     ...
;     Unit cur, nxt; int ui = 0;
;     if (!S.next(0, cur)) return;
;     f32x4 acc[2][2][4][2];
; #pragma unroll
;     for (int a = 0; a < 2; ++a)
; #pragma unroll
;         for (int b = 0; b < 2; ++b)
; #pragma unroll
;             for (int m = 0; m < 4; ++m)
; #pragma unroll
;                 for (int n = 0; n < 2; ++n) acc[a][b][m][n] = (f32x4){0.f, 0.f, 0.f, 0.f};
;     bf16x8 At[4][2], B0[2][2], B1[2][2];
;     const char* cA = (const char*)g.A + (size_t)cur.pm * tstep; const char* cB = (const char*)g.Bt + (size_t)cur.pn * tstep;
;     PG8_STAGE(PG8_SB(0, 0), cB, voffB0); PG8_STAGE(PG8_SA(0, 0), cA, voffA); PG8_STAGE(PG8_SB(0, 1), cB, voffB1); PG8_STAGE(PG8_SA(0, 1), cA + hstep, voffA);
;     if (wr == 1) PG8_BAR;
;     PG8_WAIT_V(4); PG8_BAR;
;     PG8_STAGE(PG8_SB(1, 0), cB + kstep, voffB0); PG8_STAGE(PG8_SA(1, 0), cA + kstep, voffA); PG8_STAGE(PG8_SB(1, 1), cB + kstep, voffB1);
;     PG8_WAIT_V(6); PG8_BAR;
.LBB0_1267:
	s_and_b64 vcc, exec, s[4:5]
	s_cbranch_vccnz .LBB0_1297
	v_bfe_i32 v2, v12, 27, 1
	v_lshlrev_b32_e32 v0, 4, v12
	v_lshrrev_b32_e32 v2, 22, v2
	v_add_u32_e32 v2, v0, v2
	v_and_b32_e32 v2, 0xfffffc00, v2
	v_sub_u32_e32 v2, v0, v2
	v_ashrrev_i32_e32 v1, 31, v12
	v_lshrrev_b32_e32 v3, 4, v2
	v_lshrrev_b32_e32 v1, 26, v1
	v_bitop3_b32 v2, v3, v2, 32 bitop3:0x6c
	v_add_u32_e32 v1, v12, v1
	v_ashrrev_i32_e32 v4, 31, v2
	v_ashrrev_i32_e32 v1, 6, v1
	v_lshrrev_b32_e32 v4, 26, v4
	v_lshlrev_b32_e32 v3, 3, v1
	v_add_u32_e32 v4, v2, v4
	v_and_b32_e32 v3, -16, v3
	v_ashrrev_i32_e32 v5, 6, v4
	v_and_b32_e32 v4, 0xc0, v4
	v_add_u32_e32 v3, v5, v3
	v_sub_u32_e32 v2, v2, v4
	v_mov_b32_e32 v4, 1
	v_lshlrev_b32_e32 v1, 5, v1
	v_ashrrev_i16_sdwa v2, v4, sext(v2) dst_sel:DWORD dst_unused:UNUSED_PAD src0_sel:DWORD src1_sel:BYTE_0
	v_lshlrev_b32_e32 v6, 1, v3
	v_lshlrev_b32_e32 v7, 2, v3
	v_lshrrev_b32_e32 v8, 2, v3
	v_and_b32_e32 v5, 3, v5
	v_and_b32_e32 v1, 32, v1
	v_bfe_i32 v2, v2, 0, 16
	v_and_b32_e32 v6, 0x7fffc0, v6
	v_and_b32_e32 v8, 4, v8
	v_and_or_b32 v5, v7, 48, v5
	v_or3_b32 v5, v5, v6, v8
	v_add_lshl_u32 v1, v1, v2, 1
	v_add_u32_e32 v0, 0x2000, v0
	v_lshl_add_u32 v128, v3, 9, v1
	v_lshl_add_u32 v130, v5, 9, v1
	v_ashrrev_i32_e32 v1, 31, v0
	v_lshrrev_b32_e32 v1, 22, v1
	s_load_dwordx2 s[6:7], s[6:7], 0xf0
	v_add_u32_e32 v1, v0, v1
	v_ashrrev_i32_e32 v1, 10, v1
	v_mul_i32_i24_e32 v2, 0x400, v1
	v_sub_u32_e32 v0, v0, v2
	v_lshrrev_b32_e32 v2, 4, v0
	s_waitcnt lgkmcnt(0)
	s_add_u32 s55, s6, 0x1f800000
	v_bitop3_b32 v0, v2, v0, 32 bitop3:0x6c
	s_addc_u32 s56, s7, 0
	v_ashrrev_i32_e32 v3, 31, v0
	s_add_u32 s57, s6, 0x4800000
	v_lshrrev_b32_e32 v3, 26, v3
	s_addc_u32 s58, s7, 0
	s_ashr_i32 s8, s54, 6
	v_lshlrev_b32_e32 v2, 3, v1
	v_add_u32_e32 v3, v0, v3
	s_ashr_i32 s41, s40, 31
	s_ashr_i32 s39, s38, 31
	v_and_b32_e32 v2, -16, v2
	v_ashrrev_i32_e32 v5, 6, v3
	v_and_b32_e32 v3, 0xc0, v3
	s_ashr_i32 s9, s54, 8
	s_lshl_b32 s59, s8, 10
	s_lshl_b64 s[10:11], s[40:41], 17
	s_lshl_b64 s[16:17], s[38:39], 17
	v_add_u32_e32 v2, v5, v2
	v_sub_u32_e32 v0, v0, v3
	s_add_u32 s42, s57, s16
	v_lshlrev_b32_e32 v1, 5, v1
	v_ashrrev_i16_sdwa v0, v4, sext(v0) dst_sel:DWORD dst_unused:UNUSED_PAD src0_sel:DWORD src1_sel:BYTE_0
	v_lshlrev_b32_e32 v3, 1, v2
	v_lshlrev_b32_e32 v4, 2, v2
	v_lshrrev_b32_e32 v6, 2, v2
	v_and_b32_e32 v5, 3, v5
	s_addc_u32 s43, s58, s17
	s_add_i32 s41, s59, 0
	v_and_b32_e32 v1, 32, v1
	v_bfe_i32 v0, v0, 0, 16
	v_and_b32_e32 v3, 0x7fffc0, v3
	v_and_b32_e32 v6, 4, v6
	v_and_or_b32 v4, v4, 48, v5
	s_add_i32 m0, s41, 0x10000
	v_or3_b32 v3, v4, v3, v6
	v_add_lshl_u32 v0, v1, v0, 1
	global_load_lds_dwordx4 v130, s[42:43]
	s_add_i32 m0, s41, 0x12000
	v_lshl_add_u32 v136, v3, 9, v0
	s_add_u32 s44, s55, s10
	global_load_lds_dwordx4 v136, s[42:43]
	s_addc_u32 s45, s56, s11
	s_mov_b32 m0, s41
	s_add_i32 s60, s41, 0x2000
	v_lshl_add_u32 v134, v2, 9, v0
	global_load_lds_dwordx4 v128, s[44:45]
	s_mov_b32 m0, s60
	v_add_u32_e32 v132, 0x1000, v130
	global_load_lds_dwordx4 v134, s[44:45]
	s_add_i32 m0, s41, 0x14000
	v_add_u32_e32 v138, 0x1000, v136
	global_load_lds_dwordx4 v132, s[42:43]
	s_add_i32 m0, s41, 0x16000
	s_add_u32 s10, s44, 0x10000
	s_addc_u32 s11, s45, 0
	s_add_i32 s61, s41, 0x4000
	global_load_lds_dwordx4 v138, s[42:43]
	s_mov_b32 m0, s61
	s_add_i32 s62, s41, 0x6000
	global_load_lds_dwordx4 v128, s[10:11]
	s_mov_b32 m0, s62
	v_mov_b32_e32 v131, 0
	global_load_lds_dwordx4 v134, s[10:11]
	v_mov_b32_e32 v137, v131
	v_mov_b32_e32 v129, v131
	v_mov_b32_e32 v135, v131
	v_mov_b32_e32 v133, v131
	v_mov_b32_e32 v139, v131
	s_mov_b32 s63, 0
	v_lshl_add_u64 v[10:11], s[42:43], 0, v[130:131]
	v_lshl_add_u64 v[8:9], s[42:43], 0, v[136:137]
	v_lshl_add_u64 v[6:7], s[44:45], 0, v[128:129]
	v_lshl_add_u64 v[4:5], s[44:45], 0, v[134:135]
	v_lshl_add_u64 v[0:1], s[42:43], 0, v[132:133]
	s_cmp_lg_u32 s9, 1
	v_lshl_add_u64 v[2:3], s[42:43], 0, v[138:139]
	s_setprio 1
	s_cbranch_scc1 .LBB0_1270
	s_barrier
.LBB0_1270:
	s_add_u32 s10, s6, 0xa400000
	s_addc_u32 s11, s7, 0
	s_add_u32 s16, s6, 0x1ec40000
	s_mov_b64 s[18:19], 0x80
	s_addc_u32 s17, s7, 0
	s_add_i32 m0, s41, 0x18000
	v_lshl_add_u64 v[10:11], v[10:11], 0, s[18:19]
	s_waitcnt vmcnt(4)
	s_barrier
	global_load_lds_dwordx4 v[10:11], off
	v_lshl_add_u64 v[8:9], v[8:9], 0, s[18:19]
	s_add_i32 m0, s41, 0x1a000
	s_add_i32 s64, s41, 0x8000
	global_load_lds_dwordx4 v[8:9], off
	v_lshl_add_u64 v[6:7], v[6:7], 0, s[18:19]
	s_mov_b32 m0, s64
	s_add_i32 s65, s41, 0xa000
	global_load_lds_dwordx4 v[6:7], off
	v_lshl_add_u64 v[4:5], v[4:5], 0, s[18:19]
	s_mov_b32 m0, s65
	v_lshl_add_u64 v[0:1], v[0:1], 0, s[18:19]
	global_load_lds_dwordx4 v[4:5], off
	s_add_i32 m0, s41, 0x1c000
	v_and_b32_e32 v146, 15, v12
	global_load_lds_dwordx4 v[0:1], off
	v_lshl_add_u64 v[0:1], v[2:3], 0, s[18:19]
	s_add_i32 m0, s41, 0x1e000
	v_lshlrev_b32_e32 v3, 2, v12
	global_load_lds_dwordx4 v[0:1], off
	v_bfe_u32 v0, v12, 4, 2
	v_lshlrev_b32_e32 v1, 4, v0
	s_and_b32 s6, s8, 3
	v_lshl_or_b32 v2, v146, 6, v1
	s_lshl_b32 s7, s9, 13
	v_and_b32_e32 v3, 32, v3
	v_bitop3_b32 v4, v2, s7, v3 bitop3:0xde
	s_lshl_b32 s7, s6, 12
	s_waitcnt vmcnt(6)
	v_bitop3_b32 v147, v2, s7, v3 bitop3:0xde
	s_lshl_b32 s26, s6, 6
	v_and_b32_e32 v2, 8, v12
	s_add_i32 s71, 0, 0x10000
	s_add_i32 s72, 0, 0x14000
	s_lshl_b32 s66, s9, 6
	s_mov_b32 s67, 0x8000
	v_cmp_gt_u32_e64 s[6:7], 8, v146
	v_and_b32_e32 v148, 7, v12
	v_cmp_eq_u32_e64 s[8:9], 0, v0
	s_ashr_i32 s68, s20, 31
	s_mov_b32 s69, s20
	s_ashr_i32 s70, s2, 31
	v_or3_b32 v149, s26, v2, v1
	v_add_u32_e32 v150, s71, v147
	v_add_u32_e32 v151, 0, v4
	v_add_u32_e32 v152, s72, v147
	v_mov_b64_e32 v[140:141], 0x1ff
	s_barrier
	s_waitcnt vmcnt(0)
	s_branch .LBB0_1272

; #define PG8_WAIT_V(n) asm volatile("s_waitcnt vmcnt(" #n ")" ::: "memory")
; #define PG8_BAR __builtin_amdgcn_s_barrier()
; template <class Epi>
; __device__ __forceinline__ void gemm_phase(LAS unsigned char* lds, const Gemm g, const StaticOrder& S, const Epi& E) {
;     int tid = threadIdx.x; asm volatile("" : "+v"(tid));
;     const int wid = __builtin_amdgcn_readfirstlane(tid >> 6), lane = tid & 63, wr = wid >> 2, wc = wid & 3, fr = lane & 15, fq = lane >> 4;
;     const int K = g.K, nt = K / BK;
;     unsigned voffA[2], voffB0[2], voffB1[2];
; #pragma unroll
;     for (int i = 0; i < 2; ++i) { int R, C; stage_rc(tid * 16 + i * 8192, R, C);
;         const int Rw = 64 * (R >> 5) + 16 * ((R >> 2) & 3) + 4 * ((R >> 4) & 1) + (R & 3);
;         const int Rf = 64 * (R >> 5) + 8 * ((R >> 2) & 3) + 4 * ((R >> 4) & 1) + (R & 3);
;         const int Rb0 = Epi::PERM ? (Epi::F32OUT ? Rf : Rw) : R, Rb1 = Epi::PERM ? (Epi::F32OUT ? Rf + 32 : Rw + 8) : R + HALF;
;         voffA[i] = (unsigned)(R * K + C) * 2u; voffB0[i] = (unsigned)(Rb0 * K + C) * 2u; voffB1[i] = (unsigned)(Rb1 * K + C) * 2u; }
;     const size_t kstep = (size_t)(BK * 2);
;     const size_t hstep = (size_t)HALF * K * 2;
;     const size_t tstep = 2 * hstep;
;     const unsigned ldsw = (unsigned)wid * 1024u;
;     const int aoff = lds_byte(wr * 64 + fr, fq * 8), boff = lds_byte(wc * 32 + fr, fq * 8);
;     ...
;     Unit cur, nxt; int ui = 0;
;     if (!S.next(0, cur)) return;
;     f32x4 acc[2][2][4][2];
; #pragma unroll
;     for (int a = 0; a < 2; ++a)
; #pragma unroll
;         for (int b = 0; b < 2; ++b)
; #pragma unroll
;             for (int m = 0; m < 4; ++m)
; #pragma unroll
;                 for (int n = 0; n < 2; ++n) acc[a][b][m][n] = (f32x4){0.f, 0.f, 0.f, 0.f};
;     bf16x8 At[4][2], B0[2][2], B1[2][2];
;     const char* cA = (const char*)g.A + (size_t)cur.pm * tstep; const char* cB = (const char*)g.Bt + (size_t)cur.pn * tstep;
;     PG8_STAGE(PG8_SB(0, 0), cB, voffB0); PG8_STAGE(PG8_SA(0, 0), cA, voffA); PG8_STAGE(PG8_SB(0, 1), cB, voffB1); PG8_STAGE(PG8_SA(0, 1), cA + hstep, voffA);
;     if (wr == 1) PG8_BAR;
;     PG8_WAIT_V(4); PG8_BAR;
;     PG8_STAGE(PG8_SB(1, 0), cB + kstep, voffB0); PG8_STAGE(PG8_SA(1, 0), cA + kstep, voffA); PG8_STAGE(PG8_SB(1, 1), cB + kstep, voffB1);
;     PG8_WAIT_V(6); PG8_BAR;
.LBB0_1354:
	v_ashrrev_i32_e32 v1, 31, v12
	v_lshrrev_b32_e32 v1, 26, v1
	v_add_u32_e32 v1, v12, v1
	v_ashrrev_i32_e32 v13, 6, v1
	v_bfe_i32 v1, v12, 27, 1
	v_lshlrev_b32_e32 v0, 4, v12
	v_lshrrev_b32_e32 v1, 22, v1
	v_add_u32_e32 v1, v0, v1
	v_and_b32_e32 v1, 0xfffffc00, v1
	v_sub_u32_e32 v1, v0, v1
	v_lshrrev_b32_e32 v2, 4, v1
	v_bitop3_b32 v1, v2, v1, 32 bitop3:0x6c
	v_ashrrev_i32_e32 v3, 31, v1
	v_lshrrev_b32_e32 v3, 26, v3
	v_add_u32_e32 v3, v1, v3
	v_lshlrev_b32_e32 v2, 3, v13
	v_ashrrev_i32_e32 v14, 6, v3
	v_and_b32_e32 v3, 0xc0, v3
	v_and_b32_e32 v2, -16, v2
	v_sub_u32_e32 v1, v1, v3
	v_mov_b32_e32 v3, 1
	v_add_u32_e32 v2, v14, v2
	v_ashrrev_i16_sdwa v1, v3, sext(v1) dst_sel:DWORD dst_unused:UNUSED_PAD src0_sel:DWORD src1_sel:BYTE_0
	s_ashr_i32 s6, s17, 3
	v_lshlrev_b32_e32 v4, 5, v13
	v_bfe_i32 v15, v1, 0, 16
	v_lshlrev_b32_e32 v1, 1, v2
	v_lshlrev_b32_e32 v5, 2, v2
	v_lshrrev_b32_e32 v6, 2, v2
	v_and_b32_e32 v7, 3, v14
	v_and_b32_e32 v4, 32, v4
	v_and_b32_e32 v1, 0xfffc0, v1
	v_and_b32_e32 v6, 4, v6
	v_and_or_b32 v5, v5, 48, v7
	s_add_i32 s6, s16, s6
	v_or3_b32 v1, v5, v1, v6
	v_add_lshl_u32 v4, v4, v15, 1
	v_add_u32_e32 v0, 0x2000, v0
	s_ashr_i32 s12, s6, 31
	v_lshl_add_u32 v130, v1, 12, v4
	v_ashrrev_i32_e32 v1, 31, v0
	s_lshr_b32 s12, s12, 24
	v_lshrrev_b32_e32 v1, 22, v1
	s_add_i32 s12, s6, s12
	v_add_u32_e32 v1, v0, v1
	s_ashr_i32 s13, s12, 8
	s_and_b32 s12, s12, 0xffffff00
	v_ashrrev_i32_e32 v16, 10, v1
	s_sub_i32 s12, s6, s12
	v_mul_i32_i24_e32 v1, 0x400, v16
	s_sext_i32_i16 s6, s12
	v_sub_u32_e32 v0, v0, v1
	s_bfe_u32 s6, s6, 0x3001c
	v_lshrrev_b32_e32 v1, 4, v0
	s_add_i32 s16, s12, s6
	v_bitop3_b32 v0, v1, v0, 32 bitop3:0x6c
	s_sext_i32_i16 s6, s16
	s_and_b32 s16, s16, 0xfff8
	v_lshl_add_u32 v128, v2, 12, v4
	v_ashrrev_i32_e32 v2, 31, v0
	s_sub_i32 s12, s12, s16
	v_lshrrev_b32_e32 v2, 26, v2
	s_lshl_b32 s13, s13, 3
	s_sext_i32_i16 s12, s12
	s_ashr_i32 s7, s44, 6
	v_add_u32_e32 v2, v0, v2
	s_lshr_b32 s6, s6, 3
	s_add_i32 s36, s13, s12
	v_lshlrev_b32_e32 v1, 3, v16
	v_ashrrev_i32_e32 v17, 6, v2
	v_and_b32_e32 v2, 0xc0, v2
	s_ashr_i32 s37, s36, 31
	s_bfe_i64 s[16:17], s[6:7], 0x100000
	v_and_b32_e32 v1, -16, v1
	v_sub_u32_e32 v0, v0, v2
	s_ashr_i32 s18, s44, 8
	s_lshl_b32 s46, s7, 10
	s_lshl_b64 s[12:13], s[36:37], 20
	s_lshl_b64 s[16:17], s[16:17], 20
	v_add_u32_e32 v1, v17, v1
	v_ashrrev_i16_sdwa v0, v3, sext(v0) dst_sel:DWORD dst_unused:UNUSED_PAD src0_sel:DWORD src1_sel:BYTE_0
	s_waitcnt lgkmcnt(0)
	s_add_u32 s40, s10, s16
	v_lshlrev_b32_e32 v4, 5, v16
	v_bfe_i32 v18, v0, 0, 16
	v_lshlrev_b32_e32 v0, 1, v1
	v_lshlrev_b32_e32 v2, 2, v1
	v_lshrrev_b32_e32 v3, 2, v1
	v_and_b32_e32 v5, 3, v17
	s_addc_u32 s41, s11, s17
	s_add_i32 s37, s46, 0
	v_and_b32_e32 v4, 32, v4
	v_and_b32_e32 v0, 0xfffc0, v0
	v_and_b32_e32 v3, 4, v3
	v_and_or_b32 v2, v2, 48, v5
	s_add_i32 m0, s37, 0x10000
	v_or3_b32 v0, v2, v0, v3
	v_add_lshl_u32 v2, v4, v18, 1
	global_load_lds_dwordx4 v130, s[40:41]
	s_add_i32 m0, s37, 0x12000
	v_lshl_add_u32 v136, v0, 12, v2
	s_add_u32 s38, s8, s12
	global_load_lds_dwordx4 v136, s[40:41]
	s_addc_u32 s39, s9, s13
	s_mov_b32 m0, s37
	s_add_i32 s47, s37, 0x2000
	v_lshl_add_u32 v134, v1, 12, v2
	global_load_lds_dwordx4 v128, s[38:39]
	s_mov_b32 m0, s47
	v_add_u32_e32 v132, 0x8000, v130
	global_load_lds_dwordx4 v134, s[38:39]
	s_add_i32 m0, s37, 0x14000
	v_add_u32_e32 v138, 0x8000, v136
	global_load_lds_dwordx4 v132, s[40:41]
	s_add_i32 m0, s37, 0x16000
	s_add_u32 s12, s38, 0x80000
	s_addc_u32 s13, s39, 0
	s_add_i32 s48, s37, 0x4000
	global_load_lds_dwordx4 v138, s[40:41]
	s_mov_b32 m0, s48
	s_add_i32 s49, s37, 0x6000
	global_load_lds_dwordx4 v128, s[12:13]
	s_mov_b32 m0, s49
	v_mov_b32_e32 v131, 0
	global_load_lds_dwordx4 v134, s[12:13]
	v_mov_b32_e32 v137, v131
	v_mov_b32_e32 v129, v131
	v_mov_b32_e32 v135, v131
	v_mov_b32_e32 v133, v131
	v_mov_b32_e32 v139, v131
	s_mov_b32 s50, 0
	v_lshl_add_u64 v[10:11], s[40:41], 0, v[130:131]
	v_lshl_add_u64 v[8:9], s[40:41], 0, v[136:137]
	v_lshl_add_u64 v[6:7], s[38:39], 0, v[128:129]
	v_lshl_add_u64 v[4:5], s[38:39], 0, v[134:135]
	v_lshl_add_u64 v[0:1], s[40:41], 0, v[132:133]
	s_cmp_lg_u32 s18, 1
	v_lshl_add_u64 v[2:3], s[40:41], 0, v[138:139]
	s_setprio 1
	s_cbranch_scc1 .LBB0_1356
	s_barrier
.LBB0_1356:
	s_add_u32 s12, s10, 0xec00000
	s_mov_b64 s[16:17], 0x80
	s_addc_u32 s13, s11, 0
	s_add_i32 m0, s37, 0x18000
	v_lshl_add_u64 v[10:11], v[10:11], 0, s[16:17]
	s_waitcnt vmcnt(4)
	s_barrier
	global_load_lds_dwordx4 v[10:11], off
	v_lshl_add_u64 v[8:9], v[8:9], 0, s[16:17]
	s_add_i32 m0, s37, 0x1a000
	s_add_i32 s51, s37, 0x8000
	global_load_lds_dwordx4 v[8:9], off
	v_lshl_add_u64 v[6:7], v[6:7], 0, s[16:17]
	s_mov_b32 m0, s51
	s_add_i32 s52, s37, 0xa000
	global_load_lds_dwordx4 v[6:7], off
	v_lshl_add_u64 v[4:5], v[4:5], 0, s[16:17]
	s_mov_b32 m0, s52
	v_lshl_add_u64 v[0:1], v[0:1], 0, s[16:17]
	global_load_lds_dwordx4 v[4:5], off
	s_add_i32 m0, s37, 0x1c000
	v_and_b32_e32 v146, 15, v12
	global_load_lds_dwordx4 v[0:1], off
	v_lshl_add_u64 v[0:1], v[2:3], 0, s[16:17]
	s_add_i32 m0, s37, 0x1e000
	v_lshlrev_b32_e32 v2, 2, v12
	global_load_lds_dwordx4 v[0:1], off
	v_and_b32_e32 v0, 48, v12
	s_sext_i32_i16 s59, s6
	s_and_b32 s6, s7, 3
	s_lshl_b32 s7, s18, 13
	v_lshl_or_b32 v1, v146, 6, v0
	v_and_b32_e32 v2, 32, v2
	v_bitop3_b32 v3, v1, s7, v2 bitop3:0xde
	s_lshl_b32 s7, s6, 12
	s_lshl_b32 s53, s18, 6
	v_bitop3_b32 v147, v1, s7, v2 bitop3:0xde
	s_lshl_b32 s18, s6, 6
	v_and_b32_e32 v1, 8, v12
	v_or3_b32 v156, s18, v1, v0
	v_lshlrev_b32_e32 v0, 15, v13
	v_and_b32_e32 v0, 0xffff0000, v0
	v_lshl_add_u32 v0, v14, 12, v0
	v_and_b32_e32 v1, 1, v13
	v_lshl_or_b32 v0, v1, 6, v0
	v_lshl_add_u32 v140, v15, 1, v0
	v_lshlrev_b32_e32 v0, 15, v16
	v_and_b32_e32 v0, 0xffff0000, v0
	s_waitcnt vmcnt(6)
	v_and_b32_e32 v148, 7, v12
	v_lshl_add_u32 v0, v17, 12, v0
	v_and_b32_e32 v1, 1, v16
	v_sub_u32_e32 v2, v148, v146
	v_lshl_or_b32 v0, v1, 6, v0
	s_add_i32 s56, 0, 0x10000
	s_add_i32 s57, 0, 0x14000
	v_cmp_gt_u32_e64 s[6:7], 8, v146
	s_ashr_i32 s54, s20, 31
	s_mov_b32 s55, s20
	v_add_u32_e32 v149, 16, v2
	v_add_u32_e32 v150, 32, v2
	v_add_u32_e32 v151, 48, v2
	v_add_u32_e32 v152, 0x80, v2
	v_add_u32_e32 v153, 0x90, v2
	v_add_u32_e32 v154, 0xa0, v2
	v_add_u32_e32 v155, 0xb0, v2
	v_mov_b32_e32 v141, v131
	v_lshl_add_u32 v142, v18, 1, v0
	v_mov_b32_e32 v143, v131
	v_add_u32_e32 v157, s56, v147
	v_add_u32_e32 v158, 0, v3
	v_add_u32_e32 v159, s57, v147
	s_mov_b32 s58, 0x20000
	v_mov_b64_e32 v[144:145], 0x7ff
	s_barrier

; template <class Epi>
; __device__ __forceinline__ void gemm_phase(LAS unsigned char* lds, const Gemm g, const StaticOrder& S, const Epi& E) {
;     int tid = threadIdx.x; asm volatile("" : "+v"(tid));
;     const int wid = __builtin_amdgcn_readfirstlane(tid >> 6), lane = tid & 63, wr = wid >> 2, wc = wid & 3, fr = lane & 15, fq = lane >> 4;
;     const int K = g.K, nt = K / BK;
;     unsigned voffA[2], voffB0[2], voffB1[2];
; #pragma unroll
;     for (int i = 0; i < 2; ++i) { int R, C; stage_rc(tid * 16 + i * 8192, R, C);
;         const int Rw = 64 * (R >> 5) + 16 * ((R >> 2) & 3) + 4 * ((R >> 4) & 1) + (R & 3);
;         const int Rf = 64 * (R >> 5) + 8 * ((R >> 2) & 3) + 4 * ((R >> 4) & 1) + (R & 3);
;         const int Rb0 = Epi::PERM ? (Epi::F32OUT ? Rf : Rw) : R, Rb1 = Epi::PERM ? (Epi::F32OUT ? Rf + 32 : Rw + 8) : R + HALF;
;         voffA[i] = (unsigned)(R * K + C) * 2u; voffB0[i] = (unsigned)(Rb0 * K + C) * 2u; voffB1[i] = (unsigned)(Rb1 * K + C) * 2u; }
;     const size_t kstep = (size_t)(BK * 2);
;     const size_t hstep = (size_t)HALF * K * 2;
;     const size_t tstep = 2 * hstep;
;     const unsigned ldsw = (unsigned)wid * 1024u;
;     const int aoff = lds_byte(wr * 64 + fr, fq * 8), boff = lds_byte(wc * 32 + fr, fq * 8);
;     ...
;     Unit cur, nxt; int ui = 0;
;     if (!S.next(0, cur)) return;
;     f32x4 acc[2][2][4][2];
; #pragma unroll
;     for (int a = 0; a < 2; ++a)
; #pragma unroll
;         for (int b = 0; b < 2; ++b)
; #pragma unroll
;             for (int m = 0; m < 4; ++m)
; #pragma unroll
;                 for (int n = 0; n < 2; ++n) acc[a][b][m][n] = (f32x4){0.f, 0.f, 0.f, 0.f};
;     bf16x8 At[4][2], B0[2][2], B1[2][2];
;     const char* cA = (const char*)g.A + (size_t)cur.pm * tstep; const char* cB = (const char*)g.Bt + (size_t)cur.pn * tstep;
;     PG8_STAGE(PG8_SB(0, 0), cB, voffB0); PG8_STAGE(PG8_SA(0, 0), cA, voffA); PG8_STAGE(PG8_SB(0, 1), cB, voffB1); PG8_STAGE(PG8_SA(0, 1), cA + hstep, voffA);
;     if (wr == 1) PG8_BAR;
;     PG8_WAIT_V(4); PG8_BAR;
;     PG8_STAGE(PG8_SB(1, 0), cB + kstep, voffB0); PG8_STAGE(PG8_SA(1, 0), cA + kstep, voffA); PG8_STAGE(PG8_SB(1, 1), cB + kstep, voffB1);
;     PG8_WAIT_V(6); PG8_BAR;
; __global__ void __launch_bounds__(NTHREADS, 2) fwd_megakernel(Params P) {
;     ...
;     if (PH(10)) { PHASE_VARS; pg8::EpiResidB Ep{H, nullptr, nullptr, (bf16_t*)X, nullptr, SS + 0 * M};
.LBB0_1428:
	s_load_dwordx4 s[16:19], s[6:7], 0xe8
	s_and_b64 vcc, exec, s[4:5]
	s_cbranch_vccnz .LBB0_1534
	v_ashrrev_i32_e32 v1, 31, v12
	v_lshrrev_b32_e32 v1, 26, v1
	v_add_u32_e32 v1, v12, v1
	v_ashrrev_i32_e32 v13, 6, v1
	v_bfe_i32 v1, v12, 27, 1
	v_lshlrev_b32_e32 v0, 4, v12
	v_lshrrev_b32_e32 v1, 22, v1
	v_add_u32_e32 v1, v0, v1
	v_and_b32_e32 v1, 0xfffffc00, v1
	v_sub_u32_e32 v1, v0, v1
	v_lshrrev_b32_e32 v2, 4, v1
	v_bitop3_b32 v1, v2, v1, 32 bitop3:0x6c
	v_ashrrev_i32_e32 v3, 31, v1
	v_lshrrev_b32_e32 v3, 26, v3
	v_add_u32_e32 v3, v1, v3
	v_lshlrev_b32_e32 v2, 3, v13
	v_ashrrev_i32_e32 v14, 6, v3
	v_and_b32_e32 v3, 0xc0, v3
	v_and_b32_e32 v2, -16, v2
	v_sub_u32_e32 v1, v1, v3
	v_mov_b32_e32 v3, 1
	v_add_u32_e32 v2, v14, v2
	v_ashrrev_i16_sdwa v1, v3, sext(v1) dst_sel:DWORD dst_unused:UNUSED_PAD src0_sel:DWORD src1_sel:BYTE_0
	v_lshlrev_b32_e32 v4, 5, v13
	v_bfe_i32 v15, v1, 0, 16
	v_lshlrev_b32_e32 v1, 1, v2
	v_lshlrev_b32_e32 v5, 2, v2
	v_lshrrev_b32_e32 v6, 2, v2
	v_and_b32_e32 v7, 3, v14
	v_and_b32_e32 v4, 32, v4
	v_and_b32_e32 v1, 0x3ffc0, v1
	v_and_b32_e32 v6, 4, v6
	v_and_or_b32 v5, v5, 48, v7
	v_or3_b32 v1, v5, v1, v6
	v_add_lshl_u32 v4, v4, v15, 1
	v_add_u32_e32 v0, 0x2000, v0
	v_lshl_add_u32 v138, v1, 14, v4
	v_ashrrev_i32_e32 v1, 31, v0
	v_lshrrev_b32_e32 v1, 22, v1
	v_add_u32_e32 v1, v0, v1
	v_ashrrev_i32_e32 v16, 10, v1
	v_mul_i32_i24_e32 v1, 0x400, v16
	v_sub_u32_e32 v0, v0, v1
	v_lshrrev_b32_e32 v1, 4, v0
	v_bitop3_b32 v0, v1, v0, 32 bitop3:0x6c
	s_waitcnt lgkmcnt(0)
	s_add_u32 s49, s18, 0xec00000
	v_lshl_add_u32 v136, v2, 14, v4
	v_ashrrev_i32_e32 v2, 31, v0
	s_addc_u32 s50, s19, 0
	v_lshrrev_b32_e32 v2, 26, v2
	s_add_u32 s51, s18, 0x2000000
	v_add_u32_e32 v2, v0, v2
	s_addc_u32 s52, s19, 0
	s_ashr_i32 s6, s48, 6
	v_lshlrev_b32_e32 v1, 3, v16
	v_ashrrev_i32_e32 v17, 6, v2
	v_and_b32_e32 v2, 0xc0, v2
	s_ashr_i32 s11, s10, 31
	s_ashr_i32 s9, s8, 31
	v_and_b32_e32 v1, -16, v1
	v_sub_u32_e32 v0, v0, v2
	s_ashr_i32 s7, s48, 8
	s_lshl_b32 s53, s6, 10
	s_lshl_b64 s[12:13], s[10:11], 22
	s_lshl_b64 s[26:27], s[8:9], 22
	v_add_u32_e32 v1, v17, v1
	v_ashrrev_i16_sdwa v0, v3, sext(v0) dst_sel:DWORD dst_unused:UNUSED_PAD src0_sel:DWORD src1_sel:BYTE_0
	s_add_u32 s44, s51, s26
	v_lshlrev_b32_e32 v4, 5, v16
	v_bfe_i32 v18, v0, 0, 16
	v_lshlrev_b32_e32 v0, 1, v1
	v_lshlrev_b32_e32 v2, 2, v1
	v_lshrrev_b32_e32 v3, 2, v1
	v_and_b32_e32 v5, 3, v17
	s_addc_u32 s45, s52, s27
	s_add_i32 s54, s53, 0
	v_and_b32_e32 v4, 32, v4
	v_and_b32_e32 v0, 0x3ffc0, v0
	v_and_b32_e32 v3, 4, v3
	v_and_or_b32 v2, v2, 48, v5
	s_add_i32 m0, s54, 0x10000
	v_or3_b32 v0, v2, v0, v3
	v_add_lshl_u32 v2, v4, v18, 1
	global_load_lds_dwordx4 v138, s[44:45]
	s_add_i32 m0, s54, 0x12000
	v_lshl_add_u32 v144, v0, 14, v2
	s_add_u32 s42, s49, s12
	global_load_lds_dwordx4 v144, s[44:45]
	s_addc_u32 s43, s50, s13
	s_mov_b32 m0, s54
	s_add_i32 s55, s54, 0x2000
	v_lshl_add_u32 v142, v1, 14, v2
	global_load_lds_dwordx4 v136, s[42:43]
	s_mov_b32 m0, s55
	v_add_u32_e32 v140, 0x20000, v138
	global_load_lds_dwordx4 v142, s[42:43]
	s_add_i32 m0, s54, 0x14000
	v_add_u32_e32 v146, 0x20000, v144
	global_load_lds_dwordx4 v140, s[44:45]
	s_add_i32 m0, s54, 0x16000
	s_add_u32 s12, s42, 0x200000
	s_addc_u32 s13, s43, 0
	s_add_i32 s56, s54, 0x4000
	global_load_lds_dwordx4 v146, s[44:45]
	s_mov_b32 m0, s56
	s_add_i32 s57, s54, 0x6000
	global_load_lds_dwordx4 v136, s[12:13]
	s_mov_b32 m0, s57
	v_mov_b32_e32 v139, 0
	global_load_lds_dwordx4 v142, s[12:13]
	v_mov_b32_e32 v145, v139
	v_mov_b32_e32 v137, v139
	v_mov_b32_e32 v143, v139
	v_mov_b32_e32 v141, v139
	v_mov_b32_e32 v147, v139
	s_movk_i32 s58, 0x2000
	s_mov_b32 s59, 0
	v_lshl_add_u64 v[10:11], s[44:45], 0, v[138:139]
	v_lshl_add_u64 v[8:9], s[44:45], 0, v[144:145]
	v_lshl_add_u64 v[6:7], s[42:43], 0, v[136:137]
	v_lshl_add_u64 v[4:5], s[42:43], 0, v[142:143]
	v_lshl_add_u64 v[0:1], s[44:45], 0, v[140:141]
	s_cmp_lg_u32 s7, 1
	v_lshl_add_u64 v[2:3], s[44:45], 0, v[146:147]
	s_setprio 1
	s_cbranch_scc1 .LBB0_1431
	s_barrier
.LBB0_1431:
	s_add_u32 s12, s18, 0x6400000
	s_addc_u32 s13, s19, 0
	s_add_u32 s18, s18, 0x1ec10000
	s_mov_b64 s[26:27], 0x80
	s_addc_u32 s19, s19, 0
	s_add_i32 m0, s54, 0x18000
	v_lshl_add_u64 v[10:11], v[10:11], 0, s[26:27]
	s_waitcnt vmcnt(4)
	s_barrier
	global_load_lds_dwordx4 v[10:11], off
	v_lshl_add_u64 v[8:9], v[8:9], 0, s[26:27]
	s_add_i32 m0, s54, 0x1a000
	s_add_i32 s60, s54, 0x8000
	global_load_lds_dwordx4 v[8:9], off
	v_lshl_add_u64 v[6:7], v[6:7], 0, s[26:27]
	s_mov_b32 m0, s60
	s_add_i32 s61, s54, 0xa000
	global_load_lds_dwordx4 v[6:7], off
	v_lshl_add_u64 v[4:5], v[4:5], 0, s[26:27]
	s_mov_b32 m0, s61
	v_lshl_add_u64 v[0:1], v[0:1], 0, s[26:27]
	global_load_lds_dwordx4 v[4:5], off
	s_add_i32 m0, s54, 0x1c000
	s_and_b32 s9, s6, 3
	global_load_lds_dwordx4 v[0:1], off
	v_lshl_add_u64 v[0:1], v[2:3], 0, s[26:27]
	s_add_i32 m0, s54, 0x1e000
	v_and_b32_e32 v174, 15, v12
	global_load_lds_dwordx4 v[0:1], off
	v_and_b32_e32 v0, 48, v12
	v_lshlrev_b32_e32 v2, 2, v12
	s_lshl_b32 s6, s7, 13
	v_lshl_or_b32 v1, v174, 6, v0
	v_and_b32_e32 v2, 32, v2
	v_lshl_or_b32 v178, s9, 6, v0
	v_lshlrev_b32_e32 v0, 17, v13
	v_bitop3_b32 v3, v1, s6, v2 bitop3:0xde
	s_lshl_b32 s6, s9, 12
	v_and_b32_e32 v0, 0xfffc0000, v0
	v_bitop3_b32 v175, v1, s6, v2 bitop3:0xde
	v_lshl_add_u32 v0, v14, 14, v0
	v_and_b32_e32 v1, 1, v13
	v_lshl_or_b32 v0, v1, 6, v0
	v_lshl_add_u32 v148, v15, 1, v0
	v_lshlrev_b32_e32 v0, 17, v16
	s_lshl_b32 s62, s7, 6
	s_ashr_i32 s63, s20, 31
	s_ashr_i32 s65, s2, 31
	v_and_b32_e32 v0, 0xfffc0000, v0
	s_waitcnt vmcnt(6)
	s_cmp_lg_u64 s[16:17], 0
	v_lshl_add_u32 v0, v17, 14, v0
	v_and_b32_e32 v1, 1, v16
	s_cselect_b64 s[28:29], -1, 0
	v_lshl_or_b32 v0, v1, 6, v0
	s_add_i32 s66, 0, 0x10000
	s_add_i32 s67, 0, 0x14000
	v_cmp_gt_u32_e64 s[6:7], 8, v174
	v_and_b32_e32 v176, 7, v12
	v_and_b32_e32 v177, 8, v12
	s_mov_b32 s64, s20
	v_mov_b32_e32 v149, v139
	v_lshl_add_u32 v150, v18, 1, v0
	v_mov_b32_e32 v151, v139
	v_add_u32_e32 v179, s66, v175
	v_add_u32_e32 v180, 0, v3
	v_add_u32_e32 v181, s67, v175
	v_mov_b32_e32 v182, 0x358637bd
	s_movk_i32 s68, 0x1f80
	s_movk_i32 s69, 0x1f70
	s_movk_i32 s70, 0x1f60
	s_movk_i32 s71, 0x1f50
	v_mov_b64_e32 v[152:153], 0x1ff
	v_bfrev_b32_e32 v183, 63
	s_barrier
	s_branch .LBB0_1434

; #define PG8_WAIT_V(n) asm volatile("s_waitcnt vmcnt(" #n ")" ::: "memory")
; #define PG8_BAR __builtin_amdgcn_s_barrier()
; template <class Epi>
; __device__ __forceinline__ void gemm_phase(LAS unsigned char* lds, const Gemm g, const StaticOrder& S, const Epi& E) {
;     int tid = threadIdx.x; asm volatile("" : "+v"(tid));
;     const int wid = __builtin_amdgcn_readfirstlane(tid >> 6), lane = tid & 63, wr = wid >> 2, wc = wid & 3, fr = lane & 15, fq = lane >> 4;
;     const int K = g.K, nt = K / BK;
;     unsigned voffA[2], voffB0[2], voffB1[2];
; #pragma unroll
;     for (int i = 0; i < 2; ++i) { int R, C; stage_rc(tid * 16 + i * 8192, R, C);
;         const int Rw = 64 * (R >> 5) + 16 * ((R >> 2) & 3) + 4 * ((R >> 4) & 1) + (R & 3);
;         const int Rf = 64 * (R >> 5) + 8 * ((R >> 2) & 3) + 4 * ((R >> 4) & 1) + (R & 3);
;         const int Rb0 = Epi::PERM ? (Epi::F32OUT ? Rf : Rw) : R, Rb1 = Epi::PERM ? (Epi::F32OUT ? Rf + 32 : Rw + 8) : R + HALF;
;         voffA[i] = (unsigned)(R * K + C) * 2u; voffB0[i] = (unsigned)(Rb0 * K + C) * 2u; voffB1[i] = (unsigned)(Rb1 * K + C) * 2u; }
;     const size_t kstep = (size_t)(BK * 2);
;     const size_t hstep = (size_t)HALF * K * 2;
;     const size_t tstep = 2 * hstep;
;     const unsigned ldsw = (unsigned)wid * 1024u;
;     const int aoff = lds_byte(wr * 64 + fr, fq * 8), boff = lds_byte(wc * 32 + fr, fq * 8);
;     ...
;     Unit cur, nxt; int ui = 0;
;     if (!S.next(0, cur)) return;
;     f32x4 acc[2][2][4][2];
; #pragma unroll
;     for (int a = 0; a < 2; ++a)
; #pragma unroll
;         for (int b = 0; b < 2; ++b)
; #pragma unroll
;             for (int m = 0; m < 4; ++m)
; #pragma unroll
;                 for (int n = 0; n < 2; ++n) acc[a][b][m][n] = (f32x4){0.f, 0.f, 0.f, 0.f};
;     bf16x8 At[4][2], B0[2][2], B1[2][2];
;     const char* cA = (const char*)g.A + (size_t)cur.pm * tstep; const char* cB = (const char*)g.Bt + (size_t)cur.pn * tstep;
;     PG8_STAGE(PG8_SB(0, 0), cB, voffB0); PG8_STAGE(PG8_SA(0, 0), cA, voffA); PG8_STAGE(PG8_SB(0, 1), cB, voffB1); PG8_STAGE(PG8_SA(0, 1), cA + hstep, voffA);
;     if (wr == 1) PG8_BAR;
;     PG8_WAIT_V(4); PG8_BAR;
;     PG8_STAGE(PG8_SB(1, 0), cB + kstep, voffB0); PG8_STAGE(PG8_SA(1, 0), cA + kstep, voffA); PG8_STAGE(PG8_SB(1, 1), cB + kstep, voffB1);
;     PG8_WAIT_V(6); PG8_BAR;
.LBB0_1592:
	v_ashrrev_i32_e32 v1, 31, v202
	v_lshrrev_b32_e32 v1, 26, v1
	v_add_u32_e32 v1, v202, v1
	v_ashrrev_i32_e32 v12, 6, v1
	v_bfe_i32 v1, v202, 27, 1
	v_lshlrev_b32_e32 v0, 4, v202
	v_lshrrev_b32_e32 v1, 22, v1
	v_add_u32_e32 v1, v0, v1
	v_and_b32_e32 v1, 0xfffffc00, v1
	v_sub_u32_e32 v1, v0, v1
	v_lshrrev_b32_e32 v2, 4, v1
	v_bitop3_b32 v1, v2, v1, 32 bitop3:0x6c
	v_ashrrev_i32_e32 v3, 31, v1
	v_lshrrev_b32_e32 v3, 26, v3
	v_add_u32_e32 v3, v1, v3
	v_lshlrev_b32_e32 v2, 3, v12
	v_ashrrev_i32_e32 v13, 6, v3
	v_and_b32_e32 v3, 0xc0, v3
	s_waitcnt lgkmcnt(0)
	s_add_u32 s8, s6, 0x6400000
	v_and_b32_e32 v2, -16, v2
	v_sub_u32_e32 v1, v1, v3
	v_mov_b32_e32 v3, 1
	s_addc_u32 s9, s7, 0
	v_add_u32_e32 v2, v13, v2
	v_ashrrev_i16_sdwa v1, v3, sext(v1) dst_sel:DWORD dst_unused:UNUSED_PAD src0_sel:DWORD src1_sel:BYTE_0
	s_add_u32 s33, s6, 0x1f000000
	v_lshlrev_b32_e32 v4, 5, v12
	v_bfe_i32 v14, v1, 0, 16
	v_lshlrev_b32_e32 v1, 1, v2
	v_lshrrev_b32_e32 v5, 2, v2
	s_addc_u32 s40, s7, 0
	v_and_b32_e32 v4, 32, v4
	v_and_b32_e32 v5, 4, v5
	v_and_b32_e32 v6, 3, v13
	v_and_b32_e32 v1, 0xfffd8, v1
	s_add_i32 s0, s10, s0
	v_or3_b32 v1, v6, v5, v1
	v_add_lshl_u32 v4, v4, v14, 1
	v_add_u32_e32 v0, 0x2000, v0
	s_ashr_i32 s10, s0, 31
	v_lshl_add_u32 v146, v1, 12, v4
	v_ashrrev_i32_e32 v1, 31, v0
	s_lshr_b32 s10, s10, 26
	v_lshrrev_b32_e32 v1, 22, v1
	s_add_i32 s10, s0, s10
	v_add_u32_e32 v1, v0, v1
	s_ashr_i32 s11, s10, 6
	s_and_b32 s10, s10, 0xffc0
	v_ashrrev_i32_e32 v15, 10, v1
	s_sub_i32 s10, s0, s10
	v_mul_i32_i24_e32 v1, 0x400, v15
	s_bfe_i32 s0, s10, 0x80000
	v_sub_u32_e32 v0, v0, v1
	s_bfe_u32 s0, s0, 0x3000c
	v_lshrrev_b32_e32 v1, 4, v0
	s_add_i32 s14, s10, s0
	v_bitop3_b32 v0, v1, v0, 32 bitop3:0x6c
	s_bfe_i32 s0, s14, 0x80000
	s_and_b32 s14, s14, 0xf8
	v_lshl_add_u32 v144, v2, 12, v4
	v_ashrrev_i32_e32 v2, 31, v0
	s_sub_i32 s10, s10, s14
	v_lshrrev_b32_e32 v2, 26, v2
	s_lshl_b32 s11, s11, 3
	s_sext_i32_i16 s0, s0
	s_sext_i32_i8 s10, s10
	s_ashr_i32 s1, s3, 6
	v_add_u32_e32 v2, v0, v2
	s_lshr_b32 s0, s0, 3
	s_add_i32 s30, s11, s10
	v_lshlrev_b32_e32 v1, 3, v15
	v_ashrrev_i32_e32 v16, 6, v2
	v_and_b32_e32 v2, 0xc0, v2
	s_ashr_i32 s31, s30, 31
	s_bfe_i64 s[14:15], s[0:1], 0x100000
	v_and_b32_e32 v1, -16, v1
	v_sub_u32_e32 v0, v0, v2
	s_ashr_i32 s16, s3, 8
	s_lshl_b32 s41, s1, 10
	s_lshl_b64 s[10:11], s[30:31], 20
	s_lshl_b64 s[14:15], s[14:15], 20
	v_add_u32_e32 v1, v16, v1
	v_ashrrev_i16_sdwa v0, v3, sext(v0) dst_sel:DWORD dst_unused:UNUSED_PAD src0_sel:DWORD src1_sel:BYTE_0
	s_add_u32 s36, s33, s14
	v_lshlrev_b32_e32 v4, 5, v15
	v_bfe_i32 v17, v0, 0, 16
	v_lshlrev_b32_e32 v0, 1, v1
	v_lshrrev_b32_e32 v2, 2, v1
	s_addc_u32 s37, s40, s15
	s_add_i32 s31, s41, 0
	v_and_b32_e32 v4, 32, v4
	v_and_b32_e32 v2, 4, v2
	v_and_b32_e32 v3, 3, v16
	v_and_b32_e32 v0, 0xfffd8, v0
	s_add_i32 m0, s31, 0x10000
	v_or3_b32 v0, v3, v2, v0
	v_add_lshl_u32 v2, v4, v17, 1
	global_load_lds_dwordx4 v146, s[36:37]
	s_add_i32 m0, s31, 0x12000
	v_lshl_add_u32 v152, v0, 12, v2
	s_add_u32 s34, s8, s10
	global_load_lds_dwordx4 v152, s[36:37]
	s_addc_u32 s35, s9, s11
	s_mov_b32 m0, s31
	s_add_i32 s42, s31, 0x2000
	v_lshl_add_u32 v150, v1, 12, v2
	global_load_lds_dwordx4 v144, s[34:35]
	s_mov_b32 m0, s42
	v_add_u32_e32 v148, 0x20000, v146
	global_load_lds_dwordx4 v150, s[34:35]
	s_add_i32 m0, s31, 0x14000
	v_add_u32_e32 v154, 0x20000, v152
	global_load_lds_dwordx4 v148, s[36:37]
	s_add_i32 m0, s31, 0x16000
	s_add_u32 s10, s34, 0x80000
	s_addc_u32 s11, s35, 0
	s_add_i32 s43, s31, 0x4000
	global_load_lds_dwordx4 v154, s[36:37]
	s_mov_b32 m0, s43
	s_add_i32 s44, s31, 0x6000
	global_load_lds_dwordx4 v144, s[10:11]
	s_mov_b32 m0, s44
	v_mov_b32_e32 v157, 0
	global_load_lds_dwordx4 v150, s[10:11]
	v_mov_b32_e32 v147, v157
	v_mov_b32_e32 v153, v157
	v_mov_b32_e32 v145, v157
	v_mov_b32_e32 v151, v157
	v_mov_b32_e32 v149, v157
	v_mov_b32_e32 v155, v157
	s_mov_b32 s46, 0
	s_mov_b32 s45, 0x10000
	v_lshl_add_u64 v[10:11], s[36:37], 0, v[146:147]
	v_lshl_add_u64 v[8:9], s[36:37], 0, v[152:153]
	v_lshl_add_u64 v[6:7], s[34:35], 0, v[144:145]
	v_lshl_add_u64 v[4:5], s[34:35], 0, v[150:151]
	v_lshl_add_u64 v[0:1], s[36:37], 0, v[148:149]
	s_cmp_lg_u32 s16, 1
	v_lshl_add_u64 v[2:3], s[36:37], 0, v[154:155]
	s_setprio 1
	s_cbranch_scc1 .LBB0_1594
	s_barrier
.LBB0_1594:
	s_add_u32 s10, s6, 0xa400000
	s_addc_u32 s11, s7, 0
	s_add_u32 s6, s6, 0x1ec40000
	s_addc_u32 s7, s7, 0
	s_add_u32 s12, s12, 0x2000
	s_mov_b64 s[14:15], 0x80
	s_addc_u32 s13, s13, 0
	s_add_i32 m0, s31, 0x18000
	v_lshl_add_u64 v[10:11], v[10:11], 0, s[14:15]
	s_waitcnt vmcnt(4)
	s_barrier
	global_load_lds_dwordx4 v[10:11], off
	v_lshl_add_u64 v[8:9], v[8:9], 0, s[14:15]
	s_add_i32 m0, s31, 0x1a000
	s_add_i32 s47, s31, 0x8000
	global_load_lds_dwordx4 v[8:9], off
	v_lshl_add_u64 v[6:7], v[6:7], 0, s[14:15]
	s_mov_b32 m0, s47
	s_add_i32 s48, s31, 0xa000
	global_load_lds_dwordx4 v[6:7], off
	v_lshl_add_u64 v[4:5], v[4:5], 0, s[14:15]
	s_mov_b32 m0, s48
	v_lshl_add_u64 v[0:1], v[0:1], 0, s[14:15]
	global_load_lds_dwordx4 v[4:5], off
	s_add_i32 m0, s31, 0x1c000
	s_and_b32 s17, s1, 3
	global_load_lds_dwordx4 v[0:1], off
	v_lshl_add_u64 v[0:1], v[2:3], 0, s[14:15]
	s_add_i32 m0, s31, 0x1e000
	v_and_b32_e32 v174, 15, v202
	global_load_lds_dwordx4 v[0:1], off
	v_lshrrev_b32_e32 v0, 1, v202
	v_and_b32_e32 v1, 24, v0
	v_lshlrev_b32_e32 v0, 1, v1
	v_lshlrev_b32_e32 v2, 2, v202
	s_sext_i32_i8 s53, s0
	v_lshl_or_b32 v0, v174, 6, v0
	s_lshl_b32 s0, s16, 13
	v_and_b32_e32 v2, 32, v2
	v_lshl_or_b32 v178, s17, 6, v1
	v_lshlrev_b32_e32 v1, 15, v12
	v_bitop3_b32 v3, v0, s0, v2 bitop3:0xde
	s_lshl_b32 s0, s17, 12
	v_and_b32_e32 v1, 0xffff0000, v1
	v_bitop3_b32 v175, v0, s0, v2 bitop3:0xde
	v_lshl_add_u32 v1, v13, 12, v1
	v_and_b32_e32 v2, 1, v12
	v_lshl_or_b32 v1, v2, 6, v1
	v_lshl_add_u32 v158, v14, 1, v1
	v_lshlrev_b32_e32 v1, 15, v15
	v_and_b32_e32 v1, 0xffff0000, v1
	s_waitcnt vmcnt(6)
	v_cmp_gt_u32_e64 s[0:1], 8, v174
	v_lshl_add_u32 v1, v16, 12, v1
	v_and_b32_e32 v2, 1, v15
	v_cndmask_b32_e64 v0, 4, 0, s[0:1]
	v_lshl_or_b32 v1, v2, 6, v1
	s_add_i32 s51, 0, 0x10000
	s_add_i32 s52, 0, 0x14000
	s_lshl_b32 s49, s16, 6
	s_ashr_i32 s50, s20, 31
	v_and_b32_e32 v176, 7, v202
	v_cndmask_b32_e64 v177, 32, 0, s[0:1]
	v_mov_b32_e32 v159, v157
	v_lshl_add_u32 v160, v17, 1, v1
	v_mov_b32_e32 v161, v157
	v_add_u32_e32 v179, s51, v175
	v_add_u32_e32 v180, 0, v3
	v_add_u32_e32 v181, s52, v175
	v_mov_b32_e32 v182, 0x358637bd
	v_lshlrev_b32_e32 v156, 2, v0
	s_mov_b64 s[16:17], 0x8000
	v_mov_b64_e32 v[162:163], 0x1ff
	s_barrier
